# v41 + retout items: the 4 gate loads per row block issued together (no wait on previous store)
# baseline (speedup 1.0000x reference)
.LBB0_944:
	s_andn2_saveexec_b64 s[2:3], s[2:3]
	s_cbranch_execz .LBB0_946
	v_add_u32_e32 v3, 0xfffff0dc, v2
	v_lshlrev_b32_e32 v0, 5, v3
	v_and_b32_e32 v0, 0x1ff80, v0
	v_mul_u32_u24_e32 v0, 0xea0, v0
	v_lshlrev_b32_e32 v0, 1, v0
	v_and_b32_e32 v2, 3, v2
	v_lshl_add_u64 v[82:83], s[14:15], 0, v[0:1]
	v_lshlrev_b32_e32 v0, 13, v3
	v_mbcnt_lo_u32_b32 v3, -1, 0
	v_mbcnt_hi_u32_b32 v3, -1, v3
	v_readlane_b32 s72, v236, 24
	v_or_b32_e32 v50, s8, v3
	v_lshlrev_b32_e32 v3, 2, v2
	v_readlane_b32 s73, v236, 25
	v_readlane_b32 s74, v236, 26
	v_readlane_b32 s75, v236, 27
	v_ashrrev_i32_e32 v21, 3, v50
	v_lshlrev_b32_e32 v84, 7, v2
	s_nop 0
	global_load_dword v4, v3, s[72:73]
	v_mov_b32_e32 v85, v1
	v_lshlrev_b32_e32 v20, 3, v50
	global_load_dword v3, v3, s[74:75]
	s_waitcnt lgkmcnt(0)
	s_barrier
	v_and_b32_e32 v93, 15, v50
	v_and_b32_e32 v51, 63, v50
	v_ashrrev_i32_e32 v48, 2, v50
	v_bfi_b32 v99, -16, v48, v50
	v_add_u32_e32 v98, 64, v99
	v_readlane_b32 s76, v236, 28
	v_readlane_b32 s77, v236, 29
	v_readlane_b32 s78, v236, 30
	v_readlane_b32 s79, v236, 31
	v_readlane_b32 s80, v236, 32
	v_readlane_b32 s81, v236, 33
	v_readlane_b32 s82, v236, 34
	v_readlane_b32 s83, v236, 35
	v_readlane_b32 s84, v236, 36
	v_readlane_b32 s85, v236, 37
	v_readlane_b32 s86, v236, 38
	v_readlane_b32 s87, v236, 39
	s_waitcnt vmcnt(0)
	v_mul_f32_e32 v5, 0xbfb8aa3b, v4
	v_fma_f32 v6, v4, s55, -v5
	v_rndne_f32_e32 v7, v5
	v_fmac_f32_e32 v6, 0xb2a5705f, v4
	v_sub_f32_e32 v5, v5, v7
	v_add_f32_e32 v5, v5, v6
	v_exp_f32_e32 v5, v5
	v_cvt_i32_f32_e32 v6, v7
	v_cmp_nlt_f32_e32 vcc, s56, v4
	v_ldexp_f32 v5, v5, v6
	s_nop 0
	v_cndmask_b32_e32 v5, 0, v5, vcc
	v_cmp_ngt_f32_e32 vcc, s57, v4
	s_nop 1
	v_cndmask_b32_e32 v18, v160, v5, vcc
	v_add_f32_e32 v6, 1.0, v18
	v_add_f32_e32 v4, -1.0, v6
	v_sub_f32_e32 v5, v4, v6
	v_add_f32_e32 v5, 1.0, v5
	v_sub_f32_e32 v4, v18, v4
	v_add_f32_e32 v7, v4, v5
	v_frexp_mant_f32_e32 v4, v6
	v_cmp_gt_f32_e32 vcc, s59, v4
	v_cvt_f64_f32_e32 v[4:5], v6
	v_frexp_exp_i32_f64_e32 v4, v[4:5]
	v_subbrev_co_u32_e32 v12, vcc, 0, v4, vcc
	v_sub_u32_e32 v4, 0, v12
	v_ldexp_f32 v5, v6, v4
	v_add_f32_e32 v6, -1.0, v5
	v_add_f32_e32 v8, 1.0, v5
	v_ldexp_f32 v4, v7, v4
	v_add_f32_e32 v7, 1.0, v6
	v_add_f32_e32 v9, -1.0, v8
	v_sub_f32_e32 v7, v5, v7
	v_sub_f32_e32 v5, v5, v9
	v_add_f32_e32 v7, v4, v7
	v_add_f32_e32 v4, v4, v5
	v_add_f32_e32 v13, v8, v4
	v_rcp_f32_e32 v15, v13
	v_sub_f32_e32 v5, v8, v13
	v_add_f32_e32 v14, v4, v5
	v_add_f32_e32 v5, v6, v7
	v_mul_f32_e32 v17, v5, v15
	v_sub_f32_e32 v4, v6, v5
	v_mul_f32_e32 v6, v13, v17
	v_fma_f32 v8, v17, v13, -v6
	v_fmac_f32_e32 v8, v17, v14
	v_add_f32_e32 v16, v7, v4
	v_add_f32_e32 v4, v6, v8
	v_sub_f32_e32 v7, v5, v4
	v_pk_add_f32 v[10:11], v[4:5], v[6:7] neg_lo:[0,1] neg_hi:[0,1]
	v_mov_b32_e32 v9, v4
	v_pk_add_f32 v[4:5], v[10:11], v[8:9] neg_lo:[0,1] neg_hi:[0,1]
	v_cmp_neq_f32_e32 vcc, s58, v18
	v_add_f32_e32 v5, v16, v5
	v_add_f32_e32 v4, v4, v5
	v_add_f32_e32 v5, v7, v4
	v_mul_f32_e32 v16, v15, v5
	v_mul_f32_e32 v6, v13, v16
	v_fma_f32 v8, v16, v13, -v6
	v_fmac_f32_e32 v8, v16, v14
	v_sub_f32_e32 v7, v7, v5
	v_add_f32_e32 v13, v4, v7
	v_add_f32_e32 v4, v6, v8
	v_sub_f32_e32 v7, v5, v4
	v_pk_add_f32 v[10:11], v[4:5], v[6:7] neg_lo:[0,1] neg_hi:[0,1]
	v_mov_b32_e32 v9, v4
	v_pk_add_f32 v[4:5], v[10:11], v[8:9] neg_lo:[0,1] neg_hi:[0,1]
	s_nop 0
	v_add_f32_e32 v5, v13, v5
	v_add_f32_e32 v4, v4, v5
	v_add_f32_e32 v5, v17, v16
	v_add_f32_e32 v4, v7, v4
	v_sub_f32_e32 v6, v5, v17
	v_mul_f32_e32 v4, v15, v4
	v_sub_f32_e32 v6, v16, v6
	v_add_f32_e32 v6, v6, v4
	v_add_f32_e32 v8, v5, v6
	v_mul_f32_e32 v9, v8, v8
	v_fmamk_f32 v4, v9, 0x3e9b6dac, v157
	v_fmaak_f32 v123, v9, v4, 0x3f2aaada
	v_cvt_f32_i32_e32 v4, v12
	v_sub_f32_e32 v5, v8, v5
	v_sub_f32_e32 v5, v6, v5
	v_ldexp_f32 v10, v5, 1
	v_mul_f32_e32 v5, v8, v9
	v_ldexp_f32 v7, v8, 1
	v_pk_mul_f32 v[8:9], v[4:5], v[122:123]
	s_nop 0
	v_fma_f32 v6, v4, s60, -v8
	v_fmac_f32_e32 v6, 0xb102e308, v4
	v_pk_add_f32 v[4:5], v[8:9], v[6:7]
	s_nop 0
	v_sub_f32_e32 v7, v5, v7
	v_sub_f32_e32 v7, v9, v7
	v_add_f32_e32 v11, v10, v7
	v_mov_b32_e32 v10, v8
	v_pk_add_f32 v[8:9], v[4:5], v[8:9] neg_lo:[0,1] neg_hi:[0,1]
	v_pk_add_f32 v[12:13], v[4:5], v[10:11]
	v_mov_b32_e32 v7, v4
	v_mov_b32_e32 v9, v13
	v_pk_add_f32 v[14:15], v[6:7], v[8:9] neg_lo:[0,1] neg_hi:[0,1]
	v_pk_add_f32 v[6:7], v[6:7], v[8:9]
	v_mov_b32_e32 v10, v11
	v_pk_add_f32 v[8:9], v[6:7], v[4:5] op_sel:[1,0] op_sel_hi:[0,1] neg_lo:[0,1] neg_hi:[0,1]
	v_pk_add_f32 v[16:17], v[12:13], v[8:9] op_sel_hi:[1,0] neg_lo:[0,1] neg_hi:[0,1]
	v_mov_b32_e32 v12, v13
	v_mov_b32_e32 v13, v7
	v_pk_mov_b32 v[8:9], v[4:5], v[8:9] op_sel:[1,0]
	v_mov_b32_e32 v11, v4
	v_pk_add_f32 v[8:9], v[12:13], v[8:9] neg_lo:[0,1] neg_hi:[0,1]
	v_mov_b32_e32 v16, v14
	v_pk_add_f32 v[4:5], v[10:11], v[8:9] neg_lo:[0,1] neg_hi:[0,1]
	v_mov_b32_e32 v15, v7
	v_pk_add_f32 v[8:9], v[16:17], v[4:5]
	s_nop 0
	v_pk_add_f32 v[10:11], v[8:9], v[8:9] op_sel:[0,1] op_sel_hi:[1,0]
	s_nop 0
	v_pk_add_f32 v[6:7], v[6:7], v[10:11] op_sel:[1,0] op_sel_hi:[0,1]
	v_mov_b32_e32 v9, v6
	v_pk_add_f32 v[12:13], v[8:9], v[14:15] neg_lo:[0,1] neg_hi:[0,1]
	v_mov_b32_e32 v5, v10
	v_sub_f32_e32 v7, v8, v12
	v_pk_add_f32 v[4:5], v[4:5], v[12:13] neg_lo:[0,1] neg_hi:[0,1]
	v_sub_f32_e32 v7, v14, v7
	v_add_f32_e32 v4, v4, v7
	v_add_f32_e32 v4, v4, v5
	v_add_f32_e32 v4, v6, v4
	v_cndmask_b32_e32 v4, v160, v4, vcc
	v_cmp_lt_f32_e64 vcc, |v18|, s61
	s_nop 1
	v_cndmask_b32_e32 v96, v4, v18, vcc
	v_mul_f32_e32 v4, 0xbfb8aa3b, v3
	v_fma_f32 v5, v3, s55, -v4
	v_rndne_f32_e32 v6, v4
	v_fmac_f32_e32 v5, 0xb2a5705f, v3
	v_sub_f32_e32 v4, v4, v6
	v_add_f32_e32 v4, v4, v5
	v_exp_f32_e32 v4, v4
	v_cvt_i32_f32_e32 v5, v6
	v_cmp_nlt_f32_e32 vcc, s56, v3
	v_ldexp_f32 v4, v4, v5
	s_nop 0
	v_cndmask_b32_e32 v4, 0, v4, vcc
	v_cmp_ngt_f32_e32 vcc, s57, v3
	s_nop 1
	v_cndmask_b32_e32 v3, v160, v4, vcc
	v_add_f32_e32 v6, 1.0, v3
	v_add_f32_e32 v4, -1.0, v6
	v_sub_f32_e32 v5, v4, v6
	v_add_f32_e32 v5, 1.0, v5
	v_sub_f32_e32 v4, v3, v4
	v_add_f32_e32 v7, v4, v5
	v_frexp_mant_f32_e32 v4, v6
	v_cmp_gt_f32_e32 vcc, s59, v4
	v_cvt_f64_f32_e32 v[4:5], v6
	v_frexp_exp_i32_f64_e32 v4, v[4:5]
	v_subbrev_co_u32_e32 v12, vcc, 0, v4, vcc
	v_sub_u32_e32 v4, 0, v12
	v_ldexp_f32 v5, v6, v4
	v_add_f32_e32 v6, -1.0, v5
	v_add_f32_e32 v8, 1.0, v5
	v_ldexp_f32 v4, v7, v4
	v_add_f32_e32 v7, 1.0, v6
	v_add_f32_e32 v9, -1.0, v8
	v_sub_f32_e32 v7, v5, v7
	v_sub_f32_e32 v5, v5, v9
	v_add_f32_e32 v7, v4, v7
	v_add_f32_e32 v4, v4, v5
	v_add_f32_e32 v13, v8, v4
	v_rcp_f32_e32 v15, v13
	v_sub_f32_e32 v5, v8, v13
	v_add_f32_e32 v14, v4, v5
	v_add_f32_e32 v5, v6, v7
	v_mul_f32_e32 v17, v5, v15
	v_sub_f32_e32 v4, v6, v5
	v_mul_f32_e32 v6, v13, v17
	v_fma_f32 v8, v17, v13, -v6
	v_fmac_f32_e32 v8, v17, v14
	v_add_f32_e32 v16, v7, v4
	v_add_f32_e32 v4, v6, v8
	v_sub_f32_e32 v7, v5, v4
	v_pk_add_f32 v[10:11], v[4:5], v[6:7] neg_lo:[0,1] neg_hi:[0,1]
	v_mov_b32_e32 v9, v4
	v_pk_add_f32 v[4:5], v[10:11], v[8:9] neg_lo:[0,1] neg_hi:[0,1]
	v_cmp_neq_f32_e32 vcc, s58, v3
	v_add_f32_e32 v5, v16, v5
	v_add_f32_e32 v4, v4, v5
	v_add_f32_e32 v5, v7, v4
	v_mul_f32_e32 v16, v15, v5
	v_mul_f32_e32 v6, v13, v16
	v_fma_f32 v8, v16, v13, -v6
	v_fmac_f32_e32 v8, v16, v14
	v_sub_f32_e32 v7, v7, v5
	v_add_f32_e32 v13, v4, v7
	v_add_f32_e32 v4, v6, v8
	v_sub_f32_e32 v7, v5, v4
	v_pk_add_f32 v[10:11], v[4:5], v[6:7] neg_lo:[0,1] neg_hi:[0,1]
	v_mov_b32_e32 v9, v4
	v_pk_add_f32 v[4:5], v[10:11], v[8:9] neg_lo:[0,1] neg_hi:[0,1]
	s_nop 0
	v_add_f32_e32 v5, v13, v5
	v_add_f32_e32 v4, v4, v5
	v_add_f32_e32 v5, v17, v16
	v_add_f32_e32 v4, v7, v4
	v_sub_f32_e32 v6, v5, v17
	v_mul_f32_e32 v4, v15, v4
	v_sub_f32_e32 v6, v16, v6
	v_add_f32_e32 v6, v6, v4
	v_add_f32_e32 v8, v5, v6
	v_mul_f32_e32 v9, v8, v8
	v_fmamk_f32 v4, v9, 0x3e9b6dac, v157
	v_fmaak_f32 v123, v9, v4, 0x3f2aaada
	v_cvt_f32_i32_e32 v4, v12
	v_sub_f32_e32 v5, v8, v5
	v_sub_f32_e32 v5, v6, v5
	v_ldexp_f32 v10, v5, 1
	v_mul_f32_e32 v5, v8, v9
	v_ldexp_f32 v7, v8, 1
	v_pk_mul_f32 v[8:9], v[4:5], v[122:123]
	s_nop 0
	v_fma_f32 v6, v4, s60, -v8
	v_fmac_f32_e32 v6, 0xb102e308, v4
	v_pk_add_f32 v[4:5], v[8:9], v[6:7]
	s_nop 0
	v_sub_f32_e32 v7, v5, v7
	v_sub_f32_e32 v7, v9, v7
	v_add_f32_e32 v11, v10, v7
	v_mov_b32_e32 v10, v8
	v_pk_add_f32 v[8:9], v[4:5], v[8:9] neg_lo:[0,1] neg_hi:[0,1]
	v_pk_add_f32 v[12:13], v[4:5], v[10:11]
	v_mov_b32_e32 v7, v4
	v_mov_b32_e32 v9, v13
	v_pk_add_f32 v[14:15], v[6:7], v[8:9] neg_lo:[0,1] neg_hi:[0,1]
	v_pk_add_f32 v[6:7], v[6:7], v[8:9]
	v_mov_b32_e32 v10, v11
	v_pk_add_f32 v[8:9], v[6:7], v[4:5] op_sel:[1,0] op_sel_hi:[0,1] neg_lo:[0,1] neg_hi:[0,1]
	v_pk_add_f32 v[16:17], v[12:13], v[8:9] op_sel_hi:[1,0] neg_lo:[0,1] neg_hi:[0,1]
	v_mov_b32_e32 v12, v13
	v_mov_b32_e32 v13, v7
	v_pk_mov_b32 v[8:9], v[4:5], v[8:9] op_sel:[1,0]
	v_mov_b32_e32 v11, v4
	v_pk_add_f32 v[8:9], v[12:13], v[8:9] neg_lo:[0,1] neg_hi:[0,1]
	v_mov_b32_e32 v16, v14
	v_pk_add_f32 v[4:5], v[10:11], v[8:9] neg_lo:[0,1] neg_hi:[0,1]
	v_mov_b32_e32 v15, v7
	v_pk_add_f32 v[8:9], v[16:17], v[4:5]
	s_nop 0
	v_pk_add_f32 v[10:11], v[8:9], v[8:9] op_sel:[0,1] op_sel_hi:[1,0]
	s_nop 0
	v_pk_add_f32 v[6:7], v[6:7], v[10:11] op_sel:[1,0] op_sel_hi:[0,1]
	v_mov_b32_e32 v9, v6
	v_pk_add_f32 v[12:13], v[8:9], v[14:15] neg_lo:[0,1] neg_hi:[0,1]
	v_mov_b32_e32 v5, v10
	v_sub_f32_e32 v7, v8, v12
	v_pk_add_f32 v[4:5], v[4:5], v[12:13] neg_lo:[0,1] neg_hi:[0,1]
	v_sub_f32_e32 v7, v14, v7
	v_add_f32_e32 v4, v4, v7
	v_add_f32_e32 v4, v4, v5
	v_add_f32_e32 v4, v6, v4
	v_cndmask_b32_e32 v4, v160, v4, vcc
	v_cmp_lt_f32_e64 vcc, |v3|, s61
	v_mov_b32_e32 v11, v1
	s_nop 0
	v_cndmask_b32_e32 v97, v4, v3, vcc
	v_lshlrev_b32_e32 v3, 4, v50
	v_mad_i64_i32 v[4:5], s[6:7], v21, s52, v[82:83]
	v_and_b32_e32 v10, 0x70, v3
	v_lshl_add_u64 v[2:3], v[4:5], 0, v[84:85]
	v_lshl_add_u64 v[6:7], v[2:3], 0, v[10:11]
	global_load_dwordx4 v[172:175], v[6:7], off
	v_add_u32_e32 v12, s92, v10
	v_mad_u64_u32 v[8:9], s[6:7], v21, s62, v[12:13]
	s_nop 0
	v_mov_b32_e32 v206, v8
	global_load_dwordx4 v[176:179], v[6:7], off offset:512
	s_nop 0
	v_mov_b32_e32 v207, v8
	v_add_u32_e32 v8, 0x100, v50
	v_ashrrev_i32_e32 v9, 3, v8
	v_mad_i64_i32 v[2:3], s[6:7], v9, s52, v[82:83]
	v_lshl_add_u64 v[2:3], v[2:3], 0, v[84:85]
	v_lshl_add_u64 v[6:7], v[2:3], 0, v[10:11]
	global_load_dwordx4 v[180:183], v[6:7], off
	v_mad_u64_u32 v[14:15], s[6:7], v9, s62, v[12:13]
	s_nop 0
	v_mov_b32_e32 v208, v14
	global_load_dwordx4 v[184:187], v[6:7], off offset:512
	v_add_u32_e32 v7, 0x200, v50
	v_add_u32_e32 v6, 0x300, v50
	s_nop 0
	v_mov_b32_e32 v209, v14
	v_ashrrev_i32_e32 v4, 3, v7
	v_mad_i64_i32 v[2:3], s[6:7], v4, s52, v[82:83]
	v_lshl_add_u64 v[2:3], v[2:3], 0, v[84:85]
	v_lshl_add_u64 v[14:15], v[2:3], 0, v[10:11]
	v_mad_u64_u32 v[16:17], s[6:7], v4, s62, v[12:13]
	global_load_dwordx4 v[188:191], v[14:15], off
	v_ashrrev_i32_e32 v7, 4, v7
	s_nop 0
	v_mov_b32_e32 v210, v16
	global_load_dwordx4 v[192:195], v[14:15], off offset:512
	s_nop 0
	v_mov_b32_e32 v211, v16
	v_ashrrev_i32_e32 v4, 3, v6
	v_mad_i64_i32 v[2:3], s[6:7], v4, s52, v[82:83]
	v_lshl_add_u64 v[2:3], v[2:3], 0, v[84:85]
	v_lshl_add_u64 v[10:11], v[2:3], 0, v[10:11]
	v_mad_u64_u32 v[12:13], s[6:7], v4, s62, v[12:13]
	global_load_dwordx4 v[196:199], v[10:11], off
	s_mov_b64 s[6:7], 0x2140
	s_nop 0
	v_mov_b32_e32 v212, v12
	global_load_dwordx4 v[200:203], v[10:11], off offset:512
	v_and_b32_e32 v10, 48, v20
	v_and_b32_e32 v20, -8, v21
	v_ashrrev_i32_e32 v21, 31, v20
	v_and_b32_e32 v11, 8, v50
	v_lshlrev_b64 v[14:15], 1, v[20:21]
	s_waitcnt vmcnt(0) lgkmcnt(0)
	ds_write_b128 v206, v[172:175]
	ds_write_b128 v207, v[176:179] offset:18432
	ds_write_b128 v208, v[180:183]
	ds_write_b128 v209, v[184:187] offset:18432
	ds_write_b128 v210, v[188:191]
	ds_write_b128 v211, v[192:195] offset:18432
	ds_write_b128 v212, v[196:199]
	ds_write_b128 v12, v[200:203] offset:18432
	v_lshlrev_b32_e32 v2, 1, v50
	v_and_b32_e32 v2, 0x7e, v2
	v_mul_u32_u24_e32 v2, 0xea0, v2
	v_lshlrev_b32_e32 v2, 1, v2
	v_mov_b32_e32 v3, v1
	v_lshlrev_b32_e32 v5, 2, v50
	v_lshl_add_u64 v[2:3], v[82:83], 0, v[2:3]
	v_and_b32_e32 v4, 0xc4, v5
	v_lshl_add_u64 v[18:19], v[2:3], 0, v[84:85]
	v_add_u32_e32 v4, s92, v4
	v_lshl_add_u64 v[2:3], v[18:19], 0, s[6:7]
	v_add3_u32 v4, v4, v10, v11
	v_lshl_add_u64 v[10:11], v[18:19], 0, v[14:15]
	global_load_dwordx4 v[10:13], v[10:11], off offset:1024
	v_lshl_add_u64 v[14:15], v[2:3], 0, v[14:15]
	global_load_dwordx4 v[14:17], v[14:15], off
	s_waitcnt vmcnt(0) lgkmcnt(0)
	v_and_b32_e32 v21, 0xffff, v10
	v_lshrrev_b32_e32 v10, 16, v10
	v_lshl_or_b32 v22, v14, 16, v21
	v_mad_u64_u32 v[20:21], s[6:7], v20, s64, v[4:5]
	v_and_or_b32 v10, v14, s54, v10
	v_add_u32_e32 v14, 0x9000, v20
	ds_write2_b32 v14, v22, v10 offset1:68
	v_and_b32_e32 v10, 0xffff, v11
	v_lshrrev_b32_e32 v11, 16, v11
	v_lshl_or_b32 v10, v15, 16, v10
	v_and_or_b32 v11, v15, s54, v11
	ds_write2_b32 v14, v10, v11 offset0:136 offset1:204
	v_and_b32_e32 v10, 0xffff, v12
	v_lshrrev_b32_e32 v11, 16, v12
	v_lshl_or_b32 v10, v16, 16, v10
	v_and_or_b32 v11, v16, s54, v11
	v_add_u32_e32 v12, 0x9400, v20
	v_and_b32_e32 v20, -8, v9
	ds_write2_b32 v12, v10, v11 offset0:16 offset1:84
	v_and_b32_e32 v10, 0xffff, v13
	v_lshrrev_b32_e32 v11, 16, v13
	v_ashrrev_i32_e32 v21, 31, v20
	v_lshl_or_b32 v10, v17, 16, v10
	v_and_or_b32 v11, v17, s54, v11
	v_lshlrev_b64 v[14:15], 1, v[20:21]
	ds_write2_b32 v12, v10, v11 offset0:152 offset1:220
	v_lshl_add_u64 v[10:11], v[18:19], 0, v[14:15]
	global_load_dwordx4 v[10:13], v[10:11], off offset:1024
	v_lshl_add_u64 v[2:3], v[2:3], 0, v[14:15]
	global_load_dwordx4 v[14:17], v[2:3], off
	s_waitcnt vmcnt(0) lgkmcnt(0)
	v_and_b32_e32 v2, 0xffff, v10
	v_lshl_or_b32 v9, v14, 16, v2
	v_mad_u64_u32 v[2:3], s[6:7], v20, s64, v[4:5]
	v_lshrrev_b32_e32 v3, 16, v10
	v_and_or_b32 v3, v14, s54, v3
	v_add_u32_e32 v4, 0x9000, v2
	ds_write2_b32 v4, v9, v3 offset1:68
	v_and_b32_e32 v3, 0xffff, v11
	v_lshrrev_b32_e32 v9, 16, v11
	v_lshl_or_b32 v3, v15, 16, v3
	v_and_or_b32 v9, v15, s54, v9
	ds_write2_b32 v4, v3, v9 offset0:136 offset1:204
	v_and_b32_e32 v3, 0xffff, v12
	v_lshrrev_b32_e32 v4, 16, v12
	v_lshl_or_b32 v3, v16, 16, v3
	v_and_or_b32 v4, v16, s54, v4
	v_add_u32_e32 v2, 0x9400, v2
	ds_write2_b32 v2, v3, v4 offset0:16 offset1:84
	v_and_b32_e32 v3, 0xffff, v13
	v_lshrrev_b32_e32 v4, 16, v13
	v_lshl_or_b32 v3, v17, 16, v3
	v_and_or_b32 v4, v17, s54, v4
	v_and_b32_e32 v9, 60, v5
	ds_write2_b32 v2, v3, v4 offset0:152 offset1:220
	v_lshl_add_u64 v[2:3], v[0:1], 2, s[18:19]
	v_lshlrev_b32_e32 v0, 2, v9
	v_lshl_add_u64 v[2:3], v[2:3], 0, v[0:1]
	v_lshl_add_u32 v0, v9, 1, s92
	v_ashrrev_i32_e32 v9, 4, v50
	v_lshlrev_b32_e32 v10, 6, v9
	s_mov_b64 s[6:7], 0x4000
	v_ashrrev_i32_e32 v11, 31, v10
	v_lshl_add_u64 v[4:5], v[2:3], 0, s[6:7]
	v_lshlrev_b64 v[14:15], 2, v[10:11]
	v_lshl_add_u64 v[10:11], v[2:3], 0, v[14:15]
	v_lshl_add_u64 v[14:15], v[4:5], 0, v[14:15]
	global_load_dwordx4 v[10:13], v[10:11], off
	s_nop 0
	global_load_dwordx4 v[14:17], v[14:15], off
	s_waitcnt vmcnt(0) lgkmcnt(0)
	v_cvt_pk_bf16_f32 v10, v10, v11
	v_cvt_pk_bf16_f32 v11, v12, v13
	v_cvt_pk_bf16_f32 v14, v14, v15
	v_cvt_pk_bf16_f32 v15, v16, v17
	v_ashrrev_i32_e32 v16, 4, v8
	v_lshlrev_b32_e32 v8, 6, v16
	v_mad_u64_u32 v[12:13], s[6:7], v9, s62, v[0:1]
	v_ashrrev_i32_e32 v9, 31, v8
	ds_write2st64_b64 v12, v[10:11], v[14:15] offset0:106 offset1:124
	v_lshlrev_b64 v[12:13], 2, v[8:9]
	v_lshl_add_u64 v[8:9], v[2:3], 0, v[12:13]
	v_lshl_add_u64 v[12:13], v[4:5], 0, v[12:13]
	global_load_dwordx4 v[8:11], v[8:9], off
	s_nop 0
	global_load_dwordx4 v[12:15], v[12:13], off
	s_waitcnt vmcnt(0) lgkmcnt(0)
	v_cvt_pk_bf16_f32 v8, v8, v9
	v_cvt_pk_bf16_f32 v9, v10, v11
	v_mad_u64_u32 v[10:11], s[6:7], v16, s62, v[0:1]
	v_cvt_pk_bf16_f32 v12, v12, v13
	v_cvt_pk_bf16_f32 v13, v14, v15
	ds_write2st64_b64 v10, v[8:9], v[12:13] offset0:106 offset1:124
	v_lshlrev_b32_e32 v8, 6, v7
	v_ashrrev_i32_e32 v9, 31, v8
	v_lshlrev_b64 v[12:13], 2, v[8:9]
	v_lshl_add_u64 v[8:9], v[2:3], 0, v[12:13]
	v_lshl_add_u64 v[12:13], v[4:5], 0, v[12:13]
	global_load_dwordx4 v[8:11], v[8:9], off
	s_nop 0
	global_load_dwordx4 v[12:15], v[12:13], off
	s_waitcnt vmcnt(0) lgkmcnt(0)
	v_cvt_pk_bf16_f32 v8, v8, v9
	v_cvt_pk_bf16_f32 v9, v10, v11
	v_mad_u64_u32 v[10:11], s[6:7], v7, s62, v[0:1]
	v_cvt_pk_bf16_f32 v12, v12, v13
	v_cvt_pk_bf16_f32 v13, v14, v15
	ds_write2st64_b64 v10, v[8:9], v[12:13] offset0:106 offset1:124
	v_ashrrev_i32_e32 v12, 4, v6
	v_lshlrev_b32_e32 v6, 6, v12
	v_ashrrev_i32_e32 v7, 31, v6
	v_lshlrev_b64 v[10:11], 2, v[6:7]
	v_lshl_add_u64 v[2:3], v[2:3], 0, v[10:11]
	global_load_dwordx4 v[6:9], v[2:3], off
	v_lshl_add_u64 v[2:3], v[4:5], 0, v[10:11]
	global_load_dwordx4 v[2:5], v[2:3], off
	v_and_b32_e32 v14, 48, v50
	s_waitcnt vmcnt(0) lgkmcnt(0)
	v_cvt_pk_bf16_f32 v6, v6, v7
	v_cvt_pk_bf16_f32 v7, v8, v9
	v_mad_u64_u32 v[8:9], s[6:7], v12, s62, v[0:1]
	v_cvt_pk_bf16_f32 v2, v2, v3
	v_cvt_pk_bf16_f32 v3, v4, v5
	v_mul_u32_u24_e32 v0, 0x48, v93
	ds_write2st64_b64 v8, v[6:7], v[2:3] offset0:106 offset1:124
	v_lshlrev_b32_e32 v2, 1, v0
	v_add_u32_e32 v0, s92, v14
	v_and_b32_e32 v12, -16, v48
	v_add_u32_e32 v13, s92, v2
	v_add_u32_e32 v88, v0, v2
	v_or_b32_e32 v2, 48, v51
	v_mul_u32_u24_e32 v2, 0x48, v2
	v_mul_lo_u32 v12, v12, s62
	v_lshl_add_u32 v89, v2, 1, v0
	v_mov_b32_e32 v2, v1
	v_mov_b32_e32 v6, v1
	v_add3_u32 v90, v13, v14, v12
	s_waitcnt lgkmcnt(0)
	s_barrier
	ds_read_b128 v[12:15], v90
	ds_read_b128 v[16:19], v88 offset:54272
	ds_read_b128 v[20:23], v88 offset:56576
	ds_read_b128 v[24:27], v88 offset:58880
	ds_read_b128 v[28:31], v89 offset:54272
	v_mov_b32_e32 v3, v2
	v_mov_b32_e32 v4, v2
	v_mov_b32_e32 v5, v2
	v_add_u32_e32 v11, 0xf800, v88
	v_mov_b32_e32 v7, v6
	s_waitcnt lgkmcnt(3)
	v_mfma_f32_16x16x32_bf16 v[16:19], v[16:19], v[12:15], v[2:5]
	v_mov_b32_e32 v8, v6
	v_mov_b32_e32 v9, v6
	v_add_u32_e32 v10, 0xf840, v88
	s_waitcnt lgkmcnt(2)
	v_mfma_f32_16x16x32_bf16 v[20:23], v[20:23], v[12:15], v[2:5]
	v_or_b32_e32 v51, 0x70, v51
	v_mul_u32_u24_e32 v51, 0x48, v51
	v_lshl_add_u32 v92, v51, 1, v0
	s_waitcnt lgkmcnt(1)
	v_mfma_f32_16x16x32_bf16 v[24:27], v[24:27], v[12:15], v[2:5]
	v_lshrrev_b32_e32 v0, 2, v50
	v_mov_b32_e32 v50, v1
	v_and_b32_e32 v91, 12, v0
	s_waitcnt lgkmcnt(0)
	v_mfma_f32_16x16x32_bf16 v[2:5], v[28:31], v[12:15], v[2:5]
	ds_read_b128 v[28:31], v90 offset:64
	ds_read_b128 v[32:35], v88 offset:54336
	ds_read_b128 v[36:39], v88 offset:56640
	ds_read_b128 v[40:43], v88 offset:58944
	ds_read_b128 v[44:47], v89 offset:54336
	v_sub_u32_e32 v0, v99, v91
	v_sub_u32_e32 v86, 0, v0
	s_waitcnt lgkmcnt(3)
	v_mfma_f32_16x16x32_bf16 v[16:19], v[32:35], v[28:31], v[16:19]
	v_max_i32_e32 v0, v0, v86
	v_cvt_f32_u32_e32 v0, v0
	v_cmp_lt_i32_e32 vcc, v99, v91
	s_waitcnt lgkmcnt(2)
	v_mfma_f32_16x16x32_bf16 v[20:23], v[36:39], v[28:31], v[20:23]
	v_or_b32_e32 v94, 16, v91
	v_cndmask_b32_e32 v86, v96, v97, vcc
	v_mul_f32_e32 v0, v86, v0
	s_waitcnt lgkmcnt(1)
	v_mfma_f32_16x16x32_bf16 v[24:27], v[40:43], v[28:31], v[24:27]
	v_mul_f32_e32 v0, 0xbfb8aa3b, v0
	v_exp_f32_e32 v86, v0
	v_cmp_gt_i32_e32 vcc, v99, v91
	s_waitcnt lgkmcnt(0)
	v_mfma_f32_16x16x32_bf16 v[2:5], v[44:47], v[28:31], v[2:5]
	ds_read_b128 v[32:35], v88 offset:63488
	ds_read_b128 v[36:39], v11 offset:2304
	ds_read_b128 v[40:43], v11 offset:4608
	ds_read_b128 v[44:47], v89 offset:63488
	v_or_b32_e32 v95, 17, v91
	v_or_b32_e32 v120, 0x53, v91
	s_waitcnt lgkmcnt(3)
	v_mfma_f32_16x16x32_bf16 v[32:35], v[32:35], v[12:15], v[6:9]
	v_or_b32_e32 v121, 0x60, v91
	v_or_b32_e32 v123, 0x61, v91
	s_waitcnt lgkmcnt(2)
	v_mfma_f32_16x16x32_bf16 v[36:39], v[36:39], v[12:15], v[6:9]
	s_waitcnt lgkmcnt(1)
	v_mfma_f32_16x16x32_bf16 v[40:43], v[40:43], v[12:15], v[6:9]
	s_waitcnt lgkmcnt(0)
	v_mfma_f32_16x16x32_bf16 v[6:9], v[44:47], v[12:15], v[6:9]
	ds_read_b128 v[12:15], v88 offset:63552
	ds_read_b128 v[44:47], v10 offset:2304
	ds_read_b128 v[52:55], v10 offset:4608
	ds_read_b128 v[56:59], v89 offset:63552
	s_waitcnt lgkmcnt(3)
	v_mfma_f32_16x16x32_bf16 v[12:15], v[12:15], v[28:31], v[32:35]
	s_waitcnt lgkmcnt(2)
	v_mfma_f32_16x16x32_bf16 v[44:47], v[44:47], v[28:31], v[36:39]
	s_waitcnt lgkmcnt(1)
	v_mfma_f32_16x16x32_bf16 v[52:55], v[52:55], v[28:31], v[40:43]
	s_waitcnt lgkmcnt(0)
	v_mfma_f32_16x16x32_bf16 v[6:9], v[56:59], v[28:31], v[6:9]
	v_sub_u32_e32 v29, 0x80, v99
	v_add_u32_e32 v28, 1, v99
	v_cvt_f32_i32_e32 v29, v29
	v_cvt_f32_i32_e32 v28, v28
	v_mul_f32_e32 v29, v29, v97
	v_mul_f32_e32 v28, v28, v96
	v_mul_f32_e32 v29, 0xbfb8aa3b, v29
	v_mul_f32_e32 v28, 0xbfb8aa3b, v28
	v_exp_f32_e32 v30, v29
	v_exp_f32_e32 v28, v28
	v_pk_mul_f32 v[12:13], v[30:31], v[12:13] op_sel_hi:[0,1]
	v_pk_mul_f32 v[14:15], v[30:31], v[14:15] op_sel_hi:[0,1]
	v_pk_fma_f32 v[34:35], v[28:29], v[16:17], v[12:13] op_sel_hi:[0,1,1]
	v_pk_mul_f32 v[12:13], v[30:31], v[44:45] op_sel_hi:[0,1]
	v_pk_fma_f32 v[36:37], v[28:29], v[18:19], v[14:15] op_sel_hi:[0,1,1]
	v_pk_mul_f32 v[14:15], v[30:31], v[46:47] op_sel_hi:[0,1]
	v_pk_fma_f32 v[38:39], v[28:29], v[20:21], v[12:13] op_sel_hi:[0,1,1]
	v_pk_mul_f32 v[12:13], v[30:31], v[52:53] op_sel_hi:[0,1]
	v_pk_mul_f32 v[6:7], v[30:31], v[6:7] op_sel_hi:[0,1]
	v_pk_fma_f32 v[40:41], v[28:29], v[22:23], v[14:15] op_sel_hi:[0,1,1]
	v_pk_mul_f32 v[14:15], v[30:31], v[54:55] op_sel_hi:[0,1]
	v_pk_fma_f32 v[42:43], v[28:29], v[24:25], v[12:13] op_sel_hi:[0,1,1]
	v_pk_mul_f32 v[8:9], v[30:31], v[8:9] op_sel_hi:[0,1]
	v_pk_fma_f32 v[46:47], v[28:29], v[2:3], v[6:7] op_sel_hi:[0,1,1]
	v_mov_b32_e32 v2, v1
	v_mov_b32_e32 v12, v1
	v_pk_fma_f32 v[44:45], v[28:29], v[26:27], v[14:15] op_sel_hi:[0,1,1]
	v_pk_fma_f32 v[48:49], v[28:29], v[4:5], v[8:9] op_sel_hi:[0,1,1]
	ds_read_b128 v[22:25], v90 offset:9216
	ds_read_b128 v[6:9], v88 offset:54272
	ds_read_b128 v[16:19], v88 offset:56576
	ds_read_b128 v[26:29], v88 offset:58880
	ds_read_b128 v[30:33], v89 offset:54272
	v_mov_b32_e32 v3, v2
	v_mov_b32_e32 v4, v2
	v_mov_b32_e32 v5, v2
	v_mov_b32_e32 v13, v12
	v_mov_b32_e32 v14, v12
	s_waitcnt lgkmcnt(3)
	v_mfma_f32_16x16x32_bf16 v[6:9], v[6:9], v[22:25], v[2:5]
	v_mov_b32_e32 v15, v12
	s_waitcnt lgkmcnt(2)
	v_mfma_f32_16x16x32_bf16 v[16:19], v[16:19], v[22:25], v[2:5]
	s_waitcnt lgkmcnt(1)
	v_mfma_f32_16x16x32_bf16 v[26:29], v[26:29], v[22:25], v[2:5]
	s_waitcnt lgkmcnt(0)
	v_mfma_f32_16x16x32_bf16 v[30:33], v[30:33], v[22:25], v[2:5]
	ds_read_b128 v[52:55], v90 offset:9280
	s_nop 1
	ds_read_b128 v[2:5], v88 offset:54336
	ds_read_b128 v[56:59], v88 offset:56640
	ds_read_b128 v[60:63], v88 offset:58944
	ds_read_b128 v[64:67], v89 offset:54336
	s_waitcnt lgkmcnt(3)
	v_mfma_f32_16x16x32_bf16 v[2:5], v[2:5], v[52:55], v[6:9]
	s_waitcnt lgkmcnt(2)
	v_mfma_f32_16x16x32_bf16 v[6:9], v[56:59], v[52:55], v[16:19]
	s_waitcnt lgkmcnt(1)
	v_mfma_f32_16x16x32_bf16 v[18:21], v[60:63], v[52:55], v[26:29]
	s_waitcnt lgkmcnt(0)
	v_mfma_f32_16x16x32_bf16 v[26:29], v[64:67], v[52:55], v[30:33]
	s_nop 2
	ds_read_b128 v[30:33], v88 offset:63488
	ds_read_b128 v[56:59], v11 offset:2304
	ds_read_b128 v[60:63], v11 offset:4608
	ds_read_b128 v[64:67], v89 offset:63488
	s_waitcnt lgkmcnt(3)
	v_mfma_f32_16x16x32_bf16 v[30:33], v[30:33], v[22:25], v[12:15]
	s_waitcnt lgkmcnt(2)
	v_mfma_f32_16x16x32_bf16 v[56:59], v[56:59], v[22:25], v[12:15]
	s_waitcnt lgkmcnt(1)
	v_mfma_f32_16x16x32_bf16 v[60:63], v[60:63], v[22:25], v[12:15]
	s_waitcnt lgkmcnt(0)
	v_mfma_f32_16x16x32_bf16 v[64:67], v[64:67], v[22:25], v[12:15]
	s_nop 2
	ds_read_b128 v[12:15], v88 offset:63552
	ds_read_b128 v[22:25], v10 offset:2304
	ds_read_b128 v[68:71], v10 offset:4608
	ds_read_b128 v[72:75], v89 offset:63552
	s_waitcnt lgkmcnt(3)
	v_mfma_f32_16x16x32_bf16 v[10:13], v[12:15], v[52:55], v[30:33]
	v_mov_b32_e32 v51, v50
	s_waitcnt lgkmcnt(2)
	v_mfma_f32_16x16x32_bf16 v[14:17], v[22:25], v[52:55], v[56:59]
	s_waitcnt lgkmcnt(1)
	v_mfma_f32_16x16x32_bf16 v[22:25], v[68:71], v[52:55], v[60:63]
	s_waitcnt lgkmcnt(0)
	v_mfma_f32_16x16x32_bf16 v[30:33], v[72:75], v[52:55], v[64:67]
	ds_read_b128 v[54:57], v90
	ds_read_b128 v[58:61], v88 offset:18432
	s_nop 0
	ds_read_b128 v[62:65], v88 offset:20736
	ds_read_b128 v[66:69], v88 offset:23040
	ds_read_b128 v[70:73], v89 offset:18432
	ds_read_b128 v[74:77], v88 offset:27648
	ds_read_b128 v[78:81], v88 offset:29952
	ds_read_b128 v[100:103], v88 offset:32256
	ds_read_b128 v[104:107], v92 offset:18432
	v_mov_b32_e32 v52, v50
	v_mov_b32_e32 v53, v50
	s_waitcnt lgkmcnt(7)
	s_nop 0
	v_mfma_f32_16x16x32_bf16 v[58:61], v[58:61], v[54:57], v[50:53]
	s_waitcnt lgkmcnt(6)
	v_mfma_f32_16x16x32_bf16 v[62:65], v[62:65], v[54:57], v[50:53]
	s_waitcnt lgkmcnt(5)
	v_mfma_f32_16x16x32_bf16 v[66:69], v[66:69], v[54:57], v[50:53]
	s_waitcnt lgkmcnt(4)
	v_mfma_f32_16x16x32_bf16 v[108:111], v[70:73], v[54:57], v[50:53]
	s_waitcnt lgkmcnt(3)
	v_mfma_f32_16x16x32_bf16 v[112:115], v[74:77], v[54:57], v[50:53]
	s_waitcnt lgkmcnt(2)
	v_mfma_f32_16x16x32_bf16 v[116:119], v[78:81], v[54:57], v[50:53]
	s_waitcnt lgkmcnt(1)
	v_mfma_f32_16x16x32_bf16 v[100:103], v[100:103], v[54:57], v[50:53]
	s_waitcnt lgkmcnt(0)
	v_mfma_f32_16x16x32_bf16 v[50:53], v[104:107], v[54:57], v[50:53]
	ds_read_b128 v[104:107], v90 offset:64
	ds_read_b128 v[54:57], v88 offset:18496
	ds_read_b128 v[70:73], v88 offset:20800
	ds_read_b128 v[124:127], v88 offset:23104
	ds_read_b128 v[128:131], v89 offset:18496
	ds_read_b128 v[132:135], v88 offset:27712
	ds_read_b128 v[136:139], v88 offset:30016
	ds_read_b128 v[140:143], v88 offset:32320
	ds_read_b128 v[144:147], v92 offset:18496
	s_waitcnt lgkmcnt(7)
	v_mfma_f32_16x16x32_bf16 v[78:81], v[54:57], v[104:107], v[58:61]
	s_waitcnt lgkmcnt(1)
	v_mfma_f32_16x16x32_bf16 v[54:57], v[140:143], v[104:107], v[100:103]
	s_nop 2
	v_or_b32_e32 v102, 1, v91
	v_sub_u32_e32 v0, v102, v99
	v_sub_u32_e32 v87, v99, v102
	v_cndmask_b32_e32 v0, v0, v87, vcc
	v_cvt_f32_i32_e32 v0, v0
	v_cndmask_b32_e32 v87, v97, v96, vcc
	v_mfma_f32_16x16x32_bf16 v[74:77], v[70:73], v[104:107], v[62:65]
	v_or_b32_e32 v103, 3, v91
	v_mul_f32_e32 v0, v87, v0
	v_mul_f32_e32 v0, 0xbfb8aa3b, v0
	v_exp_f32_e32 v87, v0
	v_mfma_f32_16x16x32_bf16 v[70:73], v[124:127], v[104:107], v[66:69]
	v_or_b32_e32 v100, 18, v91
	v_or_b32_e32 v101, 19, v91
	v_pk_mul_f32 v[78:79], v[86:87], v[78:79]
	v_mfma_f32_16x16x32_bf16 v[66:69], v[128:131], v[104:107], v[108:111]
	v_or_b32_e32 v124, 0x62, v91
	v_or_b32_e32 v125, 0x63, v91
	v_lshl_add_u32 v130, v93, 7, v88
	v_mfma_f32_16x16x32_bf16 v[62:65], v[132:135], v[104:107], v[112:115]
	v_or_b32_e32 v108, 35, v91
	v_or_b32_e32 v109, 48, v91
	v_or_b32_e32 v110, 49, v91
	v_mfma_f32_16x16x32_bf16 v[58:61], v[136:139], v[104:107], v[116:119]
	v_or_b32_e32 v111, 50, v91
	v_or_b32_e32 v112, 51, v91
	v_or_b32_e32 v113, 64, v91
	s_waitcnt lgkmcnt(0)
	v_mfma_f32_16x16x32_bf16 v[50:53], v[144:147], v[104:107], v[50:53]
	v_or_b32_e32 v104, 2, v91
	v_sub_u32_e32 v0, v99, v104
	v_sub_u32_e32 v86, 0, v0
	v_max_i32_e32 v0, v0, v86
	v_cvt_f32_u32_e32 v0, v0
	v_cmp_lt_i32_e32 vcc, v99, v104
	v_or_b32_e32 v105, 32, v91
	v_or_b32_e32 v106, 33, v91
	v_cndmask_b32_e32 v86, v96, v97, vcc
	v_mul_f32_e32 v0, v86, v0
	v_mul_f32_e32 v0, 0xbfb8aa3b, v0
	v_exp_f32_e32 v86, v0
	v_sub_u32_e32 v0, v99, v103
	v_sub_u32_e32 v87, 0, v0
	v_max_i32_e32 v0, v0, v87
	v_cvt_f32_u32_e32 v0, v0
	v_cmp_lt_i32_e32 vcc, v99, v103
	v_or_b32_e32 v107, 34, v91
	v_or_b32_e32 v114, 0x41, v91
	v_cndmask_b32_e32 v87, v96, v97, vcc
	v_mul_f32_e32 v0, v87, v0
	v_mul_f32_e32 v0, 0xbfb8aa3b, v0
	v_exp_f32_e32 v87, v0
	v_sub_u32_e32 v0, v99, v94
	v_cmp_lt_i32_e32 vcc, v99, v94
	v_or_b32_e32 v115, 0x42, v91
	v_pk_mul_f32 v[80:81], v[86:87], v[80:81]
	v_sub_u32_e32 v86, 0, v0
	v_max_i32_e32 v0, v0, v86
	v_cvt_f32_u32_e32 v0, v0
	v_cndmask_b32_e32 v86, v96, v97, vcc
	v_cmp_lt_i32_e32 vcc, v99, v95
	v_or_b32_e32 v116, 0x43, v91
	v_mul_f32_e32 v0, v86, v0
	v_mul_f32_e32 v0, 0xbfb8aa3b, v0
	v_exp_f32_e32 v86, v0
	v_sub_u32_e32 v0, v99, v95
	v_sub_u32_e32 v87, 0, v0
	v_max_i32_e32 v0, v0, v87
	v_cvt_f32_u32_e32 v0, v0
	v_cndmask_b32_e32 v87, v96, v97, vcc
	v_cmp_lt_i32_e32 vcc, v99, v100
	v_or_b32_e32 v117, 0x50, v91
	v_mul_f32_e32 v0, v87, v0
	v_mul_f32_e32 v0, 0xbfb8aa3b, v0
	v_exp_f32_e32 v87, v0
	v_sub_u32_e32 v0, v99, v100
	v_or_b32_e32 v118, 0x51, v91
	v_or_b32_e32 v119, 0x52, v91
	v_pk_mul_f32 v[74:75], v[86:87], v[74:75]
	v_sub_u32_e32 v86, 0, v0
	v_max_i32_e32 v0, v0, v86
	v_cvt_f32_u32_e32 v0, v0
	v_cndmask_b32_e32 v86, v96, v97, vcc
	v_cmp_lt_i32_e32 vcc, v99, v101
	v_cvt_pk_bf16_f32 v78, v78, v79
	v_mul_f32_e32 v0, v86, v0
	v_mul_f32_e32 v0, 0xbfb8aa3b, v0
	v_exp_f32_e32 v86, v0
	v_sub_u32_e32 v0, v99, v101
	v_sub_u32_e32 v87, 0, v0
	v_max_i32_e32 v0, v0, v87
	v_cvt_f32_u32_e32 v0, v0
	v_cndmask_b32_e32 v87, v96, v97, vcc
	v_cmp_lt_i32_e32 vcc, v99, v105
	v_cvt_pk_bf16_f32 v79, v80, v81
	v_mul_f32_e32 v0, v87, v0
	v_mul_f32_e32 v0, 0xbfb8aa3b, v0
	v_exp_f32_e32 v87, v0
	v_sub_u32_e32 v0, v99, v105
	v_cvt_pk_bf16_f32 v80, v74, v75
	v_or_b32_e32 v126, 0x70, v91
	v_pk_mul_f32 v[76:77], v[86:87], v[76:77]
	v_sub_u32_e32 v86, 0, v0
	v_max_i32_e32 v0, v0, v86
	v_cvt_f32_u32_e32 v0, v0
	v_cndmask_b32_e32 v86, v96, v97, vcc
	v_cmp_lt_i32_e32 vcc, v99, v106
	v_cvt_pk_bf16_f32 v81, v76, v77
	v_mul_f32_e32 v0, v86, v0
	v_mul_f32_e32 v0, 0xbfb8aa3b, v0
	v_exp_f32_e32 v86, v0
	v_sub_u32_e32 v0, v99, v106
	v_sub_u32_e32 v87, 0, v0
	v_max_i32_e32 v0, v0, v87
	v_cvt_f32_u32_e32 v0, v0
	v_cndmask_b32_e32 v87, v96, v97, vcc
	v_cmp_lt_i32_e32 vcc, v99, v107
	ds_read_b128 v[74:77], v130 offset:36864
	v_mul_f32_e32 v0, v87, v0
	v_mul_f32_e32 v0, 0xbfb8aa3b, v0
	v_exp_f32_e32 v87, v0
	v_sub_u32_e32 v0, v99, v107
	v_or_b32_e32 v127, 0x71, v91
	v_or_b32_e32 v128, 0x72, v91
	v_pk_mul_f32 v[70:71], v[86:87], v[70:71]
	v_sub_u32_e32 v86, 0, v0
	v_max_i32_e32 v0, v0, v86
	v_cvt_f32_u32_e32 v0, v0
	v_cndmask_b32_e32 v86, v96, v97, vcc
	v_cmp_lt_i32_e32 vcc, v99, v108
	v_cvt_pk_bf16_f32 v70, v70, v71
	v_mul_f32_e32 v0, v86, v0
	v_mul_f32_e32 v0, 0xbfb8aa3b, v0
	v_exp_f32_e32 v86, v0
	v_sub_u32_e32 v0, v99, v108
	v_sub_u32_e32 v87, 0, v0
	v_max_i32_e32 v0, v0, v87
	v_cvt_f32_u32_e32 v0, v0
	v_cndmask_b32_e32 v87, v96, v97, vcc
	v_cmp_lt_i32_e32 vcc, v99, v109
	v_or_b32_e32 v129, 0x73, v91
	v_mul_f32_e32 v0, v87, v0
	v_mul_f32_e32 v0, 0xbfb8aa3b, v0
	v_exp_f32_e32 v87, v0
	v_sub_u32_e32 v0, v99, v109
	v_pk_mul_f32 v[72:73], v[86:87], v[72:73]
	v_sub_u32_e32 v86, 0, v0
	v_max_i32_e32 v0, v0, v86
	v_cvt_f32_u32_e32 v0, v0
	v_cndmask_b32_e32 v86, v96, v97, vcc
	v_cmp_lt_i32_e32 vcc, v99, v110
	v_cvt_pk_bf16_f32 v71, v72, v73
	v_mul_f32_e32 v0, v86, v0
	v_mul_f32_e32 v0, 0xbfb8aa3b, v0
	v_exp_f32_e32 v86, v0
	v_sub_u32_e32 v0, v99, v110
	v_sub_u32_e32 v87, 0, v0
	v_max_i32_e32 v0, v0, v87
	v_cvt_f32_u32_e32 v0, v0
	v_cndmask_b32_e32 v87, v96, v97, vcc
	v_cmp_lt_i32_e32 vcc, v99, v111
	v_mul_f32_e32 v0, v87, v0
	v_mul_f32_e32 v0, 0xbfb8aa3b, v0
	v_exp_f32_e32 v87, v0
	v_sub_u32_e32 v0, v99, v111
	v_pk_mul_f32 v[66:67], v[86:87], v[66:67]
	v_sub_u32_e32 v86, 0, v0
	v_max_i32_e32 v0, v0, v86
	v_cvt_f32_u32_e32 v0, v0
	v_cndmask_b32_e32 v86, v96, v97, vcc
	v_cmp_lt_i32_e32 vcc, v99, v112
	v_cvt_pk_bf16_f32 v72, v66, v67
	v_mul_f32_e32 v0, v86, v0
	v_mul_f32_e32 v0, 0xbfb8aa3b, v0
	v_exp_f32_e32 v86, v0
	v_sub_u32_e32 v0, v99, v112
	v_sub_u32_e32 v87, 0, v0
	v_max_i32_e32 v0, v0, v87
	v_cvt_f32_u32_e32 v0, v0
	v_cndmask_b32_e32 v87, v96, v97, vcc
	v_cmp_lt_i32_e32 vcc, v99, v113
	v_mul_f32_e32 v0, v87, v0
	v_mul_f32_e32 v0, 0xbfb8aa3b, v0
	v_exp_f32_e32 v87, v0
	v_sub_u32_e32 v0, v99, v113
	v_pk_mul_f32 v[68:69], v[86:87], v[68:69]
	v_sub_u32_e32 v86, 0, v0
	v_max_i32_e32 v0, v0, v86
	v_cvt_f32_u32_e32 v0, v0
	v_cndmask_b32_e32 v86, v96, v97, vcc
	v_cmp_lt_i32_e32 vcc, v99, v114
	v_cvt_pk_bf16_f32 v73, v68, v69
	v_mul_f32_e32 v0, v86, v0
	v_mul_f32_e32 v0, 0xbfb8aa3b, v0
	v_exp_f32_e32 v86, v0
	v_sub_u32_e32 v0, v99, v114
	v_sub_u32_e32 v87, 0, v0
	v_max_i32_e32 v0, v0, v87
	v_cvt_f32_u32_e32 v0, v0
	v_cndmask_b32_e32 v87, v96, v97, vcc
	v_cmp_lt_i32_e32 vcc, v99, v115
	ds_read_b128 v[66:69], v130 offset:36928
	v_mul_f32_e32 v0, v87, v0
	v_mul_f32_e32 v0, 0xbfb8aa3b, v0
	v_exp_f32_e32 v87, v0
	v_sub_u32_e32 v0, v99, v115
	s_waitcnt lgkmcnt(1)
	v_mfma_f32_16x16x32_bf16 v[34:37], v[74:77], v[78:81], v[34:37]
	ds_read_b128 v[74:77], v130 offset:41216
	v_pk_mul_f32 v[62:63], v[86:87], v[62:63]
	v_sub_u32_e32 v86, 0, v0
	v_max_i32_e32 v0, v0, v86
	v_cvt_f32_u32_e32 v0, v0
	v_cndmask_b32_e32 v86, v96, v97, vcc
	v_cmp_lt_i32_e32 vcc, v99, v116
	v_cvt_pk_bf16_f32 v62, v62, v63
	v_mul_f32_e32 v0, v86, v0
	v_mul_f32_e32 v0, 0xbfb8aa3b, v0
	v_exp_f32_e32 v86, v0
	v_sub_u32_e32 v0, v99, v116
	v_sub_u32_e32 v87, 0, v0
	v_max_i32_e32 v0, v0, v87
	v_cvt_f32_u32_e32 v0, v0
	v_cndmask_b32_e32 v87, v96, v97, vcc
	v_cmp_lt_i32_e32 vcc, v99, v117
	s_waitcnt lgkmcnt(1)
	v_mfma_f32_16x16x32_bf16 v[34:37], v[66:69], v[70:73], v[34:37]
	v_mul_f32_e32 v0, v87, v0
	v_mul_f32_e32 v0, 0xbfb8aa3b, v0
	v_exp_f32_e32 v87, v0
	v_sub_u32_e32 v0, v99, v117
	ds_read_b128 v[66:69], v130 offset:41280
	v_pk_mul_f32 v[64:65], v[86:87], v[64:65]
	v_sub_u32_e32 v86, 0, v0
	v_max_i32_e32 v0, v0, v86
	v_cvt_f32_u32_e32 v0, v0
	v_cndmask_b32_e32 v86, v96, v97, vcc
	v_cmp_lt_i32_e32 vcc, v99, v118
	v_cvt_pk_bf16_f32 v63, v64, v65
	v_mul_f32_e32 v0, v86, v0
	v_mul_f32_e32 v0, 0xbfb8aa3b, v0
	v_exp_f32_e32 v86, v0
	v_sub_u32_e32 v0, v99, v118
	v_sub_u32_e32 v87, 0, v0
	v_max_i32_e32 v0, v0, v87
	v_cvt_f32_u32_e32 v0, v0
	v_cndmask_b32_e32 v87, v96, v97, vcc
	v_cmp_lt_i32_e32 vcc, v99, v119
	v_mul_f32_e32 v0, v87, v0
	v_mul_f32_e32 v0, 0xbfb8aa3b, v0
	v_exp_f32_e32 v87, v0
	v_sub_u32_e32 v0, v99, v119
	v_pk_mul_f32 v[58:59], v[86:87], v[58:59]
	v_sub_u32_e32 v86, 0, v0
	v_max_i32_e32 v0, v0, v86
	v_cvt_f32_u32_e32 v0, v0
	v_cndmask_b32_e32 v86, v96, v97, vcc
	v_cmp_lt_i32_e32 vcc, v99, v120
	v_cvt_pk_bf16_f32 v64, v58, v59
	v_mul_f32_e32 v0, v86, v0
	v_mul_f32_e32 v0, 0xbfb8aa3b, v0
	v_exp_f32_e32 v86, v0
	v_sub_u32_e32 v0, v99, v120
	v_sub_u32_e32 v87, 0, v0
	v_max_i32_e32 v0, v0, v87
	v_cvt_f32_u32_e32 v0, v0
	v_cndmask_b32_e32 v87, v96, v97, vcc
	v_cmp_lt_i32_e32 vcc, v99, v121
	v_mul_f32_e32 v0, v87, v0
	v_mul_f32_e32 v0, 0xbfb8aa3b, v0
	v_exp_f32_e32 v87, v0
	v_sub_u32_e32 v0, v99, v121
	v_pk_mul_f32 v[60:61], v[86:87], v[60:61]
	v_sub_u32_e32 v86, 0, v0
	v_max_i32_e32 v0, v0, v86
	v_cvt_f32_u32_e32 v0, v0
	v_cndmask_b32_e32 v86, v96, v97, vcc
	v_cmp_lt_i32_e32 vcc, v99, v123
	v_cvt_pk_bf16_f32 v65, v60, v61
	v_mul_f32_e32 v0, v86, v0
	v_mul_f32_e32 v0, 0xbfb8aa3b, v0
	v_exp_f32_e32 v86, v0
	v_sub_u32_e32 v0, v99, v123
	v_sub_u32_e32 v87, 0, v0
	v_max_i32_e32 v0, v0, v87
	v_cvt_f32_u32_e32 v0, v0
	v_cndmask_b32_e32 v87, v96, v97, vcc
	v_cmp_lt_i32_e32 vcc, v99, v124
	ds_read_b128 v[58:61], v130 offset:36992
	v_mul_f32_e32 v0, v87, v0
	v_mul_f32_e32 v0, 0xbfb8aa3b, v0
	v_exp_f32_e32 v87, v0
	v_sub_u32_e32 v0, v99, v124
	s_waitcnt lgkmcnt(2)
	v_mfma_f32_16x16x32_bf16 v[38:41], v[74:77], v[78:81], v[38:41]
	ds_read_b128 v[74:77], v130 offset:45568
	v_pk_mul_f32 v[54:55], v[86:87], v[54:55]
	v_sub_u32_e32 v86, 0, v0
	v_max_i32_e32 v0, v0, v86
	v_cvt_f32_u32_e32 v0, v0
	v_cndmask_b32_e32 v86, v96, v97, vcc
	v_cmp_lt_i32_e32 vcc, v99, v125
	s_waitcnt lgkmcnt(1)
	v_mfma_f32_16x16x32_bf16 v[34:37], v[58:61], v[62:65], v[34:37]
	v_mul_f32_e32 v0, v86, v0
	v_mul_f32_e32 v0, 0xbfb8aa3b, v0
	v_exp_f32_e32 v86, v0
	v_sub_u32_e32 v0, v99, v125
	v_sub_u32_e32 v87, 0, v0
	v_max_i32_e32 v0, v0, v87
	v_cvt_f32_u32_e32 v0, v0
	v_cndmask_b32_e32 v87, v96, v97, vcc
	v_cmp_lt_i32_e32 vcc, v99, v126
	ds_read_b128 v[58:61], v130 offset:41344
	v_mul_f32_e32 v0, v87, v0
	v_mul_f32_e32 v0, 0xbfb8aa3b, v0
	v_exp_f32_e32 v87, v0
	v_sub_u32_e32 v0, v99, v126
	v_mfma_f32_16x16x32_bf16 v[38:41], v[66:69], v[70:73], v[38:41]
	ds_read_b128 v[66:69], v130 offset:45632
	v_pk_mul_f32 v[56:57], v[86:87], v[56:57]
	v_sub_u32_e32 v86, 0, v0
	v_max_i32_e32 v0, v0, v86
	v_cvt_f32_u32_e32 v0, v0
	v_cndmask_b32_e32 v86, v96, v97, vcc
	v_cmp_lt_i32_e32 vcc, v99, v127
	s_waitcnt lgkmcnt(2)
	v_mfma_f32_16x16x32_bf16 v[42:45], v[74:77], v[78:81], v[42:45]
	v_mul_f32_e32 v0, v86, v0
	v_mul_f32_e32 v0, 0xbfb8aa3b, v0
	v_exp_f32_e32 v86, v0
	v_sub_u32_e32 v0, v99, v127
	v_sub_u32_e32 v87, 0, v0
	v_max_i32_e32 v0, v0, v87
	v_cvt_f32_u32_e32 v0, v0
	v_cndmask_b32_e32 v87, v96, v97, vcc
	ds_read_b128 v[74:77], v130 offset:49920
	s_waitcnt lgkmcnt(2)
	v_mfma_f32_16x16x32_bf16 v[38:41], v[58:61], v[62:65], v[38:41]
	v_mul_f32_e32 v0, v87, v0
	v_mul_f32_e32 v0, 0xbfb8aa3b, v0
	v_exp_f32_e32 v87, v0
	ds_read_b128 v[58:61], v130 offset:45696
	v_sub_u32_e32 v0, v99, v128
	s_waitcnt lgkmcnt(2)
	v_mfma_f32_16x16x32_bf16 v[42:45], v[66:69], v[70:73], v[42:45]
	v_mul_f32_e64 v50, v86, v50
	v_mul_f32_e64 v51, v87, v51
	v_sub_u32_e32 v86, 0, v0
	v_max_i32_e32 v0, v0, v86
	ds_read_b128 v[66:69], v130 offset:49984
	v_cvt_f32_u32_e32 v0, v0
	v_cmp_lt_i32_e32 vcc, v99, v128
	s_waitcnt lgkmcnt(1)
	v_mfma_f32_16x16x32_bf16 v[58:61], v[58:61], v[62:65], v[42:45]
	v_cndmask_b32_e32 v86, v96, v97, vcc
	v_mul_f32_e32 v0, v86, v0
	s_nop 0
	ds_read_b128 v[42:45], v130 offset:50048
	v_mfma_f32_16x16x32_bf16 v[46:49], v[74:77], v[78:81], v[46:49]
	v_mul_f32_e32 v0, 0xbfb8aa3b, v0
	v_exp_f32_e32 v86, v0
	v_sub_u32_e32 v0, v99, v129
	v_sub_u32_e32 v87, 0, v0
	v_max_i32_e32 v0, v0, v87
	s_waitcnt lgkmcnt(1)
	v_mfma_f32_16x16x32_bf16 v[46:49], v[66:69], v[70:73], v[46:49]
	v_cvt_f32_u32_e32 v0, v0
	v_cmp_lt_i32_e32 vcc, v99, v129
	s_waitcnt lgkmcnt(0)
	v_mfma_f32_16x16x32_bf16 v[62:65], v[42:45], v[62:65], v[46:49]
	v_cndmask_b32_e32 v87, v96, v97, vcc
	ds_read_b128 v[42:45], v130 offset:37056
	v_mul_f32_e32 v0, v87, v0
	v_mul_f32_e32 v0, 0xbfb8aa3b, v0
	v_exp_f32_e32 v87, v0
	s_nop 0
	v_pk_mul_f32 v[86:87], v[86:87], v[52:53]
	v_cvt_pk_bf16_f32 v52, v54, v55
	v_cvt_pk_bf16_f32 v53, v56, v57
	v_cvt_pk_bf16_f32 v54, v50, v51
	v_cvt_pk_bf16_f32 v55, v86, v87
	s_waitcnt lgkmcnt(0)
	s_nop 0
	v_mfma_f32_16x16x32_bf16 v[46:49], v[42:45], v[52:55], v[34:37]
	s_nop 2
	ds_read_b128 v[34:37], v130 offset:41408
	s_waitcnt lgkmcnt(0)
	v_mfma_f32_16x16x32_bf16 v[42:45], v[34:37], v[52:55], v[38:41]
	ds_read_b128 v[34:37], v130 offset:45760
	s_nop 0
	v_mul_f32_e32 v0, v47, v47
	v_fmac_f32_e32 v0, v46, v46
	s_waitcnt lgkmcnt(0)
	v_mfma_f32_16x16x32_bf16 v[38:41], v[34:37], v[52:55], v[58:61]
	ds_read_b128 v[34:37], v130 offset:50112
	v_fmac_f32_e32 v0, v48, v48
	v_fmac_f32_e32 v0, v49, v49
	v_fmac_f32_e32 v0, v42, v42
	v_fmac_f32_e32 v0, v43, v43
	v_fmac_f32_e32 v0, v44, v44
	s_waitcnt lgkmcnt(0)
	v_mfma_f32_16x16x32_bf16 v[34:37], v[34:37], v[52:55], v[62:65]
	v_fmac_f32_e32 v0, v45, v45
	v_pk_mul_f32 v[52:53], v[38:39], v[38:39]
	v_pk_mul_f32 v[50:51], v[40:41], v[40:41]
	v_add_f32_e32 v0, v52, v0
	v_add_f32_e32 v0, v53, v0
	v_add_f32_e32 v0, v50, v0
	v_add_f32_e32 v0, v51, v0
	s_nop 0
	v_pk_mul_f32 v[52:53], v[34:35], v[34:35]
	v_pk_mul_f32 v[50:51], v[36:37], v[36:37]
	v_add_f32_e32 v0, v52, v0
	v_add_f32_e32 v0, v53, v0
	v_add_f32_e32 v0, v50, v0
	v_add_f32_e32 v0, v51, v0
	v_and_b32_e32 v51, 64, v170
	v_xor_b32_e32 v50, 16, v170
	v_add_u32_e32 v51, 64, v51
	v_cmp_lt_i32_e32 vcc, v50, v51
	v_mad_i64_i32 v[52:53], s[6:7], v99, s52, v[82:83]
	s_nop 0
	v_cndmask_b32_e32 v50, v170, v50, vcc
	v_lshlrev_b32_e32 v131, 2, v50
	ds_bpermute_b32 v50, v131, v0
	v_lshl_add_u64 v[52:53], v[52:53], 0, v[84:85]
	s_waitcnt lgkmcnt(0)
	v_add_f32_e32 v0, v0, v50
	v_xor_b32_e32 v50, 32, v170
	v_cmp_lt_i32_e32 vcc, v50, v51
	s_nop 1
	v_cndmask_b32_e32 v50, v170, v50, vcc
	v_lshlrev_b32_e32 v132, 2, v50
	ds_bpermute_b32 v50, v132, v0
	s_waitcnt lgkmcnt(0)
	v_add_f32_e32 v0, v0, v50
	v_fmamk_f32 v0, v0, 0x3c800000, v158
	v_cmp_gt_f32_e32 vcc, s66, v0
	v_mul_f32_e32 v50, 0x4b800000, v0
	s_nop 0
	v_cndmask_b32_e32 v0, v0, v50, vcc
	v_rsq_f32_e32 v0, v0
	s_nop 0
	v_mul_f32_e32 v50, 0x45800000, v0
	v_cndmask_b32_e32 v50, v0, v50, vcc
	v_lshlrev_b32_e32 v0, 1, v91
	v_lshl_add_u64 v[52:53], v[52:53], 0, v[0:1]
	global_load_dwordx2 v[54:55], v[52:53], off offset:1536
	global_load_dwordx2 v[214:215], v[52:53], off offset:1568
	global_load_dwordx2 v[216:217], v[52:53], off offset:1600
	global_load_dwordx2 v[218:219], v[52:53], off offset:1632
	v_cmp_lt_i32_e32 vcc, v98, v91
	s_waitcnt vmcnt(0) lgkmcnt(0)
	v_lshlrev_b32_e32 v56, 16, v54
	v_mul_f32_e32 v51, 0xbfb8aa3b, v56
	v_exp_f32_e32 v51, v51
	v_and_b32_e32 v57, 0xffff0000, v54
	v_lshlrev_b32_e32 v54, 16, v55
	v_and_b32_e32 v55, 0xffff0000, v55
	v_add_f32_e32 v51, 1.0, v51
	v_rcp_f32_e32 v58, v51
	v_mul_f32_e32 v51, 0xbfb8aa3b, v57
	v_exp_f32_e32 v51, v51
	s_nop 0
	v_add_f32_e32 v51, 1.0, v51
	v_rcp_f32_e32 v59, v51
	s_nop 0
	v_pk_mul_f32 v[56:57], v[58:59], v[56:57]
	s_nop 0
	v_pk_mul_f32 v[56:57], v[56:57], v[50:51] op_sel_hi:[1,0]
	v_mul_f32_e32 v51, 0xbfb8aa3b, v54
	v_exp_f32_e32 v51, v51
	v_pk_mul_f32 v[46:47], v[46:47], v[56:57]
	v_add_f32_e32 v51, 1.0, v51
	v_rcp_f32_e32 v56, v51
	v_mul_f32_e32 v51, 0xbfb8aa3b, v55
	v_exp_f32_e32 v51, v51
	v_cvt_pk_bf16_f32 v46, v46, v47
	v_add_f32_e32 v51, 1.0, v51
	v_rcp_f32_e32 v57, v51
	s_nop 0
	v_pk_mul_f32 v[54:55], v[56:57], v[54:55]
	s_nop 0
	v_pk_mul_f32 v[54:55], v[54:55], v[50:51] op_sel_hi:[1,0]
	s_nop 0
	v_pk_mul_f32 v[48:49], v[48:49], v[54:55]
	s_nop 0
	v_cvt_pk_bf16_f32 v47, v48, v49
	global_store_dwordx2 v[52:53], v[46:47], off offset:1536
	s_nop 0
	s_nop 0
	v_lshlrev_b32_e32 v48, 16, v214
	v_mul_f32_e32 v51, 0xbfb8aa3b, v48
	v_exp_f32_e32 v51, v51
	v_and_b32_e32 v49, 0xffff0000, v214
	v_lshlrev_b32_e32 v46, 16, v215
	v_and_b32_e32 v47, 0xffff0000, v215
	v_add_f32_e32 v51, 1.0, v51
	v_rcp_f32_e32 v54, v51
	v_mul_f32_e32 v51, 0xbfb8aa3b, v49
	v_exp_f32_e32 v51, v51
	s_nop 0
	v_add_f32_e32 v51, 1.0, v51
	v_rcp_f32_e32 v55, v51
	s_nop 0
	v_pk_mul_f32 v[48:49], v[54:55], v[48:49]
	s_nop 0
	v_pk_mul_f32 v[48:49], v[48:49], v[50:51] op_sel_hi:[1,0]
	s_nop 0
	v_pk_mul_f32 v[42:43], v[42:43], v[48:49]
	v_mul_f32_e32 v48, 0xbfb8aa3b, v46
	v_mul_f32_e32 v49, 0xbfb8aa3b, v47
	v_exp_f32_e32 v48, v48
	v_exp_f32_e32 v49, v49
	v_cvt_pk_bf16_f32 v42, v42, v43
	v_add_f32_e32 v48, 1.0, v48
	v_add_f32_e32 v49, 1.0, v49
	v_rcp_f32_e32 v48, v48
	v_rcp_f32_e32 v49, v49
	s_nop 0
	v_pk_mul_f32 v[46:47], v[48:49], v[46:47]
	s_nop 0
	v_pk_mul_f32 v[46:47], v[46:47], v[50:51] op_sel_hi:[1,0]
	s_nop 0
	v_pk_mul_f32 v[44:45], v[44:45], v[46:47]
	s_nop 0
	v_cvt_pk_bf16_f32 v43, v44, v45
	global_store_dwordx2 v[52:53], v[42:43], off offset:1568
	s_nop 0
	s_nop 0
	v_lshlrev_b32_e32 v44, 16, v216
	v_and_b32_e32 v45, 0xffff0000, v216
	v_mul_f32_e32 v46, 0xbfb8aa3b, v44
	v_mul_f32_e32 v47, 0xbfb8aa3b, v45
	v_exp_f32_e32 v46, v46
	v_exp_f32_e32 v47, v47
	v_lshlrev_b32_e32 v42, 16, v217
	v_and_b32_e32 v43, 0xffff0000, v217
	v_add_f32_e32 v46, 1.0, v46
	v_add_f32_e32 v47, 1.0, v47
	v_rcp_f32_e32 v46, v46
	v_rcp_f32_e32 v47, v47
	s_nop 0
	v_pk_mul_f32 v[44:45], v[46:47], v[44:45]
	s_nop 0
	v_pk_mul_f32 v[44:45], v[44:45], v[50:51] op_sel_hi:[1,0]
	s_nop 0
	v_pk_mul_f32 v[38:39], v[38:39], v[44:45]
	v_mul_f32_e32 v44, 0xbfb8aa3b, v42
	v_mul_f32_e32 v45, 0xbfb8aa3b, v43
	v_exp_f32_e32 v44, v44
	v_exp_f32_e32 v45, v45
	v_cvt_pk_bf16_f32 v38, v38, v39
	v_add_f32_e32 v44, 1.0, v44
	v_add_f32_e32 v45, 1.0, v45
	v_rcp_f32_e32 v44, v44
	v_rcp_f32_e32 v45, v45
	s_nop 0
	v_pk_mul_f32 v[42:43], v[44:45], v[42:43]
	s_nop 0
	v_pk_mul_f32 v[42:43], v[50:51], v[42:43] op_sel_hi:[0,1]
	v_pk_mul_f32 v[40:41], v[40:41], v[42:43]
	s_nop 0
	v_cvt_pk_bf16_f32 v39, v40, v41
	global_store_dwordx2 v[52:53], v[38:39], off offset:1600
	s_nop 0
	s_nop 0
	v_lshlrev_b32_e32 v40, 16, v218
	v_and_b32_e32 v41, 0xffff0000, v218
	v_mul_f32_e32 v42, 0xbfb8aa3b, v40
	v_mul_f32_e32 v43, 0xbfb8aa3b, v41
	v_exp_f32_e32 v42, v42
	v_exp_f32_e32 v43, v43
	v_lshlrev_b32_e32 v38, 16, v219
	v_and_b32_e32 v39, 0xffff0000, v219
	v_add_f32_e32 v42, 1.0, v42
	v_add_f32_e32 v43, 1.0, v43
	v_rcp_f32_e32 v42, v42
	v_rcp_f32_e32 v43, v43
	s_nop 0
	v_pk_mul_f32 v[40:41], v[42:43], v[40:41]
	s_nop 0
	v_pk_mul_f32 v[40:41], v[50:51], v[40:41] op_sel_hi:[0,1]
	v_pk_mul_f32 v[34:35], v[34:35], v[40:41]
	v_mul_f32_e32 v40, 0xbfb8aa3b, v38
	v_mul_f32_e32 v41, 0xbfb8aa3b, v39
	v_exp_f32_e32 v40, v40
	v_exp_f32_e32 v41, v41
	v_cvt_pk_bf16_f32 v34, v34, v35
	v_add_f32_e32 v40, 1.0, v40
	v_add_f32_e32 v41, 1.0, v41
	v_rcp_f32_e32 v40, v40
	v_rcp_f32_e32 v41, v41
	s_nop 0
	v_pk_mul_f32 v[38:39], v[40:41], v[38:39]
	s_nop 0
	v_pk_mul_f32 v[38:39], v[50:51], v[38:39] op_sel_hi:[0,1]
	v_pk_mul_f32 v[36:37], v[36:37], v[38:39]
	s_nop 0
	v_cvt_pk_bf16_f32 v35, v36, v37
	global_store_dwordx2 v[52:53], v[34:35], off offset:1632
	v_mov_b32_e32 v34, v1
	ds_read_b128 v[38:41], v90 offset:9216
	ds_read_b128 v[42:45], v88 offset:18432
	ds_read_b128 v[46:49], v88 offset:20736
	ds_read_b128 v[50:53], v88 offset:23040
	ds_read_b128 v[54:57], v89 offset:18432
	ds_read_b128 v[58:61], v88 offset:27648
	ds_read_b128 v[62:65], v88 offset:29952
	ds_read_b128 v[66:69], v88 offset:32256
	ds_read_b128 v[70:73], v92 offset:18432
	v_mov_b32_e32 v35, v34
	v_mov_b32_e32 v36, v34
	v_mov_b32_e32 v37, v34
	s_waitcnt lgkmcnt(0)
	s_nop 0
	v_mfma_f32_16x16x32_bf16 v[42:45], v[42:45], v[38:41], v[34:37]
	v_mfma_f32_16x16x32_bf16 v[46:49], v[46:49], v[38:41], v[34:37]
	v_mfma_f32_16x16x32_bf16 v[50:53], v[50:53], v[38:41], v[34:37]
	v_mfma_f32_16x16x32_bf16 v[74:77], v[54:57], v[38:41], v[34:37]
	v_mfma_f32_16x16x32_bf16 v[78:81], v[58:61], v[38:41], v[34:37]
	v_mfma_f32_16x16x32_bf16 v[134:137], v[62:65], v[38:41], v[34:37]
	v_mfma_f32_16x16x32_bf16 v[66:69], v[66:69], v[38:41], v[34:37]
	v_mfma_f32_16x16x32_bf16 v[34:37], v[70:73], v[38:41], v[34:37]
	ds_read_b128 v[70:73], v90 offset:9280
	ds_read_b128 v[38:41], v88 offset:18496
	ds_read_b128 v[54:57], v88 offset:20800
	ds_read_b128 v[138:141], v88 offset:23104
	ds_read_b128 v[142:145], v89 offset:18496
	ds_read_b128 v[146:149], v88 offset:27712
	ds_read_b128 v[150:153], v88 offset:30016
	ds_read_b128 v[86:89], v88 offset:32320
	ds_read_b128 v[166:169], v92 offset:18496
	s_waitcnt lgkmcnt(0)
	v_mfma_f32_16x16x32_bf16 v[62:65], v[38:41], v[70:73], v[42:45]
	v_mfma_f32_16x16x32_bf16 v[38:41], v[86:89], v[70:73], v[66:69]
	s_nop 2
	v_sub_u32_e32 v66, v98, v91
	v_sub_u32_e32 v67, 0, v66
	v_max_i32_e32 v66, v66, v67
	v_cvt_f32_u32_e32 v66, v66
	v_cndmask_b32_e32 v67, v96, v97, vcc
	v_cmp_gt_i32_e32 vcc, v98, v91
	v_sub_u32_e32 v68, v98, v102
	v_mul_f32_e32 v66, v67, v66
	v_sub_u32_e32 v67, v102, v98
	v_cndmask_b32_e32 v67, v67, v68, vcc
	v_cvt_f32_i32_e32 v67, v67
	v_cndmask_b32_e32 v68, v97, v96, vcc
	v_cmp_lt_i32_e32 vcc, v98, v104
	v_mfma_f32_16x16x32_bf16 v[58:61], v[54:57], v[70:73], v[46:49]
	v_mul_f32_e32 v67, v68, v67
	v_sub_u32_e32 v68, v98, v104
	v_sub_u32_e32 v69, 0, v68
	v_max_i32_e32 v68, v68, v69
	v_cvt_f32_u32_e32 v68, v68
	v_cndmask_b32_e32 v69, v96, v97, vcc
	v_mfma_f32_16x16x32_bf16 v[54:57], v[138:141], v[70:73], v[50:53]
	v_cmp_lt_i32_e32 vcc, v98, v103
	v_mul_f32_e32 v68, v69, v68
	v_sub_u32_e32 v69, v98, v103
	v_mfma_f32_16x16x32_bf16 v[50:53], v[142:145], v[70:73], v[74:77]
	v_mul_f32_e32 v66, 0xbfb8aa3b, v66
	v_mul_f32_e32 v67, 0xbfb8aa3b, v67
	v_exp_f32_e32 v66, v66
	v_mfma_f32_16x16x32_bf16 v[46:49], v[146:149], v[70:73], v[78:81]
	v_exp_f32_e32 v67, v67
	v_mul_f32_e32 v68, 0xbfb8aa3b, v68
	v_exp_f32_e32 v68, v68
	v_mfma_f32_16x16x32_bf16 v[42:45], v[150:153], v[70:73], v[134:137]
	v_mul_f32_e64 v62, v66, v62
	v_mul_f32_e64 v63, v67, v63
	v_sub_u32_e32 v67, 64, v99
	v_add_u32_e32 v66, 0x41, v99
	v_mfma_f32_16x16x32_bf16 v[34:37], v[166:169], v[70:73], v[34:37]
	v_sub_u32_e32 v70, 0, v69
	v_max_i32_e32 v69, v69, v70
	v_cvt_f32_u32_e32 v69, v69
	v_cndmask_b32_e32 v70, v96, v97, vcc
	v_cmp_lt_i32_e32 vcc, v98, v94
	v_cvt_f32_i32_e32 v67, v67
	v_mul_f32_e32 v69, v70, v69
	v_sub_u32_e32 v70, v98, v94
	v_sub_u32_e32 v71, 0, v70
	v_max_i32_e32 v70, v70, v71
	v_cvt_f32_u32_e32 v70, v70
	v_cndmask_b32_e32 v71, v96, v97, vcc
	v_cmp_lt_i32_e32 vcc, v98, v95
	v_mul_f32_e32 v69, 0xbfb8aa3b, v69
	v_mul_f32_e32 v70, v71, v70
	v_sub_u32_e32 v71, v98, v95
	v_sub_u32_e32 v72, 0, v71
	v_max_i32_e32 v71, v71, v72
	v_cvt_f32_u32_e32 v71, v71
	v_cndmask_b32_e32 v72, v96, v97, vcc
	v_cmp_lt_i32_e32 vcc, v98, v100
	v_cvt_f32_i32_e32 v66, v66
	v_mul_f32_e32 v71, v72, v71
	v_sub_u32_e32 v72, v98, v100
	v_sub_u32_e32 v73, 0, v72
	v_max_i32_e32 v72, v72, v73
	v_cvt_f32_u32_e32 v72, v72
	v_cndmask_b32_e32 v73, v96, v97, vcc
	v_cmp_lt_i32_e32 vcc, v98, v101
	v_exp_f32_e32 v69, v69
	v_mul_f32_e32 v72, v73, v72
	v_sub_u32_e32 v73, v98, v101
	v_sub_u32_e32 v74, 0, v73
	v_max_i32_e32 v73, v73, v74
	v_cvt_f32_u32_e32 v73, v73
	v_cndmask_b32_e32 v74, v96, v97, vcc
	v_cmp_lt_i32_e32 vcc, v98, v105
	v_mul_f32_e32 v67, v67, v97
	v_mul_f32_e32 v73, v74, v73
	v_sub_u32_e32 v74, v98, v105
	v_sub_u32_e32 v75, 0, v74
	v_max_i32_e32 v74, v74, v75
	v_cvt_f32_u32_e32 v74, v74
	v_cndmask_b32_e32 v75, v96, v97, vcc
	v_cmp_lt_i32_e32 vcc, v98, v106
	v_mul_f32_e32 v66, v66, v96
	v_mul_f32_e32 v74, v75, v74
	v_sub_u32_e32 v75, v98, v106
	v_sub_u32_e32 v76, 0, v75
	v_max_i32_e32 v75, v75, v76
	v_cvt_f32_u32_e32 v75, v75
	v_cndmask_b32_e32 v76, v96, v97, vcc
	v_cmp_lt_i32_e32 vcc, v98, v107
	v_mul_f32_e32 v67, 0xbfb8aa3b, v67
	v_mul_f32_e32 v75, v76, v75
	v_sub_u32_e32 v76, v98, v107
	v_sub_u32_e32 v77, 0, v76
	v_max_i32_e32 v76, v76, v77
	v_cvt_f32_u32_e32 v76, v76
	v_cndmask_b32_e32 v77, v96, v97, vcc
	v_cmp_lt_i32_e32 vcc, v98, v108
	v_pk_mul_f32 v[64:65], v[68:69], v[64:65]
	v_mul_f32_e32 v76, v77, v76
	v_sub_u32_e32 v77, v98, v108
	v_sub_u32_e32 v78, 0, v77
	v_max_i32_e32 v77, v77, v78
	v_cvt_f32_u32_e32 v77, v77
	v_cndmask_b32_e32 v78, v96, v97, vcc
	v_cmp_lt_i32_e32 vcc, v98, v109
	v_mul_f32_e32 v66, 0xbfb8aa3b, v66
	v_mul_f32_e32 v77, v78, v77
	v_sub_u32_e32 v78, v98, v109
	v_sub_u32_e32 v79, 0, v78
	v_max_i32_e32 v78, v78, v79
	v_cvt_f32_u32_e32 v78, v78
	v_cndmask_b32_e32 v79, v96, v97, vcc
	v_cmp_lt_i32_e32 vcc, v98, v110
	v_exp_f32_e32 v68, v67
	v_mul_f32_e32 v78, v79, v78
	v_sub_u32_e32 v79, v98, v110
	v_sub_u32_e32 v80, 0, v79
	v_max_i32_e32 v79, v79, v80
	v_cvt_f32_u32_e32 v79, v79
	v_cndmask_b32_e32 v80, v96, v97, vcc
	v_cmp_lt_i32_e32 vcc, v98, v111
	v_exp_f32_e32 v66, v66
	v_mul_f32_e32 v79, v80, v79
	v_sub_u32_e32 v80, v98, v111
	v_sub_u32_e32 v81, 0, v80
	v_max_i32_e32 v80, v80, v81
	v_cvt_f32_u32_e32 v80, v80
	v_cndmask_b32_e32 v81, v96, v97, vcc
	v_cmp_lt_i32_e32 vcc, v98, v112
	v_pk_mul_f32 v[22:23], v[68:69], v[22:23] op_sel_hi:[0,1]
	v_mul_f32_e32 v80, v81, v80
	v_sub_u32_e32 v81, v98, v112
	v_sub_u32_e32 v86, 0, v81
	v_max_i32_e32 v81, v81, v86
	v_cvt_f32_u32_e32 v81, v81
	v_cndmask_b32_e32 v86, v96, v97, vcc
	v_pk_mul_f32 v[24:25], v[68:69], v[24:25] op_sel_hi:[0,1]
	v_pk_fma_f32 v[20:21], v[66:67], v[20:21], v[24:25] op_sel_hi:[0,1,1]
	v_mul_f32_e32 v81, v86, v81
	v_sub_u32_e32 v86, v98, v113
	v_sub_u32_e32 v87, 0, v86
	v_max_i32_e32 v86, v86, v87
	v_cvt_f32_u32_e32 v86, v86
	v_pk_fma_f32 v[18:19], v[66:67], v[18:19], v[22:23] op_sel_hi:[0,1,1]
	ds_read_b128 v[22:25], v130 offset:36864
	v_mul_f32_e32 v70, 0xbfb8aa3b, v70
	v_mul_f32_e32 v71, 0xbfb8aa3b, v71
	v_mul_f32_e32 v72, 0xbfb8aa3b, v72
	v_mul_f32_e32 v73, 0xbfb8aa3b, v73
	v_cmp_lt_i32_e32 vcc, v98, v113
	v_exp_f32_e32 v70, v70
	v_exp_f32_e32 v71, v71
	v_exp_f32_e32 v72, v72
	v_exp_f32_e32 v73, v73
	v_cndmask_b32_e32 v87, v96, v97, vcc
	v_mul_f32_e32 v86, v87, v86
	v_sub_u32_e32 v87, v98, v114
	v_sub_u32_e32 v88, 0, v87
	v_max_i32_e32 v87, v87, v88
	v_cvt_f32_u32_e32 v87, v87
	v_pk_mul_f32 v[58:59], v[70:71], v[58:59]
	v_pk_mul_f32 v[60:61], v[72:73], v[60:61]
	v_pk_mul_f32 v[14:15], v[68:69], v[14:15] op_sel_hi:[0,1]
	v_pk_mul_f32 v[16:17], v[68:69], v[16:17] op_sel_hi:[0,1]
	v_pk_mul_f32 v[10:11], v[68:69], v[10:11] op_sel_hi:[0,1]
	v_pk_mul_f32 v[12:13], v[68:69], v[12:13] op_sel_hi:[0,1]
	v_pk_fma_f32 v[8:9], v[66:67], v[8:9], v[16:17] op_sel_hi:[0,1,1]
	v_pk_fma_f32 v[6:7], v[66:67], v[6:7], v[14:15] op_sel_hi:[0,1,1]
	v_pk_fma_f32 v[12:13], v[66:67], v[4:5], v[12:13] op_sel_hi:[0,1,1]
	v_pk_fma_f32 v[10:11], v[66:67], v[2:3], v[10:11] op_sel_hi:[0,1,1]
	v_cvt_pk_bf16_f32 v14, v62, v63
	v_cvt_pk_bf16_f32 v15, v64, v65
	v_cvt_pk_bf16_f32 v16, v58, v59
	v_cvt_pk_bf16_f32 v17, v60, v61
	v_cmp_lt_i32_e32 vcc, v98, v114
	v_pk_mul_f32 v[30:31], v[68:69], v[30:31] op_sel_hi:[0,1]
	s_waitcnt lgkmcnt(0)
	v_mfma_f32_16x16x32_bf16 v[10:13], v[22:25], v[14:17], v[10:13]
	ds_read_b128 v[22:25], v130 offset:41216
	v_cndmask_b32_e32 v88, v96, v97, vcc
	v_mul_f32_e32 v87, v88, v87
	v_sub_u32_e32 v88, v98, v115
	v_sub_u32_e32 v89, 0, v88
	v_max_i32_e32 v88, v88, v89
	v_cvt_f32_u32_e32 v88, v88
	v_cmp_lt_i32_e32 vcc, v98, v115
	s_waitcnt lgkmcnt(0)
	v_mfma_f32_16x16x32_bf16 v[4:7], v[22:25], v[14:17], v[6:9]
	v_cndmask_b32_e32 v89, v96, v97, vcc
	v_mul_f32_e32 v88, v89, v88
	v_sub_u32_e32 v89, v98, v116
	ds_read_b128 v[22:25], v130 offset:45568
	v_sub_u32_e32 v90, 0, v89
	v_max_i32_e32 v89, v89, v90
	v_cvt_f32_u32_e32 v89, v89
	v_cmp_lt_i32_e32 vcc, v98, v116
	s_waitcnt lgkmcnt(0)
	v_mfma_f32_16x16x32_bf16 v[18:21], v[22:25], v[14:17], v[18:21]
	v_cndmask_b32_e32 v90, v96, v97, vcc
	v_mul_f32_e32 v89, v90, v89
	v_sub_u32_e32 v90, v98, v117
	v_sub_u32_e32 v91, 0, v90
	v_max_i32_e32 v90, v90, v91
	ds_read_b128 v[22:25], v130 offset:49920
	v_cvt_f32_u32_e32 v90, v90
	v_cmp_lt_i32_e32 vcc, v98, v117
	v_pk_mul_f32 v[32:33], v[68:69], v[32:33] op_sel_hi:[0,1]
	v_pk_fma_f32 v[28:29], v[66:67], v[28:29], v[32:33] op_sel_hi:[0,1,1]
	v_cndmask_b32_e32 v91, v96, v97, vcc
	v_mul_f32_e32 v90, v91, v90
	v_sub_u32_e32 v91, v98, v118
	v_sub_u32_e32 v92, 0, v91
	v_max_i32_e32 v91, v91, v92
	v_cvt_f32_u32_e32 v91, v91
	v_pk_fma_f32 v[26:27], v[66:67], v[26:27], v[30:31] op_sel_hi:[0,1,1]
	v_cmp_lt_i32_e32 vcc, v98, v118
	v_mul_f32_e32 v74, 0xbfb8aa3b, v74
	s_waitcnt lgkmcnt(0)
	v_mfma_f32_16x16x32_bf16 v[14:17], v[22:25], v[14:17], v[26:29]
	v_mul_f32_e32 v75, 0xbfb8aa3b, v75
	v_mul_f32_e32 v76, 0xbfb8aa3b, v76
	v_mul_f32_e32 v77, 0xbfb8aa3b, v77
	ds_read_b128 v[26:29], v130 offset:36928
	v_mul_f32_e32 v78, 0xbfb8aa3b, v78
	v_mul_f32_e32 v79, 0xbfb8aa3b, v79
	v_mul_f32_e32 v80, 0xbfb8aa3b, v80
	v_mul_f32_e32 v81, 0xbfb8aa3b, v81
	v_cndmask_b32_e32 v92, v96, v97, vcc
	v_exp_f32_e32 v74, v74
	v_exp_f32_e32 v75, v75
	v_exp_f32_e32 v76, v76
	v_exp_f32_e32 v77, v77
	v_exp_f32_e32 v78, v78
	v_exp_f32_e32 v79, v79
	v_exp_f32_e32 v80, v80
	v_exp_f32_e32 v81, v81
	v_mul_f32_e32 v91, v92, v91
	v_sub_u32_e32 v92, v98, v119
	v_sub_u32_e32 v93, 0, v92
	v_max_i32_e32 v92, v92, v93
	v_cvt_f32_u32_e32 v92, v92
	v_pk_mul_f32 v[54:55], v[74:75], v[54:55]
	v_pk_mul_f32 v[56:57], v[76:77], v[56:57]
	v_pk_mul_f32 v[50:51], v[78:79], v[50:51]
	v_pk_mul_f32 v[52:53], v[80:81], v[52:53]
	v_cmp_lt_i32_e32 vcc, v98, v119
	v_cvt_pk_bf16_f32 v22, v54, v55
	v_cvt_pk_bf16_f32 v23, v56, v57
	v_cvt_pk_bf16_f32 v24, v50, v51
	v_cvt_pk_bf16_f32 v25, v52, v53
	v_cndmask_b32_e32 v93, v96, v97, vcc
	v_mul_f32_e32 v92, v93, v92
	s_waitcnt lgkmcnt(0)
	v_mfma_f32_16x16x32_bf16 v[8:11], v[26:29], v[22:25], v[10:13]
	ds_read_b128 v[26:29], v130 offset:41280
	v_sub_u32_e32 v93, v98, v120
	v_sub_u32_e32 v94, 0, v93
	v_max_i32_e32 v93, v93, v94
	v_cvt_f32_u32_e32 v93, v93
	v_cmp_lt_i32_e32 vcc, v98, v120
	s_waitcnt lgkmcnt(0)
	v_mfma_f32_16x16x32_bf16 v[4:7], v[26:29], v[22:25], v[4:7]
	v_cndmask_b32_e32 v94, v96, v97, vcc
	v_mul_f32_e32 v93, v94, v93
	v_sub_u32_e32 v94, v98, v121
	v_sub_u32_e32 v95, 0, v94
	ds_read_b128 v[26:29], v130 offset:45632
	v_max_i32_e32 v94, v94, v95
	v_cvt_f32_u32_e32 v94, v94
	v_cmp_lt_i32_e32 vcc, v98, v121
	s_waitcnt lgkmcnt(0)
	v_mfma_f32_16x16x32_bf16 v[18:21], v[26:29], v[22:25], v[18:21]
	v_cndmask_b32_e32 v95, v96, v97, vcc
	v_mul_f32_e32 v94, v95, v94
	v_sub_u32_e32 v95, v98, v123
	v_sub_u32_e32 v100, 0, v95
	v_max_i32_e32 v95, v95, v100
	v_cvt_f32_u32_e32 v95, v95
	ds_read_b128 v[26:29], v130 offset:49984
	v_cmp_lt_i32_e32 vcc, v98, v123
	s_waitcnt lgkmcnt(0)
	v_mfma_f32_16x16x32_bf16 v[12:15], v[26:29], v[22:25], v[14:17]
	v_cndmask_b32_e32 v100, v96, v97, vcc
	v_mul_f32_e32 v95, v100, v95
	v_sub_u32_e32 v100, v98, v124
	v_sub_u32_e32 v101, 0, v100
	v_max_i32_e32 v100, v100, v101
	v_cvt_f32_u32_e32 v100, v100
	v_cmp_lt_i32_e32 vcc, v98, v124
	ds_read_b128 v[26:29], v130 offset:36992
	v_mul_f32_e32 v86, 0xbfb8aa3b, v86
	v_cndmask_b32_e32 v101, v96, v97, vcc
	v_mul_f32_e32 v87, 0xbfb8aa3b, v87
	v_mul_f32_e32 v88, 0xbfb8aa3b, v88
	v_mul_f32_e32 v89, 0xbfb8aa3b, v89
	v_mul_f32_e32 v90, 0xbfb8aa3b, v90
	v_mul_f32_e32 v91, 0xbfb8aa3b, v91
	v_mul_f32_e32 v92, 0xbfb8aa3b, v92
	v_mul_f32_e32 v93, 0xbfb8aa3b, v93
	v_mul_f32_e32 v100, v101, v100
	v_sub_u32_e32 v101, v98, v125
	v_exp_f32_e32 v86, v86
	v_exp_f32_e32 v87, v87
	v_exp_f32_e32 v88, v88
	v_exp_f32_e32 v89, v89
	v_exp_f32_e32 v90, v90
	v_exp_f32_e32 v91, v91
	v_exp_f32_e32 v92, v92
	v_exp_f32_e32 v93, v93
	v_sub_u32_e32 v102, 0, v101
	v_max_i32_e32 v101, v101, v102
	v_cvt_f32_u32_e32 v101, v101
	v_cmp_lt_i32_e32 vcc, v98, v125
	v_pk_mul_f32 v[46:47], v[86:87], v[46:47]
	v_pk_mul_f32 v[48:49], v[88:89], v[48:49]
	v_pk_mul_f32 v[42:43], v[90:91], v[42:43]
	v_pk_mul_f32 v[44:45], v[92:93], v[44:45]
	v_cndmask_b32_e32 v102, v96, v97, vcc
	v_cvt_pk_bf16_f32 v22, v46, v47
	v_cvt_pk_bf16_f32 v23, v48, v49
	v_cvt_pk_bf16_f32 v24, v42, v43
	v_cvt_pk_bf16_f32 v25, v44, v45
	v_mul_f32_e32 v101, v102, v101
	v_sub_u32_e32 v102, v98, v126
	s_waitcnt lgkmcnt(0)
	v_mfma_f32_16x16x32_bf16 v[8:11], v[26:29], v[22:25], v[8:11]
	ds_read_b128 v[26:29], v130 offset:41344
	v_sub_u32_e32 v103, 0, v102
	v_max_i32_e32 v102, v102, v103
	v_cvt_f32_u32_e32 v102, v102
	v_cmp_lt_i32_e32 vcc, v98, v126
	s_waitcnt lgkmcnt(0)
	v_mfma_f32_16x16x32_bf16 v[4:7], v[26:29], v[22:25], v[4:7]
	v_cndmask_b32_e32 v103, v96, v97, vcc
	v_mul_f32_e32 v102, v103, v102
	v_sub_u32_e32 v103, v98, v127
	v_sub_u32_e32 v104, 0, v103
	v_max_i32_e32 v103, v103, v104
	ds_read_b128 v[26:29], v130 offset:45696
	v_cvt_f32_u32_e32 v103, v103
	v_cmp_lt_i32_e32 vcc, v98, v127
	s_waitcnt lgkmcnt(0)
	v_mfma_f32_16x16x32_bf16 v[18:21], v[26:29], v[22:25], v[18:21]
	v_cndmask_b32_e32 v104, v96, v97, vcc
	v_mul_f32_e32 v103, v104, v103
	v_sub_u32_e32 v104, v98, v128
	v_sub_u32_e32 v105, 0, v104
	v_max_i32_e32 v104, v104, v105
	v_cvt_f32_u32_e32 v104, v104
	ds_read_b128 v[26:29], v130 offset:50048
	v_cmp_lt_i32_e32 vcc, v98, v128
	s_waitcnt lgkmcnt(0)
	v_mfma_f32_16x16x32_bf16 v[22:25], v[26:29], v[22:25], v[12:15]
	v_cndmask_b32_e32 v105, v96, v97, vcc
	v_mul_f32_e32 v104, v105, v104
	v_sub_u32_e32 v105, v98, v129
	v_sub_u32_e32 v106, 0, v105
	v_max_i32_e32 v105, v105, v106
	v_cvt_f32_u32_e32 v105, v105
	v_cmp_lt_i32_e32 vcc, v98, v129
	ds_read_b128 v[12:15], v130 offset:37056
	v_mul_f32_e32 v94, 0xbfb8aa3b, v94
	v_cndmask_b32_e32 v106, v96, v97, vcc
	v_mul_f32_e32 v105, v106, v105
	v_mul_f32_e32 v95, 0xbfb8aa3b, v95
	v_mul_f32_e32 v100, 0xbfb8aa3b, v100
	v_mul_f32_e32 v101, 0xbfb8aa3b, v101
	v_mul_f32_e32 v102, 0xbfb8aa3b, v102
	v_mul_f32_e32 v103, 0xbfb8aa3b, v103
	v_mul_f32_e32 v104, 0xbfb8aa3b, v104
	v_mul_f32_e32 v105, 0xbfb8aa3b, v105
	v_exp_f32_e32 v94, v94
	v_exp_f32_e32 v95, v95
	v_exp_f32_e32 v100, v100
	v_exp_f32_e32 v101, v101
	v_exp_f32_e32 v102, v102
	v_exp_f32_e32 v103, v103
	v_exp_f32_e32 v104, v104
	v_exp_f32_e32 v105, v105
	v_pk_mul_f32 v[38:39], v[94:95], v[38:39]
	v_pk_mul_f32 v[34:35], v[102:103], v[34:35]
	v_pk_mul_f32 v[40:41], v[100:101], v[40:41]
	v_pk_mul_f32 v[2:3], v[104:105], v[36:37]
	v_cvt_pk_bf16_f32 v26, v38, v39
	v_cvt_pk_bf16_f32 v27, v40, v41
	v_cvt_pk_bf16_f32 v28, v34, v35
	v_cvt_pk_bf16_f32 v29, v2, v3
	s_waitcnt lgkmcnt(0)
	s_nop 0
	v_mfma_f32_16x16x32_bf16 v[14:17], v[12:15], v[26:29], v[8:11]
	s_nop 2
	ds_read_b128 v[8:11], v130 offset:41408
	s_waitcnt lgkmcnt(0)
	v_mfma_f32_16x16x32_bf16 v[10:13], v[8:11], v[26:29], v[4:7]
	s_nop 2
	ds_read_b128 v[2:5], v130 offset:45760
	s_waitcnt lgkmcnt(0)
	v_mfma_f32_16x16x32_bf16 v[6:9], v[2:5], v[26:29], v[18:21]
	ds_read_b128 v[2:5], v130 offset:50112
	s_nop 6
	v_pk_mul_f32 v[20:21], v[6:7], v[6:7]
	s_waitcnt lgkmcnt(0)
	v_mfma_f32_16x16x32_bf16 v[2:5], v[2:5], v[26:29], v[22:25]
	s_nop 2
	v_mul_f32_e32 v22, v15, v15
	v_fmac_f32_e32 v22, v14, v14
	v_fmac_f32_e32 v22, v16, v16
	v_fmac_f32_e32 v22, v17, v17
	v_fmac_f32_e32 v22, v10, v10
	v_fmac_f32_e32 v22, v11, v11
	v_fmac_f32_e32 v22, v12, v12
	v_fmac_f32_e32 v22, v13, v13
	v_add_f32_e32 v20, v20, v22
	v_pk_mul_f32 v[18:19], v[8:9], v[8:9]
	v_add_f32_e32 v20, v21, v20
	v_add_f32_e32 v18, v18, v20
	v_add_f32_e32 v22, v19, v18
	v_pk_mul_f32 v[20:21], v[2:3], v[2:3]
	v_pk_mul_f32 v[18:19], v[4:5], v[4:5]
	v_add_f32_e32 v20, v20, v22
	v_add_f32_e32 v20, v21, v20
	v_add_f32_e32 v18, v18, v20
	v_mad_i64_i32 v[20:21], s[6:7], v98, s52, v[82:83]
	v_lshl_add_u64 v[20:21], v[20:21], 0, v[84:85]
	v_lshl_add_u64 v[20:21], v[20:21], 0, v[0:1]
	global_load_dwordx2 v[22:23], v[20:21], off offset:1536
	global_load_dwordx2 v[214:215], v[20:21], off offset:1568
	global_load_dwordx2 v[216:217], v[20:21], off offset:1600
	global_load_dwordx2 v[218:219], v[20:21], off offset:1632
	v_add_f32_e32 v18, v19, v18
	ds_bpermute_b32 v19, v131, v18
	s_waitcnt lgkmcnt(0)
	v_add_f32_e32 v18, v18, v19
	ds_bpermute_b32 v19, v132, v18
	s_waitcnt lgkmcnt(0)
	v_add_f32_e32 v18, v18, v19
	v_fmamk_f32 v18, v18, 0x3c800000, v158
	v_cmp_gt_f32_e32 vcc, s66, v18
	v_mul_f32_e32 v19, 0x4b800000, v18
	s_waitcnt vmcnt(0)
	v_lshlrev_b32_e32 v24, 16, v22
	v_mul_f32_e32 v0, 0xbfb8aa3b, v24
	v_exp_f32_e32 v0, v0
	v_and_b32_e32 v25, 0xffff0000, v22
	v_cndmask_b32_e32 v18, v18, v19, vcc
	v_rsq_f32_e32 v18, v18
	v_add_f32_e32 v0, 1.0, v0
	v_rcp_f32_e32 v26, v0
	v_mul_f32_e32 v0, 0xbfb8aa3b, v25
	v_exp_f32_e32 v0, v0
	v_lshlrev_b32_e32 v22, 16, v23
	v_mul_f32_e32 v19, 0x45800000, v18
	v_cndmask_b32_e32 v18, v18, v19, vcc
	v_add_f32_e32 v0, 1.0, v0
	v_rcp_f32_e32 v27, v0
	v_mul_f32_e32 v0, 0xbfb8aa3b, v22
	v_exp_f32_e32 v0, v0
	v_and_b32_e32 v23, 0xffff0000, v23
	v_pk_mul_f32 v[24:25], v[26:27], v[24:25]
	v_add_f32_e32 v0, 1.0, v0
	v_pk_mul_f32 v[24:25], v[24:25], v[18:19] op_sel_hi:[1,0]
	s_nop 0
	v_pk_mul_f32 v[14:15], v[14:15], v[24:25]
	v_rcp_f32_e32 v24, v0
	v_mul_f32_e32 v0, 0xbfb8aa3b, v23
	v_exp_f32_e32 v0, v0
	v_cvt_pk_bf16_f32 v14, v14, v15
	v_add_f32_e32 v0, 1.0, v0
	v_rcp_f32_e32 v25, v0
	s_nop 0
	v_pk_mul_f32 v[22:23], v[24:25], v[22:23]
	s_nop 0
	v_pk_mul_f32 v[22:23], v[22:23], v[18:19] op_sel_hi:[1,0]
	s_nop 0
	v_pk_mul_f32 v[16:17], v[16:17], v[22:23]
	s_nop 0
	v_cvt_pk_bf16_f32 v15, v16, v17
	global_store_dwordx2 v[20:21], v[14:15], off offset:1536
	s_nop 0
	s_nop 0
	v_lshlrev_b32_e32 v16, 16, v214
	v_mul_f32_e32 v0, 0xbfb8aa3b, v16
	v_exp_f32_e32 v0, v0
	v_and_b32_e32 v17, 0xffff0000, v214
	v_lshlrev_b32_e32 v14, 16, v215
	v_and_b32_e32 v15, 0xffff0000, v215
	v_add_f32_e32 v0, 1.0, v0
	v_rcp_f32_e32 v22, v0
	v_mul_f32_e32 v0, 0xbfb8aa3b, v17
	v_exp_f32_e32 v0, v0
	s_nop 0
	v_add_f32_e32 v0, 1.0, v0
	v_rcp_f32_e32 v23, v0
	v_mul_f32_e32 v0, 0xbfb8aa3b, v14
	v_exp_f32_e32 v0, v0
	v_pk_mul_f32 v[16:17], v[22:23], v[16:17]
	s_nop 0
	v_pk_mul_f32 v[16:17], v[16:17], v[18:19] op_sel_hi:[1,0]
	v_add_f32_e32 v0, 1.0, v0
	v_pk_mul_f32 v[10:11], v[10:11], v[16:17]
	v_rcp_f32_e32 v16, v0
	v_mul_f32_e32 v0, 0xbfb8aa3b, v15
	v_exp_f32_e32 v0, v0
	v_cvt_pk_bf16_f32 v10, v10, v11
	v_add_f32_e32 v0, 1.0, v0
	v_rcp_f32_e32 v17, v0
	s_nop 0
	v_pk_mul_f32 v[14:15], v[16:17], v[14:15]
	s_nop 0
	v_pk_mul_f32 v[14:15], v[14:15], v[18:19] op_sel_hi:[1,0]
	s_nop 0
	v_pk_mul_f32 v[12:13], v[12:13], v[14:15]
	s_nop 0
	v_cvt_pk_bf16_f32 v11, v12, v13
	global_store_dwordx2 v[20:21], v[10:11], off offset:1568
	s_nop 0
	s_nop 0
	v_lshlrev_b32_e32 v12, 16, v216
	v_mul_f32_e32 v0, 0xbfb8aa3b, v12
	v_exp_f32_e32 v0, v0
	v_and_b32_e32 v13, 0xffff0000, v216
	v_lshlrev_b32_e32 v10, 16, v217
	v_and_b32_e32 v11, 0xffff0000, v217
	v_add_f32_e32 v0, 1.0, v0
	v_rcp_f32_e32 v14, v0
	v_mul_f32_e32 v0, 0xbfb8aa3b, v13
	v_exp_f32_e32 v0, v0
	s_nop 0
	v_add_f32_e32 v0, 1.0, v0
	v_rcp_f32_e32 v15, v0
	v_mul_f32_e32 v0, 0xbfb8aa3b, v10
	v_exp_f32_e32 v0, v0
	v_pk_mul_f32 v[12:13], v[14:15], v[12:13]
	s_nop 0
	v_pk_mul_f32 v[12:13], v[12:13], v[18:19] op_sel_hi:[1,0]
	v_add_f32_e32 v0, 1.0, v0
	v_pk_mul_f32 v[6:7], v[6:7], v[12:13]
	v_rcp_f32_e32 v12, v0
	v_mul_f32_e32 v0, 0xbfb8aa3b, v11
	v_exp_f32_e32 v0, v0
	v_cvt_pk_bf16_f32 v6, v6, v7
	v_add_f32_e32 v0, 1.0, v0
	v_rcp_f32_e32 v13, v0
	s_nop 0
	v_pk_mul_f32 v[10:11], v[12:13], v[10:11]
	s_nop 0
	v_pk_mul_f32 v[10:11], v[10:11], v[18:19] op_sel_hi:[1,0]
	s_nop 0
	v_pk_mul_f32 v[8:9], v[8:9], v[10:11]
	s_nop 0
	v_cvt_pk_bf16_f32 v7, v8, v9
	global_store_dwordx2 v[20:21], v[6:7], off offset:1600
	s_nop 0
	s_nop 0
	v_lshlrev_b32_e32 v8, 16, v218
	v_mul_f32_e32 v0, 0xbfb8aa3b, v8
	v_exp_f32_e32 v0, v0
	v_and_b32_e32 v9, 0xffff0000, v218
	v_lshlrev_b32_e32 v6, 16, v219
	v_and_b32_e32 v7, 0xffff0000, v219
	v_add_f32_e32 v0, 1.0, v0
	v_rcp_f32_e32 v10, v0
	v_mul_f32_e32 v0, 0xbfb8aa3b, v9
	v_exp_f32_e32 v0, v0
	s_nop 0
	v_add_f32_e32 v0, 1.0, v0
	v_rcp_f32_e32 v11, v0
	v_mul_f32_e32 v0, 0xbfb8aa3b, v6
	v_exp_f32_e32 v0, v0
	v_pk_mul_f32 v[8:9], v[10:11], v[8:9]
	s_nop 0
	v_pk_mul_f32 v[8:9], v[18:19], v[8:9] op_sel_hi:[0,1]
	v_add_f32_e32 v0, 1.0, v0
	v_pk_mul_f32 v[2:3], v[2:3], v[8:9]
	v_rcp_f32_e32 v8, v0
	v_mul_f32_e32 v0, 0xbfb8aa3b, v7
	v_exp_f32_e32 v0, v0
	v_cvt_pk_bf16_f32 v2, v2, v3
	v_add_f32_e32 v0, 1.0, v0
	v_rcp_f32_e32 v9, v0
	s_nop 0
	v_pk_mul_f32 v[6:7], v[8:9], v[6:7]
	s_nop 0
	v_pk_mul_f32 v[6:7], v[18:19], v[6:7] op_sel_hi:[0,1]
	v_pk_mul_f32 v[4:5], v[4:5], v[6:7]
	s_nop 0
	v_cvt_pk_bf16_f32 v3, v4, v5
	global_store_dwordx2 v[20:21], v[2:3], off offset:1632

.LBB0_1939:
	s_andn2_saveexec_b64 s[2:3], s[2:3]
	s_cbranch_execz .LBB0_1941
	v_add_u32_e32 v3, 0xfffff0dc, v2
	v_lshlrev_b32_e32 v0, 5, v3
	v_and_b32_e32 v0, 0x1ff80, v0
	v_mul_u32_u24_e32 v0, 0xea0, v0
	v_lshlrev_b32_e32 v0, 1, v0
	s_mov_b64 s[52:53], s[76:77]
	v_and_b32_e32 v2, 3, v2
	v_lshl_add_u64 v[82:83], s[16:17], 0, v[0:1]
	v_lshlrev_b32_e32 v0, 13, v3
	v_mbcnt_lo_u32_b32 v3, -1, 0
	v_mbcnt_hi_u32_b32 v3, -1, v3
	s_mov_b64 s[54:55], s[78:79]
	s_mov_b64 s[58:59], s[82:83]
	s_mov_b64 s[60:61], s[84:85]
	v_readlane_b32 s72, v236, 24
	v_or_b32_e32 v50, s10, v3
	v_lshlrev_b32_e32 v3, 2, v2
	v_readlane_b32 s73, v236, 25
	s_mov_b32 s4, 0xbfb8aa3b
	v_readlane_b32 s74, v236, 26
	v_readlane_b32 s75, v236, 27
	s_mov_b32 s5, 0x42ce8ed0
	s_nop 0
	global_load_dword v4, v3, s[72:73] offset:16
	v_ashrrev_i32_e32 v21, 3, v50
	v_lshlrev_b32_e32 v84, 7, v2
	v_mov_b32_e32 v85, v1
	global_load_dword v3, v3, s[74:75] offset:16
	s_waitcnt lgkmcnt(0)
	s_barrier
	v_lshlrev_b32_e32 v20, 3, v50
	v_and_b32_e32 v93, 15, v50
	v_and_b32_e32 v51, 63, v50
	v_ashrrev_i32_e32 v48, 2, v50
	v_bfi_b32 v99, -16, v48, v50
	s_mov_b32 s8, 0x800000
	v_add_u32_e32 v98, 64, v99
	v_readlane_b32 s76, v236, 28
	v_readlane_b32 s77, v236, 29
	v_readlane_b32 s78, v236, 30
	v_readlane_b32 s79, v236, 31
	v_readlane_b32 s82, v236, 34
	v_readlane_b32 s83, v236, 35
	v_readlane_b32 s84, v236, 36
	v_readlane_b32 s85, v236, 37
	s_mov_b64 s[78:79], s[54:55]
	s_mov_b64 s[76:77], s[52:53]
	s_mov_b64 s[82:83], s[58:59]
	s_mov_b64 s[84:85], s[60:61]
	s_movk_i32 s52, 0x48
	v_readlane_b32 s80, v236, 32
	v_readlane_b32 s81, v236, 33
	v_readlane_b32 s86, v236, 38
	v_readlane_b32 s87, v236, 39
	s_waitcnt vmcnt(0)
	v_mul_f32_e32 v5, 0xbfb8aa3b, v4
	v_fma_f32 v6, v4, s4, -v5
	v_rndne_f32_e32 v7, v5
	v_fmac_f32_e32 v6, 0xb2a5705f, v4
	v_sub_f32_e32 v5, v5, v7
	v_add_f32_e32 v5, v5, v6
	v_exp_f32_e32 v5, v5
	v_cvt_i32_f32_e32 v6, v7
	v_cmp_nlt_f32_e32 vcc, s5, v4
	v_ldexp_f32 v5, v5, v6
	s_nop 0
	v_cndmask_b32_e32 v5, 0, v5, vcc
	v_cmp_ngt_f32_e32 vcc, s71, v4
	s_nop 1
	v_cndmask_b32_e32 v18, v160, v5, vcc
	v_add_f32_e32 v6, 1.0, v18
	v_add_f32_e32 v4, -1.0, v6
	v_sub_f32_e32 v5, v4, v6
	v_add_f32_e32 v5, 1.0, v5
	v_sub_f32_e32 v4, v18, v4
	v_add_f32_e32 v7, v4, v5
	v_frexp_mant_f32_e32 v4, v6
	v_cmp_gt_f32_e32 vcc, s21, v4
	v_cvt_f64_f32_e32 v[4:5], v6
	v_frexp_exp_i32_f64_e32 v4, v[4:5]
	v_subbrev_co_u32_e32 v12, vcc, 0, v4, vcc
	v_sub_u32_e32 v4, 0, v12
	v_ldexp_f32 v5, v6, v4
	v_add_f32_e32 v6, -1.0, v5
	v_add_f32_e32 v8, 1.0, v5
	v_ldexp_f32 v4, v7, v4
	v_add_f32_e32 v7, 1.0, v6
	v_add_f32_e32 v9, -1.0, v8
	v_sub_f32_e32 v7, v5, v7
	v_sub_f32_e32 v5, v5, v9
	v_add_f32_e32 v7, v4, v7
	v_add_f32_e32 v4, v4, v5
	v_add_f32_e32 v13, v8, v4
	v_rcp_f32_e32 v15, v13
	v_sub_f32_e32 v5, v8, v13
	v_add_f32_e32 v14, v4, v5
	v_add_f32_e32 v5, v6, v7
	v_mul_f32_e32 v17, v5, v15
	v_sub_f32_e32 v4, v6, v5
	v_mul_f32_e32 v6, v13, v17
	v_fma_f32 v8, v17, v13, -v6
	v_fmac_f32_e32 v8, v17, v14
	v_add_f32_e32 v16, v7, v4
	v_add_f32_e32 v4, v6, v8
	v_sub_f32_e32 v7, v5, v4
	v_pk_add_f32 v[10:11], v[4:5], v[6:7] neg_lo:[0,1] neg_hi:[0,1]
	v_mov_b32_e32 v9, v4
	v_pk_add_f32 v[4:5], v[10:11], v[8:9] neg_lo:[0,1] neg_hi:[0,1]
	v_cmp_neq_f32_e32 vcc, s93, v18
	v_add_f32_e32 v5, v16, v5
	v_add_f32_e32 v4, v4, v5
	v_add_f32_e32 v5, v7, v4
	v_mul_f32_e32 v16, v15, v5
	v_mul_f32_e32 v6, v13, v16
	v_fma_f32 v8, v16, v13, -v6
	v_fmac_f32_e32 v8, v16, v14
	v_sub_f32_e32 v7, v7, v5
	v_add_f32_e32 v13, v4, v7
	v_add_f32_e32 v4, v6, v8
	v_sub_f32_e32 v7, v5, v4
	v_pk_add_f32 v[10:11], v[4:5], v[6:7] neg_lo:[0,1] neg_hi:[0,1]
	v_mov_b32_e32 v9, v4
	v_pk_add_f32 v[4:5], v[10:11], v[8:9] neg_lo:[0,1] neg_hi:[0,1]
	s_nop 0
	v_add_f32_e32 v5, v13, v5
	v_add_f32_e32 v4, v4, v5
	v_add_f32_e32 v5, v17, v16
	v_add_f32_e32 v4, v7, v4
	v_sub_f32_e32 v6, v5, v17
	v_mul_f32_e32 v4, v15, v4
	v_sub_f32_e32 v6, v16, v6
	v_add_f32_e32 v6, v6, v4
	v_add_f32_e32 v8, v5, v6
	v_mul_f32_e32 v9, v8, v8
	v_fmamk_f32 v4, v9, 0x3e9b6dac, v157
	v_fmaak_f32 v123, v9, v4, 0x3f2aaada
	v_cvt_f32_i32_e32 v4, v12
	v_sub_f32_e32 v5, v8, v5
	v_sub_f32_e32 v5, v6, v5
	v_ldexp_f32 v10, v5, 1
	v_mul_f32_e32 v5, v8, v9
	v_ldexp_f32 v7, v8, 1
	v_pk_mul_f32 v[8:9], v[4:5], v[122:123]
	s_nop 0
	v_fma_f32 v6, v4, s56, -v8
	v_fmac_f32_e32 v6, 0xb102e308, v4
	v_pk_add_f32 v[4:5], v[8:9], v[6:7]
	s_nop 0
	v_sub_f32_e32 v7, v5, v7
	v_sub_f32_e32 v7, v9, v7
	v_add_f32_e32 v11, v10, v7
	v_mov_b32_e32 v10, v8
	v_pk_add_f32 v[8:9], v[4:5], v[8:9] neg_lo:[0,1] neg_hi:[0,1]
	v_pk_add_f32 v[12:13], v[4:5], v[10:11]
	v_mov_b32_e32 v7, v4
	v_mov_b32_e32 v9, v13
	v_pk_add_f32 v[14:15], v[6:7], v[8:9] neg_lo:[0,1] neg_hi:[0,1]
	v_pk_add_f32 v[6:7], v[6:7], v[8:9]
	v_mov_b32_e32 v10, v11
	v_pk_add_f32 v[8:9], v[6:7], v[4:5] op_sel:[1,0] op_sel_hi:[0,1] neg_lo:[0,1] neg_hi:[0,1]
	v_pk_add_f32 v[16:17], v[12:13], v[8:9] op_sel_hi:[1,0] neg_lo:[0,1] neg_hi:[0,1]
	v_mov_b32_e32 v12, v13
	v_mov_b32_e32 v13, v7
	v_pk_mov_b32 v[8:9], v[4:5], v[8:9] op_sel:[1,0]
	v_mov_b32_e32 v11, v4
	v_pk_add_f32 v[8:9], v[12:13], v[8:9] neg_lo:[0,1] neg_hi:[0,1]
	v_mov_b32_e32 v16, v14
	v_pk_add_f32 v[4:5], v[10:11], v[8:9] neg_lo:[0,1] neg_hi:[0,1]
	v_mov_b32_e32 v15, v7
	v_pk_add_f32 v[8:9], v[16:17], v[4:5]
	s_nop 0
	v_pk_add_f32 v[10:11], v[8:9], v[8:9] op_sel:[0,1] op_sel_hi:[1,0]
	s_nop 0
	v_pk_add_f32 v[6:7], v[6:7], v[10:11] op_sel:[1,0] op_sel_hi:[0,1]
	v_mov_b32_e32 v9, v6
	v_pk_add_f32 v[12:13], v[8:9], v[14:15] neg_lo:[0,1] neg_hi:[0,1]
	v_mov_b32_e32 v5, v10
	v_sub_f32_e32 v7, v8, v12
	v_pk_add_f32 v[4:5], v[4:5], v[12:13] neg_lo:[0,1] neg_hi:[0,1]
	v_sub_f32_e32 v7, v14, v7
	v_add_f32_e32 v4, v4, v7
	v_add_f32_e32 v4, v4, v5
	v_add_f32_e32 v4, v6, v4
	v_cndmask_b32_e32 v4, v160, v4, vcc
	v_cmp_lt_f32_e64 vcc, |v18|, s96
	s_nop 1
	v_cndmask_b32_e32 v96, v4, v18, vcc
	v_mul_f32_e32 v4, 0xbfb8aa3b, v3
	v_fma_f32 v5, v3, s4, -v4
	v_rndne_f32_e32 v6, v4
	v_fmac_f32_e32 v5, 0xb2a5705f, v3
	v_sub_f32_e32 v4, v4, v6
	v_add_f32_e32 v4, v4, v5
	v_exp_f32_e32 v4, v4
	v_cvt_i32_f32_e32 v5, v6
	v_cmp_nlt_f32_e32 vcc, s5, v3
	v_ldexp_f32 v4, v4, v5
	s_nop 0
	v_cndmask_b32_e32 v4, 0, v4, vcc
	v_cmp_ngt_f32_e32 vcc, s71, v3
	s_nop 1
	v_cndmask_b32_e32 v3, v160, v4, vcc
	v_add_f32_e32 v6, 1.0, v3
	v_add_f32_e32 v4, -1.0, v6
	v_sub_f32_e32 v5, v4, v6
	v_add_f32_e32 v5, 1.0, v5
	v_sub_f32_e32 v4, v3, v4
	v_add_f32_e32 v7, v4, v5
	v_frexp_mant_f32_e32 v4, v6
	v_cmp_gt_f32_e32 vcc, s21, v4
	v_cvt_f64_f32_e32 v[4:5], v6
	v_frexp_exp_i32_f64_e32 v4, v[4:5]
	v_subbrev_co_u32_e32 v12, vcc, 0, v4, vcc
	v_sub_u32_e32 v4, 0, v12
	v_ldexp_f32 v5, v6, v4
	v_add_f32_e32 v6, -1.0, v5
	v_add_f32_e32 v8, 1.0, v5
	v_ldexp_f32 v4, v7, v4
	v_add_f32_e32 v7, 1.0, v6
	v_add_f32_e32 v9, -1.0, v8
	v_sub_f32_e32 v7, v5, v7
	v_sub_f32_e32 v5, v5, v9
	v_add_f32_e32 v7, v4, v7
	v_add_f32_e32 v4, v4, v5
	v_add_f32_e32 v13, v8, v4
	v_rcp_f32_e32 v15, v13
	v_sub_f32_e32 v5, v8, v13
	v_add_f32_e32 v14, v4, v5
	v_add_f32_e32 v5, v6, v7
	v_mul_f32_e32 v17, v5, v15
	v_sub_f32_e32 v4, v6, v5
	v_mul_f32_e32 v6, v13, v17
	v_fma_f32 v8, v17, v13, -v6
	v_fmac_f32_e32 v8, v17, v14
	v_add_f32_e32 v16, v7, v4
	v_add_f32_e32 v4, v6, v8
	v_sub_f32_e32 v7, v5, v4
	v_pk_add_f32 v[10:11], v[4:5], v[6:7] neg_lo:[0,1] neg_hi:[0,1]
	v_mov_b32_e32 v9, v4
	v_pk_add_f32 v[4:5], v[10:11], v[8:9] neg_lo:[0,1] neg_hi:[0,1]
	v_cmp_neq_f32_e32 vcc, s93, v3
	v_add_f32_e32 v5, v16, v5
	v_add_f32_e32 v4, v4, v5
	v_add_f32_e32 v5, v7, v4
	v_mul_f32_e32 v16, v15, v5
	v_mul_f32_e32 v6, v13, v16
	v_fma_f32 v8, v16, v13, -v6
	v_fmac_f32_e32 v8, v16, v14
	v_sub_f32_e32 v7, v7, v5
	v_add_f32_e32 v13, v4, v7
	v_add_f32_e32 v4, v6, v8
	v_sub_f32_e32 v7, v5, v4
	v_pk_add_f32 v[10:11], v[4:5], v[6:7] neg_lo:[0,1] neg_hi:[0,1]
	v_mov_b32_e32 v9, v4
	v_pk_add_f32 v[4:5], v[10:11], v[8:9] neg_lo:[0,1] neg_hi:[0,1]
	s_nop 0
	v_add_f32_e32 v5, v13, v5
	v_add_f32_e32 v4, v4, v5
	v_add_f32_e32 v5, v17, v16
	v_add_f32_e32 v4, v7, v4
	v_sub_f32_e32 v6, v5, v17
	v_mul_f32_e32 v4, v15, v4
	v_sub_f32_e32 v6, v16, v6
	v_add_f32_e32 v6, v6, v4
	v_add_f32_e32 v8, v5, v6
	v_mul_f32_e32 v9, v8, v8
	v_fmamk_f32 v4, v9, 0x3e9b6dac, v157
	v_fmaak_f32 v123, v9, v4, 0x3f2aaada
	v_cvt_f32_i32_e32 v4, v12
	v_sub_f32_e32 v5, v8, v5
	v_sub_f32_e32 v5, v6, v5
	v_ldexp_f32 v10, v5, 1
	v_mul_f32_e32 v5, v8, v9
	v_ldexp_f32 v7, v8, 1
	v_pk_mul_f32 v[8:9], v[4:5], v[122:123]
	s_nop 0
	v_fma_f32 v6, v4, s56, -v8
	v_fmac_f32_e32 v6, 0xb102e308, v4
	v_pk_add_f32 v[4:5], v[8:9], v[6:7]
	s_nop 0
	v_sub_f32_e32 v7, v5, v7
	v_sub_f32_e32 v7, v9, v7
	v_add_f32_e32 v11, v10, v7
	v_mov_b32_e32 v10, v8
	v_pk_add_f32 v[8:9], v[4:5], v[8:9] neg_lo:[0,1] neg_hi:[0,1]
	v_pk_add_f32 v[12:13], v[4:5], v[10:11]
	v_mov_b32_e32 v7, v4
	v_mov_b32_e32 v9, v13
	v_pk_add_f32 v[14:15], v[6:7], v[8:9] neg_lo:[0,1] neg_hi:[0,1]
	v_pk_add_f32 v[6:7], v[6:7], v[8:9]
	v_mov_b32_e32 v10, v11
	v_pk_add_f32 v[8:9], v[6:7], v[4:5] op_sel:[1,0] op_sel_hi:[0,1] neg_lo:[0,1] neg_hi:[0,1]
	v_pk_add_f32 v[16:17], v[12:13], v[8:9] op_sel_hi:[1,0] neg_lo:[0,1] neg_hi:[0,1]
	v_mov_b32_e32 v12, v13
	v_mov_b32_e32 v13, v7
	v_pk_mov_b32 v[8:9], v[4:5], v[8:9] op_sel:[1,0]
	v_mov_b32_e32 v11, v4
	v_pk_add_f32 v[8:9], v[12:13], v[8:9] neg_lo:[0,1] neg_hi:[0,1]
	v_mov_b32_e32 v16, v14
	v_pk_add_f32 v[4:5], v[10:11], v[8:9] neg_lo:[0,1] neg_hi:[0,1]
	v_mov_b32_e32 v15, v7
	v_pk_add_f32 v[8:9], v[16:17], v[4:5]
	s_nop 0
	v_pk_add_f32 v[10:11], v[8:9], v[8:9] op_sel:[0,1] op_sel_hi:[1,0]
	s_nop 0
	v_pk_add_f32 v[6:7], v[6:7], v[10:11] op_sel:[1,0] op_sel_hi:[0,1]
	v_mov_b32_e32 v9, v6
	v_pk_add_f32 v[12:13], v[8:9], v[14:15] neg_lo:[0,1] neg_hi:[0,1]
	v_mov_b32_e32 v5, v10
	v_sub_f32_e32 v7, v8, v12
	v_pk_add_f32 v[4:5], v[4:5], v[12:13] neg_lo:[0,1] neg_hi:[0,1]
	v_sub_f32_e32 v7, v14, v7
	v_add_f32_e32 v4, v4, v7
	v_add_f32_e32 v4, v4, v5
	v_add_f32_e32 v4, v6, v4
	v_cndmask_b32_e32 v4, v160, v4, vcc
	v_cmp_lt_f32_e64 vcc, |v3|, s96
	v_mov_b32_e32 v11, v1
	s_nop 0
	v_cndmask_b32_e32 v97, v4, v3, vcc
	v_lshlrev_b32_e32 v3, 4, v50
	v_mad_i64_i32 v[4:5], s[4:5], v21, s33, v[82:83]
	v_and_b32_e32 v10, 0x70, v3
	v_lshl_add_u64 v[2:3], v[4:5], 0, v[84:85]
	v_lshl_add_u64 v[6:7], v[2:3], 0, v[10:11]
	global_load_dwordx4 v[172:175], v[6:7], off
	v_add_u32_e32 v12, s92, v10
	v_mad_u64_u32 v[8:9], s[4:5], v21, s97, v[12:13]
	s_nop 0
	v_mov_b32_e32 v206, v8
	global_load_dwordx4 v[176:179], v[6:7], off offset:512
	s_nop 0
	v_mov_b32_e32 v207, v8
	v_add_u32_e32 v8, 0x100, v50
	v_ashrrev_i32_e32 v9, 3, v8
	v_mad_i64_i32 v[2:3], s[4:5], v9, s33, v[82:83]
	v_lshl_add_u64 v[2:3], v[2:3], 0, v[84:85]
	v_lshl_add_u64 v[6:7], v[2:3], 0, v[10:11]
	global_load_dwordx4 v[180:183], v[6:7], off
	v_mad_u64_u32 v[14:15], s[4:5], v9, s97, v[12:13]
	s_nop 0
	v_mov_b32_e32 v208, v14
	global_load_dwordx4 v[184:187], v[6:7], off offset:512
	v_add_u32_e32 v7, 0x200, v50
	v_add_u32_e32 v6, 0x300, v50
	s_nop 0
	v_mov_b32_e32 v209, v14
	v_ashrrev_i32_e32 v4, 3, v7
	v_mad_i64_i32 v[2:3], s[4:5], v4, s33, v[82:83]
	v_lshl_add_u64 v[2:3], v[2:3], 0, v[84:85]
	v_lshl_add_u64 v[14:15], v[2:3], 0, v[10:11]
	v_mad_u64_u32 v[16:17], s[4:5], v4, s97, v[12:13]
	global_load_dwordx4 v[188:191], v[14:15], off
	v_ashrrev_i32_e32 v7, 4, v7
	s_nop 0
	v_mov_b32_e32 v210, v16
	global_load_dwordx4 v[192:195], v[14:15], off offset:512
	s_nop 0
	v_mov_b32_e32 v211, v16
	v_ashrrev_i32_e32 v4, 3, v6
	v_mad_i64_i32 v[2:3], s[4:5], v4, s33, v[82:83]
	v_lshl_add_u64 v[2:3], v[2:3], 0, v[84:85]
	v_lshl_add_u64 v[10:11], v[2:3], 0, v[10:11]
	v_mad_u64_u32 v[12:13], s[4:5], v4, s97, v[12:13]
	global_load_dwordx4 v[196:199], v[10:11], off
	s_mov_b64 s[4:5], 0x2140
	s_nop 0
	v_mov_b32_e32 v212, v12
	global_load_dwordx4 v[200:203], v[10:11], off offset:512
	v_and_b32_e32 v10, 48, v20
	v_and_b32_e32 v20, -8, v21
	v_ashrrev_i32_e32 v21, 31, v20
	v_and_b32_e32 v11, 8, v50
	v_lshlrev_b64 v[14:15], 1, v[20:21]
	s_waitcnt vmcnt(0) lgkmcnt(0)
	ds_write_b128 v206, v[172:175]
	ds_write_b128 v207, v[176:179] offset:18432
	ds_write_b128 v208, v[180:183]
	ds_write_b128 v209, v[184:187] offset:18432
	ds_write_b128 v210, v[188:191]
	ds_write_b128 v211, v[192:195] offset:18432
	ds_write_b128 v212, v[196:199]
	ds_write_b128 v12, v[200:203] offset:18432
	v_lshlrev_b32_e32 v2, 1, v50
	v_and_b32_e32 v2, 0x7e, v2
	v_mul_u32_u24_e32 v2, 0xea0, v2
	v_lshlrev_b32_e32 v2, 1, v2
	v_mov_b32_e32 v3, v1
	v_lshlrev_b32_e32 v5, 2, v50
	v_lshl_add_u64 v[2:3], v[82:83], 0, v[2:3]
	v_and_b32_e32 v4, 0xc4, v5
	v_lshl_add_u64 v[18:19], v[2:3], 0, v[84:85]
	v_add_u32_e32 v4, s92, v4
	v_lshl_add_u64 v[2:3], v[18:19], 0, s[4:5]
	v_add3_u32 v4, v4, v10, v11
	v_lshl_add_u64 v[10:11], v[18:19], 0, v[14:15]
	global_load_dwordx4 v[10:13], v[10:11], off offset:1024
	v_lshl_add_u64 v[14:15], v[2:3], 0, v[14:15]
	global_load_dwordx4 v[14:17], v[14:15], off
	s_waitcnt vmcnt(0) lgkmcnt(0)
	v_and_b32_e32 v21, 0xffff, v10
	v_lshrrev_b32_e32 v10, 16, v10
	v_lshl_or_b32 v22, v14, 16, v21
	v_mad_u64_u32 v[20:21], s[4:5], v20, s19, v[4:5]
	v_and_or_b32 v10, v14, s57, v10
	v_add_u32_e32 v14, 0x9000, v20
	ds_write2_b32 v14, v22, v10 offset1:68
	v_and_b32_e32 v10, 0xffff, v11
	v_lshrrev_b32_e32 v11, 16, v11
	v_lshl_or_b32 v10, v15, 16, v10
	v_and_or_b32 v11, v15, s57, v11
	ds_write2_b32 v14, v10, v11 offset0:136 offset1:204
	v_and_b32_e32 v10, 0xffff, v12
	v_lshrrev_b32_e32 v11, 16, v12
	v_lshl_or_b32 v10, v16, 16, v10
	v_and_or_b32 v11, v16, s57, v11
	v_add_u32_e32 v12, 0x9400, v20
	v_and_b32_e32 v20, -8, v9
	ds_write2_b32 v12, v10, v11 offset0:16 offset1:84
	v_and_b32_e32 v10, 0xffff, v13
	v_lshrrev_b32_e32 v11, 16, v13
	v_ashrrev_i32_e32 v21, 31, v20
	v_lshl_or_b32 v10, v17, 16, v10
	v_and_or_b32 v11, v17, s57, v11
	v_lshlrev_b64 v[14:15], 1, v[20:21]
	ds_write2_b32 v12, v10, v11 offset0:152 offset1:220
	v_lshl_add_u64 v[10:11], v[18:19], 0, v[14:15]
	global_load_dwordx4 v[10:13], v[10:11], off offset:1024
	v_lshl_add_u64 v[2:3], v[2:3], 0, v[14:15]
	global_load_dwordx4 v[14:17], v[2:3], off
	s_waitcnt vmcnt(0) lgkmcnt(0)
	v_and_b32_e32 v2, 0xffff, v10
	v_lshl_or_b32 v9, v14, 16, v2
	v_mad_u64_u32 v[2:3], s[4:5], v20, s19, v[4:5]
	v_lshrrev_b32_e32 v3, 16, v10
	v_and_or_b32 v3, v14, s57, v3
	v_add_u32_e32 v4, 0x9000, v2
	ds_write2_b32 v4, v9, v3 offset1:68
	v_and_b32_e32 v3, 0xffff, v11
	v_lshrrev_b32_e32 v9, 16, v11
	v_lshl_or_b32 v3, v15, 16, v3
	v_and_or_b32 v9, v15, s57, v9
	ds_write2_b32 v4, v3, v9 offset0:136 offset1:204
	v_and_b32_e32 v3, 0xffff, v12
	v_lshrrev_b32_e32 v4, 16, v12
	v_lshl_or_b32 v3, v16, 16, v3
	v_and_or_b32 v4, v16, s57, v4
	v_add_u32_e32 v2, 0x9400, v2
	ds_write2_b32 v2, v3, v4 offset0:16 offset1:84
	v_and_b32_e32 v3, 0xffff, v13
	v_lshrrev_b32_e32 v4, 16, v13
	v_lshl_or_b32 v3, v17, 16, v3
	v_and_or_b32 v4, v17, s57, v4
	v_and_b32_e32 v9, 60, v5
	ds_write2_b32 v2, v3, v4 offset0:152 offset1:220
	v_lshl_add_u64 v[2:3], v[0:1], 2, s[94:95]
	v_lshlrev_b32_e32 v0, 2, v9
	v_lshl_add_u64 v[2:3], v[2:3], 0, v[0:1]
	v_lshl_add_u32 v0, v9, 1, s92
	v_ashrrev_i32_e32 v9, 4, v50
	v_lshlrev_b32_e32 v10, 6, v9
	s_mov_b64 s[4:5], 0x4000
	v_ashrrev_i32_e32 v11, 31, v10
	v_lshl_add_u64 v[4:5], v[2:3], 0, s[4:5]
	v_lshlrev_b64 v[14:15], 2, v[10:11]
	v_lshl_add_u64 v[10:11], v[2:3], 0, v[14:15]
	v_lshl_add_u64 v[14:15], v[4:5], 0, v[14:15]
	global_load_dwordx4 v[10:13], v[10:11], off
	s_nop 0
	global_load_dwordx4 v[14:17], v[14:15], off
	s_waitcnt vmcnt(0) lgkmcnt(0)
	v_cvt_pk_bf16_f32 v10, v10, v11
	v_cvt_pk_bf16_f32 v11, v12, v13
	v_cvt_pk_bf16_f32 v14, v14, v15
	v_cvt_pk_bf16_f32 v15, v16, v17
	v_ashrrev_i32_e32 v16, 4, v8
	v_lshlrev_b32_e32 v8, 6, v16
	v_mad_u64_u32 v[12:13], s[4:5], v9, s97, v[0:1]
	v_ashrrev_i32_e32 v9, 31, v8
	ds_write2st64_b64 v12, v[10:11], v[14:15] offset0:106 offset1:124
	v_lshlrev_b64 v[12:13], 2, v[8:9]
	v_lshl_add_u64 v[8:9], v[2:3], 0, v[12:13]
	v_lshl_add_u64 v[12:13], v[4:5], 0, v[12:13]
	global_load_dwordx4 v[8:11], v[8:9], off
	s_nop 0
	global_load_dwordx4 v[12:15], v[12:13], off
	s_waitcnt vmcnt(0) lgkmcnt(0)
	v_cvt_pk_bf16_f32 v8, v8, v9
	v_cvt_pk_bf16_f32 v9, v10, v11
	v_mad_u64_u32 v[10:11], s[4:5], v16, s97, v[0:1]
	v_cvt_pk_bf16_f32 v12, v12, v13
	v_cvt_pk_bf16_f32 v13, v14, v15
	ds_write2st64_b64 v10, v[8:9], v[12:13] offset0:106 offset1:124
	v_lshlrev_b32_e32 v8, 6, v7
	v_ashrrev_i32_e32 v9, 31, v8
	v_lshlrev_b64 v[12:13], 2, v[8:9]
	v_lshl_add_u64 v[8:9], v[2:3], 0, v[12:13]
	v_lshl_add_u64 v[12:13], v[4:5], 0, v[12:13]
	global_load_dwordx4 v[8:11], v[8:9], off
	s_nop 0
	global_load_dwordx4 v[12:15], v[12:13], off
	s_waitcnt vmcnt(0) lgkmcnt(0)
	v_cvt_pk_bf16_f32 v8, v8, v9
	v_cvt_pk_bf16_f32 v9, v10, v11
	v_mad_u64_u32 v[10:11], s[4:5], v7, s97, v[0:1]
	v_cvt_pk_bf16_f32 v12, v12, v13
	v_cvt_pk_bf16_f32 v13, v14, v15
	ds_write2st64_b64 v10, v[8:9], v[12:13] offset0:106 offset1:124
	v_ashrrev_i32_e32 v12, 4, v6
	v_lshlrev_b32_e32 v6, 6, v12
	v_ashrrev_i32_e32 v7, 31, v6
	v_lshlrev_b64 v[10:11], 2, v[6:7]
	v_lshl_add_u64 v[2:3], v[2:3], 0, v[10:11]
	global_load_dwordx4 v[6:9], v[2:3], off
	v_lshl_add_u64 v[2:3], v[4:5], 0, v[10:11]
	global_load_dwordx4 v[2:5], v[2:3], off
	v_and_b32_e32 v14, 48, v50
	s_waitcnt vmcnt(0) lgkmcnt(0)
	v_cvt_pk_bf16_f32 v6, v6, v7
	v_cvt_pk_bf16_f32 v7, v8, v9
	v_mad_u64_u32 v[8:9], s[4:5], v12, s97, v[0:1]
	v_cvt_pk_bf16_f32 v2, v2, v3
	v_cvt_pk_bf16_f32 v3, v4, v5
	v_mul_u32_u24_e32 v0, 0x48, v93
	ds_write2st64_b64 v8, v[6:7], v[2:3] offset0:106 offset1:124
	v_lshlrev_b32_e32 v2, 1, v0
	v_add_u32_e32 v0, s92, v14
	v_and_b32_e32 v12, -16, v48
	v_add_u32_e32 v13, s92, v2
	v_add_u32_e32 v88, v0, v2
	v_or_b32_e32 v2, 48, v51
	v_mul_u32_u24_e32 v2, 0x48, v2
	v_mul_lo_u32 v12, v12, s97
	v_lshl_add_u32 v89, v2, 1, v0
	v_mov_b32_e32 v2, v1
	v_mov_b32_e32 v6, v1
	v_add3_u32 v90, v13, v14, v12
	s_waitcnt lgkmcnt(0)
	s_barrier
	ds_read_b128 v[12:15], v90
	ds_read_b128 v[16:19], v88 offset:54272
	ds_read_b128 v[20:23], v88 offset:56576
	ds_read_b128 v[24:27], v88 offset:58880
	ds_read_b128 v[28:31], v89 offset:54272
	v_mov_b32_e32 v3, v2
	v_mov_b32_e32 v4, v2
	v_mov_b32_e32 v5, v2
	v_add_u32_e32 v11, 0xf800, v88
	v_mov_b32_e32 v7, v6
	s_waitcnt lgkmcnt(3)
	v_mfma_f32_16x16x32_bf16 v[16:19], v[16:19], v[12:15], v[2:5]
	v_mov_b32_e32 v8, v6
	v_mov_b32_e32 v9, v6
	v_add_u32_e32 v10, 0xf840, v88
	s_waitcnt lgkmcnt(2)
	v_mfma_f32_16x16x32_bf16 v[20:23], v[20:23], v[12:15], v[2:5]
	v_or_b32_e32 v51, 0x70, v51
	v_mul_u32_u24_e32 v51, 0x48, v51
	v_lshl_add_u32 v92, v51, 1, v0
	s_waitcnt lgkmcnt(1)
	v_mfma_f32_16x16x32_bf16 v[24:27], v[24:27], v[12:15], v[2:5]
	v_lshrrev_b32_e32 v0, 2, v50
	v_mov_b32_e32 v50, v1
	v_and_b32_e32 v91, 12, v0
	s_waitcnt lgkmcnt(0)
	v_mfma_f32_16x16x32_bf16 v[2:5], v[28:31], v[12:15], v[2:5]
	ds_read_b128 v[28:31], v90 offset:64
	ds_read_b128 v[32:35], v88 offset:54336
	ds_read_b128 v[36:39], v88 offset:56640
	ds_read_b128 v[40:43], v88 offset:58944
	ds_read_b128 v[44:47], v89 offset:54336
	v_sub_u32_e32 v0, v99, v91
	v_sub_u32_e32 v86, 0, v0
	s_waitcnt lgkmcnt(3)
	v_mfma_f32_16x16x32_bf16 v[16:19], v[32:35], v[28:31], v[16:19]
	v_max_i32_e32 v0, v0, v86
	v_cvt_f32_u32_e32 v0, v0
	v_cmp_lt_i32_e32 vcc, v99, v91
	s_waitcnt lgkmcnt(2)
	v_mfma_f32_16x16x32_bf16 v[20:23], v[36:39], v[28:31], v[20:23]
	v_or_b32_e32 v94, 16, v91
	v_cndmask_b32_e32 v86, v96, v97, vcc
	v_mul_f32_e32 v0, v86, v0
	s_waitcnt lgkmcnt(1)
	v_mfma_f32_16x16x32_bf16 v[24:27], v[40:43], v[28:31], v[24:27]
	v_mul_f32_e32 v0, 0xbfb8aa3b, v0
	v_exp_f32_e32 v86, v0
	v_cmp_gt_i32_e32 vcc, v99, v91
	s_waitcnt lgkmcnt(0)
	v_mfma_f32_16x16x32_bf16 v[2:5], v[44:47], v[28:31], v[2:5]
	ds_read_b128 v[32:35], v88 offset:63488
	ds_read_b128 v[36:39], v11 offset:2304
	ds_read_b128 v[40:43], v11 offset:4608
	ds_read_b128 v[44:47], v89 offset:63488
	v_or_b32_e32 v95, 17, v91
	v_or_b32_e32 v120, 0x53, v91
	s_waitcnt lgkmcnt(3)
	v_mfma_f32_16x16x32_bf16 v[32:35], v[32:35], v[12:15], v[6:9]
	v_or_b32_e32 v121, 0x60, v91
	v_or_b32_e32 v123, 0x61, v91
	s_waitcnt lgkmcnt(2)
	v_mfma_f32_16x16x32_bf16 v[36:39], v[36:39], v[12:15], v[6:9]
	s_waitcnt lgkmcnt(1)
	v_mfma_f32_16x16x32_bf16 v[40:43], v[40:43], v[12:15], v[6:9]
	s_waitcnt lgkmcnt(0)
	v_mfma_f32_16x16x32_bf16 v[6:9], v[44:47], v[12:15], v[6:9]
	ds_read_b128 v[12:15], v88 offset:63552
	ds_read_b128 v[44:47], v10 offset:2304
	ds_read_b128 v[52:55], v10 offset:4608
	ds_read_b128 v[56:59], v89 offset:63552
	s_waitcnt lgkmcnt(3)
	v_mfma_f32_16x16x32_bf16 v[12:15], v[12:15], v[28:31], v[32:35]
	s_waitcnt lgkmcnt(2)
	v_mfma_f32_16x16x32_bf16 v[44:47], v[44:47], v[28:31], v[36:39]
	s_waitcnt lgkmcnt(1)
	v_mfma_f32_16x16x32_bf16 v[52:55], v[52:55], v[28:31], v[40:43]
	s_waitcnt lgkmcnt(0)
	v_mfma_f32_16x16x32_bf16 v[6:9], v[56:59], v[28:31], v[6:9]
	v_sub_u32_e32 v29, 0x80, v99
	v_add_u32_e32 v28, 1, v99
	v_cvt_f32_i32_e32 v29, v29
	v_cvt_f32_i32_e32 v28, v28
	v_mul_f32_e32 v29, v29, v97
	v_mul_f32_e32 v28, v28, v96
	v_mul_f32_e32 v29, 0xbfb8aa3b, v29
	v_mul_f32_e32 v28, 0xbfb8aa3b, v28
	v_exp_f32_e32 v30, v29
	v_exp_f32_e32 v28, v28
	v_pk_mul_f32 v[12:13], v[30:31], v[12:13] op_sel_hi:[0,1]
	v_pk_mul_f32 v[14:15], v[30:31], v[14:15] op_sel_hi:[0,1]
	v_pk_fma_f32 v[34:35], v[28:29], v[16:17], v[12:13] op_sel_hi:[0,1,1]
	v_pk_mul_f32 v[12:13], v[30:31], v[44:45] op_sel_hi:[0,1]
	v_pk_fma_f32 v[36:37], v[28:29], v[18:19], v[14:15] op_sel_hi:[0,1,1]
	v_pk_mul_f32 v[14:15], v[30:31], v[46:47] op_sel_hi:[0,1]
	v_pk_fma_f32 v[38:39], v[28:29], v[20:21], v[12:13] op_sel_hi:[0,1,1]
	v_pk_mul_f32 v[12:13], v[30:31], v[52:53] op_sel_hi:[0,1]
	v_pk_mul_f32 v[6:7], v[30:31], v[6:7] op_sel_hi:[0,1]
	v_pk_fma_f32 v[40:41], v[28:29], v[22:23], v[14:15] op_sel_hi:[0,1,1]
	v_pk_mul_f32 v[14:15], v[30:31], v[54:55] op_sel_hi:[0,1]
	v_pk_fma_f32 v[42:43], v[28:29], v[24:25], v[12:13] op_sel_hi:[0,1,1]
	v_pk_mul_f32 v[8:9], v[30:31], v[8:9] op_sel_hi:[0,1]
	v_pk_fma_f32 v[46:47], v[28:29], v[2:3], v[6:7] op_sel_hi:[0,1,1]
	v_mov_b32_e32 v2, v1
	v_mov_b32_e32 v12, v1
	v_pk_fma_f32 v[44:45], v[28:29], v[26:27], v[14:15] op_sel_hi:[0,1,1]
	v_pk_fma_f32 v[48:49], v[28:29], v[4:5], v[8:9] op_sel_hi:[0,1,1]
	ds_read_b128 v[22:25], v90 offset:9216
	ds_read_b128 v[6:9], v88 offset:54272
	ds_read_b128 v[16:19], v88 offset:56576
	ds_read_b128 v[26:29], v88 offset:58880
	ds_read_b128 v[30:33], v89 offset:54272
	v_mov_b32_e32 v3, v2
	v_mov_b32_e32 v4, v2
	v_mov_b32_e32 v5, v2
	v_mov_b32_e32 v13, v12
	v_mov_b32_e32 v14, v12
	s_waitcnt lgkmcnt(3)
	v_mfma_f32_16x16x32_bf16 v[6:9], v[6:9], v[22:25], v[2:5]
	v_mov_b32_e32 v15, v12
	s_waitcnt lgkmcnt(2)
	v_mfma_f32_16x16x32_bf16 v[16:19], v[16:19], v[22:25], v[2:5]
	s_waitcnt lgkmcnt(1)
	v_mfma_f32_16x16x32_bf16 v[26:29], v[26:29], v[22:25], v[2:5]
	s_waitcnt lgkmcnt(0)
	v_mfma_f32_16x16x32_bf16 v[30:33], v[30:33], v[22:25], v[2:5]
	ds_read_b128 v[52:55], v90 offset:9280
	s_nop 1
	ds_read_b128 v[2:5], v88 offset:54336
	ds_read_b128 v[56:59], v88 offset:56640
	ds_read_b128 v[60:63], v88 offset:58944
	ds_read_b128 v[64:67], v89 offset:54336
	s_waitcnt lgkmcnt(3)
	v_mfma_f32_16x16x32_bf16 v[2:5], v[2:5], v[52:55], v[6:9]
	s_waitcnt lgkmcnt(2)
	v_mfma_f32_16x16x32_bf16 v[6:9], v[56:59], v[52:55], v[16:19]
	s_waitcnt lgkmcnt(1)
	v_mfma_f32_16x16x32_bf16 v[18:21], v[60:63], v[52:55], v[26:29]
	s_waitcnt lgkmcnt(0)
	v_mfma_f32_16x16x32_bf16 v[26:29], v[64:67], v[52:55], v[30:33]
	s_nop 2
	ds_read_b128 v[30:33], v88 offset:63488
	ds_read_b128 v[56:59], v11 offset:2304
	ds_read_b128 v[60:63], v11 offset:4608
	ds_read_b128 v[64:67], v89 offset:63488
	s_waitcnt lgkmcnt(3)
	v_mfma_f32_16x16x32_bf16 v[30:33], v[30:33], v[22:25], v[12:15]
	s_waitcnt lgkmcnt(2)
	v_mfma_f32_16x16x32_bf16 v[56:59], v[56:59], v[22:25], v[12:15]
	s_waitcnt lgkmcnt(1)
	v_mfma_f32_16x16x32_bf16 v[60:63], v[60:63], v[22:25], v[12:15]
	s_waitcnt lgkmcnt(0)
	v_mfma_f32_16x16x32_bf16 v[64:67], v[64:67], v[22:25], v[12:15]
	s_nop 2
	ds_read_b128 v[12:15], v88 offset:63552
	ds_read_b128 v[22:25], v10 offset:2304
	ds_read_b128 v[68:71], v10 offset:4608
	ds_read_b128 v[72:75], v89 offset:63552
	s_waitcnt lgkmcnt(3)
	v_mfma_f32_16x16x32_bf16 v[10:13], v[12:15], v[52:55], v[30:33]
	v_mov_b32_e32 v51, v50
	s_waitcnt lgkmcnt(2)
	v_mfma_f32_16x16x32_bf16 v[14:17], v[22:25], v[52:55], v[56:59]
	s_waitcnt lgkmcnt(1)
	v_mfma_f32_16x16x32_bf16 v[22:25], v[68:71], v[52:55], v[60:63]
	s_waitcnt lgkmcnt(0)
	v_mfma_f32_16x16x32_bf16 v[30:33], v[72:75], v[52:55], v[64:67]
	ds_read_b128 v[54:57], v90
	ds_read_b128 v[58:61], v88 offset:18432
	s_nop 0
	ds_read_b128 v[62:65], v88 offset:20736
	ds_read_b128 v[66:69], v88 offset:23040
	ds_read_b128 v[70:73], v89 offset:18432
	ds_read_b128 v[74:77], v88 offset:27648
	ds_read_b128 v[78:81], v88 offset:29952
	ds_read_b128 v[100:103], v88 offset:32256
	ds_read_b128 v[104:107], v92 offset:18432
	v_mov_b32_e32 v52, v50
	v_mov_b32_e32 v53, v50
	s_waitcnt lgkmcnt(7)
	s_nop 0
	v_mfma_f32_16x16x32_bf16 v[58:61], v[58:61], v[54:57], v[50:53]
	s_waitcnt lgkmcnt(6)
	v_mfma_f32_16x16x32_bf16 v[62:65], v[62:65], v[54:57], v[50:53]
	s_waitcnt lgkmcnt(5)
	v_mfma_f32_16x16x32_bf16 v[66:69], v[66:69], v[54:57], v[50:53]
	s_waitcnt lgkmcnt(4)
	v_mfma_f32_16x16x32_bf16 v[108:111], v[70:73], v[54:57], v[50:53]
	s_waitcnt lgkmcnt(3)
	v_mfma_f32_16x16x32_bf16 v[112:115], v[74:77], v[54:57], v[50:53]
	s_waitcnt lgkmcnt(2)
	v_mfma_f32_16x16x32_bf16 v[116:119], v[78:81], v[54:57], v[50:53]
	s_waitcnt lgkmcnt(1)
	v_mfma_f32_16x16x32_bf16 v[100:103], v[100:103], v[54:57], v[50:53]
	s_waitcnt lgkmcnt(0)
	v_mfma_f32_16x16x32_bf16 v[50:53], v[104:107], v[54:57], v[50:53]
	ds_read_b128 v[104:107], v90 offset:64
	ds_read_b128 v[54:57], v88 offset:18496
	ds_read_b128 v[70:73], v88 offset:20800
	ds_read_b128 v[124:127], v88 offset:23104
	ds_read_b128 v[128:131], v89 offset:18496
	ds_read_b128 v[132:135], v88 offset:27712
	ds_read_b128 v[136:139], v88 offset:30016
	ds_read_b128 v[140:143], v88 offset:32320
	ds_read_b128 v[144:147], v92 offset:18496
	s_waitcnt lgkmcnt(7)
	v_mfma_f32_16x16x32_bf16 v[78:81], v[54:57], v[104:107], v[58:61]
	s_waitcnt lgkmcnt(1)
	v_mfma_f32_16x16x32_bf16 v[54:57], v[140:143], v[104:107], v[100:103]
	s_nop 2
	v_or_b32_e32 v102, 1, v91
	v_sub_u32_e32 v0, v102, v99
	v_sub_u32_e32 v87, v99, v102
	v_cndmask_b32_e32 v0, v0, v87, vcc
	v_cvt_f32_i32_e32 v0, v0
	v_cndmask_b32_e32 v87, v97, v96, vcc
	v_mfma_f32_16x16x32_bf16 v[74:77], v[70:73], v[104:107], v[62:65]
	v_or_b32_e32 v103, 3, v91
	v_mul_f32_e32 v0, v87, v0
	v_mul_f32_e32 v0, 0xbfb8aa3b, v0
	v_exp_f32_e32 v87, v0
	v_mfma_f32_16x16x32_bf16 v[70:73], v[124:127], v[104:107], v[66:69]
	v_or_b32_e32 v100, 18, v91
	v_or_b32_e32 v101, 19, v91
	v_pk_mul_f32 v[78:79], v[86:87], v[78:79]
	v_mfma_f32_16x16x32_bf16 v[66:69], v[128:131], v[104:107], v[108:111]
	v_or_b32_e32 v124, 0x62, v91
	v_or_b32_e32 v125, 0x63, v91
	v_lshl_add_u32 v130, v93, 7, v88
	v_mfma_f32_16x16x32_bf16 v[62:65], v[132:135], v[104:107], v[112:115]
	v_or_b32_e32 v108, 35, v91
	v_or_b32_e32 v109, 48, v91
	v_or_b32_e32 v110, 49, v91
	v_mfma_f32_16x16x32_bf16 v[58:61], v[136:139], v[104:107], v[116:119]
	v_or_b32_e32 v111, 50, v91
	v_or_b32_e32 v112, 51, v91
	v_or_b32_e32 v113, 64, v91
	s_waitcnt lgkmcnt(0)
	v_mfma_f32_16x16x32_bf16 v[50:53], v[144:147], v[104:107], v[50:53]
	v_or_b32_e32 v104, 2, v91
	v_sub_u32_e32 v0, v99, v104
	v_sub_u32_e32 v86, 0, v0
	v_max_i32_e32 v0, v0, v86
	v_cvt_f32_u32_e32 v0, v0
	v_cmp_lt_i32_e32 vcc, v99, v104
	v_or_b32_e32 v105, 32, v91
	v_or_b32_e32 v106, 33, v91
	v_cndmask_b32_e32 v86, v96, v97, vcc
	v_mul_f32_e32 v0, v86, v0
	v_mul_f32_e32 v0, 0xbfb8aa3b, v0
	v_exp_f32_e32 v86, v0
	v_sub_u32_e32 v0, v99, v103
	v_sub_u32_e32 v87, 0, v0
	v_max_i32_e32 v0, v0, v87
	v_cvt_f32_u32_e32 v0, v0
	v_cmp_lt_i32_e32 vcc, v99, v103
	v_or_b32_e32 v107, 34, v91
	v_or_b32_e32 v114, 0x41, v91
	v_cndmask_b32_e32 v87, v96, v97, vcc
	v_mul_f32_e32 v0, v87, v0
	v_mul_f32_e32 v0, 0xbfb8aa3b, v0
	v_exp_f32_e32 v87, v0
	v_sub_u32_e32 v0, v99, v94
	v_cmp_lt_i32_e32 vcc, v99, v94
	v_or_b32_e32 v115, 0x42, v91
	v_pk_mul_f32 v[80:81], v[86:87], v[80:81]
	v_sub_u32_e32 v86, 0, v0
	v_max_i32_e32 v0, v0, v86
	v_cvt_f32_u32_e32 v0, v0
	v_cndmask_b32_e32 v86, v96, v97, vcc
	v_cmp_lt_i32_e32 vcc, v99, v95
	v_or_b32_e32 v116, 0x43, v91
	v_mul_f32_e32 v0, v86, v0
	v_mul_f32_e32 v0, 0xbfb8aa3b, v0
	v_exp_f32_e32 v86, v0
	v_sub_u32_e32 v0, v99, v95
	v_sub_u32_e32 v87, 0, v0
	v_max_i32_e32 v0, v0, v87
	v_cvt_f32_u32_e32 v0, v0
	v_cndmask_b32_e32 v87, v96, v97, vcc
	v_cmp_lt_i32_e32 vcc, v99, v100
	v_or_b32_e32 v117, 0x50, v91
	v_mul_f32_e32 v0, v87, v0
	v_mul_f32_e32 v0, 0xbfb8aa3b, v0
	v_exp_f32_e32 v87, v0
	v_sub_u32_e32 v0, v99, v100
	v_or_b32_e32 v118, 0x51, v91
	v_or_b32_e32 v119, 0x52, v91
	v_pk_mul_f32 v[74:75], v[86:87], v[74:75]
	v_sub_u32_e32 v86, 0, v0
	v_max_i32_e32 v0, v0, v86
	v_cvt_f32_u32_e32 v0, v0
	v_cndmask_b32_e32 v86, v96, v97, vcc
	v_cmp_lt_i32_e32 vcc, v99, v101
	v_cvt_pk_bf16_f32 v78, v78, v79
	v_mul_f32_e32 v0, v86, v0
	v_mul_f32_e32 v0, 0xbfb8aa3b, v0
	v_exp_f32_e32 v86, v0
	v_sub_u32_e32 v0, v99, v101
	v_sub_u32_e32 v87, 0, v0
	v_max_i32_e32 v0, v0, v87
	v_cvt_f32_u32_e32 v0, v0
	v_cndmask_b32_e32 v87, v96, v97, vcc
	v_cmp_lt_i32_e32 vcc, v99, v105
	v_cvt_pk_bf16_f32 v79, v80, v81
	v_mul_f32_e32 v0, v87, v0
	v_mul_f32_e32 v0, 0xbfb8aa3b, v0
	v_exp_f32_e32 v87, v0
	v_sub_u32_e32 v0, v99, v105
	v_cvt_pk_bf16_f32 v80, v74, v75
	v_or_b32_e32 v126, 0x70, v91
	v_pk_mul_f32 v[76:77], v[86:87], v[76:77]
	v_sub_u32_e32 v86, 0, v0
	v_max_i32_e32 v0, v0, v86
	v_cvt_f32_u32_e32 v0, v0
	v_cndmask_b32_e32 v86, v96, v97, vcc
	v_cmp_lt_i32_e32 vcc, v99, v106
	v_cvt_pk_bf16_f32 v81, v76, v77
	v_mul_f32_e32 v0, v86, v0
	v_mul_f32_e32 v0, 0xbfb8aa3b, v0
	v_exp_f32_e32 v86, v0
	v_sub_u32_e32 v0, v99, v106
	v_sub_u32_e32 v87, 0, v0
	v_max_i32_e32 v0, v0, v87
	v_cvt_f32_u32_e32 v0, v0
	v_cndmask_b32_e32 v87, v96, v97, vcc
	v_cmp_lt_i32_e32 vcc, v99, v107
	ds_read_b128 v[74:77], v130 offset:36864
	v_mul_f32_e32 v0, v87, v0
	v_mul_f32_e32 v0, 0xbfb8aa3b, v0
	v_exp_f32_e32 v87, v0
	v_sub_u32_e32 v0, v99, v107
	v_or_b32_e32 v127, 0x71, v91
	v_or_b32_e32 v128, 0x72, v91
	v_pk_mul_f32 v[70:71], v[86:87], v[70:71]
	v_sub_u32_e32 v86, 0, v0
	v_max_i32_e32 v0, v0, v86
	v_cvt_f32_u32_e32 v0, v0
	v_cndmask_b32_e32 v86, v96, v97, vcc
	v_cmp_lt_i32_e32 vcc, v99, v108
	v_cvt_pk_bf16_f32 v70, v70, v71
	v_mul_f32_e32 v0, v86, v0
	v_mul_f32_e32 v0, 0xbfb8aa3b, v0
	v_exp_f32_e32 v86, v0
	v_sub_u32_e32 v0, v99, v108
	v_sub_u32_e32 v87, 0, v0
	v_max_i32_e32 v0, v0, v87
	v_cvt_f32_u32_e32 v0, v0
	v_cndmask_b32_e32 v87, v96, v97, vcc
	v_cmp_lt_i32_e32 vcc, v99, v109
	v_or_b32_e32 v129, 0x73, v91
	v_mul_f32_e32 v0, v87, v0
	v_mul_f32_e32 v0, 0xbfb8aa3b, v0
	v_exp_f32_e32 v87, v0
	v_sub_u32_e32 v0, v99, v109
	v_pk_mul_f32 v[72:73], v[86:87], v[72:73]
	v_sub_u32_e32 v86, 0, v0
	v_max_i32_e32 v0, v0, v86
	v_cvt_f32_u32_e32 v0, v0
	v_cndmask_b32_e32 v86, v96, v97, vcc
	v_cmp_lt_i32_e32 vcc, v99, v110
	v_cvt_pk_bf16_f32 v71, v72, v73
	v_mul_f32_e32 v0, v86, v0
	v_mul_f32_e32 v0, 0xbfb8aa3b, v0
	v_exp_f32_e32 v86, v0
	v_sub_u32_e32 v0, v99, v110
	v_sub_u32_e32 v87, 0, v0
	v_max_i32_e32 v0, v0, v87
	v_cvt_f32_u32_e32 v0, v0
	v_cndmask_b32_e32 v87, v96, v97, vcc
	v_cmp_lt_i32_e32 vcc, v99, v111
	v_mul_f32_e32 v0, v87, v0
	v_mul_f32_e32 v0, 0xbfb8aa3b, v0
	v_exp_f32_e32 v87, v0
	v_sub_u32_e32 v0, v99, v111
	v_pk_mul_f32 v[66:67], v[86:87], v[66:67]
	v_sub_u32_e32 v86, 0, v0
	v_max_i32_e32 v0, v0, v86
	v_cvt_f32_u32_e32 v0, v0
	v_cndmask_b32_e32 v86, v96, v97, vcc
	v_cmp_lt_i32_e32 vcc, v99, v112
	v_cvt_pk_bf16_f32 v72, v66, v67
	v_mul_f32_e32 v0, v86, v0
	v_mul_f32_e32 v0, 0xbfb8aa3b, v0
	v_exp_f32_e32 v86, v0
	v_sub_u32_e32 v0, v99, v112
	v_sub_u32_e32 v87, 0, v0
	v_max_i32_e32 v0, v0, v87
	v_cvt_f32_u32_e32 v0, v0
	v_cndmask_b32_e32 v87, v96, v97, vcc
	v_cmp_lt_i32_e32 vcc, v99, v113
	v_mul_f32_e32 v0, v87, v0
	v_mul_f32_e32 v0, 0xbfb8aa3b, v0
	v_exp_f32_e32 v87, v0
	v_sub_u32_e32 v0, v99, v113
	v_pk_mul_f32 v[68:69], v[86:87], v[68:69]
	v_sub_u32_e32 v86, 0, v0
	v_max_i32_e32 v0, v0, v86
	v_cvt_f32_u32_e32 v0, v0
	v_cndmask_b32_e32 v86, v96, v97, vcc
	v_cmp_lt_i32_e32 vcc, v99, v114
	v_cvt_pk_bf16_f32 v73, v68, v69
	v_mul_f32_e32 v0, v86, v0
	v_mul_f32_e32 v0, 0xbfb8aa3b, v0
	v_exp_f32_e32 v86, v0
	v_sub_u32_e32 v0, v99, v114
	v_sub_u32_e32 v87, 0, v0
	v_max_i32_e32 v0, v0, v87
	v_cvt_f32_u32_e32 v0, v0
	v_cndmask_b32_e32 v87, v96, v97, vcc
	v_cmp_lt_i32_e32 vcc, v99, v115
	ds_read_b128 v[66:69], v130 offset:36928
	v_mul_f32_e32 v0, v87, v0
	v_mul_f32_e32 v0, 0xbfb8aa3b, v0
	v_exp_f32_e32 v87, v0
	v_sub_u32_e32 v0, v99, v115
	s_waitcnt lgkmcnt(1)
	v_mfma_f32_16x16x32_bf16 v[34:37], v[74:77], v[78:81], v[34:37]
	ds_read_b128 v[74:77], v130 offset:41216
	v_pk_mul_f32 v[62:63], v[86:87], v[62:63]
	v_sub_u32_e32 v86, 0, v0
	v_max_i32_e32 v0, v0, v86
	v_cvt_f32_u32_e32 v0, v0
	v_cndmask_b32_e32 v86, v96, v97, vcc
	v_cmp_lt_i32_e32 vcc, v99, v116
	v_cvt_pk_bf16_f32 v62, v62, v63
	v_mul_f32_e32 v0, v86, v0
	v_mul_f32_e32 v0, 0xbfb8aa3b, v0
	v_exp_f32_e32 v86, v0
	v_sub_u32_e32 v0, v99, v116
	v_sub_u32_e32 v87, 0, v0
	v_max_i32_e32 v0, v0, v87
	v_cvt_f32_u32_e32 v0, v0
	v_cndmask_b32_e32 v87, v96, v97, vcc
	v_cmp_lt_i32_e32 vcc, v99, v117
	s_waitcnt lgkmcnt(1)
	v_mfma_f32_16x16x32_bf16 v[34:37], v[66:69], v[70:73], v[34:37]
	v_mul_f32_e32 v0, v87, v0
	v_mul_f32_e32 v0, 0xbfb8aa3b, v0
	v_exp_f32_e32 v87, v0
	v_sub_u32_e32 v0, v99, v117
	ds_read_b128 v[66:69], v130 offset:41280
	v_pk_mul_f32 v[64:65], v[86:87], v[64:65]
	v_sub_u32_e32 v86, 0, v0
	v_max_i32_e32 v0, v0, v86
	v_cvt_f32_u32_e32 v0, v0
	v_cndmask_b32_e32 v86, v96, v97, vcc
	v_cmp_lt_i32_e32 vcc, v99, v118
	v_cvt_pk_bf16_f32 v63, v64, v65
	v_mul_f32_e32 v0, v86, v0
	v_mul_f32_e32 v0, 0xbfb8aa3b, v0
	v_exp_f32_e32 v86, v0
	v_sub_u32_e32 v0, v99, v118
	v_sub_u32_e32 v87, 0, v0
	v_max_i32_e32 v0, v0, v87
	v_cvt_f32_u32_e32 v0, v0
	v_cndmask_b32_e32 v87, v96, v97, vcc
	v_cmp_lt_i32_e32 vcc, v99, v119
	v_mul_f32_e32 v0, v87, v0
	v_mul_f32_e32 v0, 0xbfb8aa3b, v0
	v_exp_f32_e32 v87, v0
	v_sub_u32_e32 v0, v99, v119
	v_pk_mul_f32 v[58:59], v[86:87], v[58:59]
	v_sub_u32_e32 v86, 0, v0
	v_max_i32_e32 v0, v0, v86
	v_cvt_f32_u32_e32 v0, v0
	v_cndmask_b32_e32 v86, v96, v97, vcc
	v_cmp_lt_i32_e32 vcc, v99, v120
	v_cvt_pk_bf16_f32 v64, v58, v59
	v_mul_f32_e32 v0, v86, v0
	v_mul_f32_e32 v0, 0xbfb8aa3b, v0
	v_exp_f32_e32 v86, v0
	v_sub_u32_e32 v0, v99, v120
	v_sub_u32_e32 v87, 0, v0
	v_max_i32_e32 v0, v0, v87
	v_cvt_f32_u32_e32 v0, v0
	v_cndmask_b32_e32 v87, v96, v97, vcc
	v_cmp_lt_i32_e32 vcc, v99, v121
	v_mul_f32_e32 v0, v87, v0
	v_mul_f32_e32 v0, 0xbfb8aa3b, v0
	v_exp_f32_e32 v87, v0
	v_sub_u32_e32 v0, v99, v121
	v_pk_mul_f32 v[60:61], v[86:87], v[60:61]
	v_sub_u32_e32 v86, 0, v0
	v_max_i32_e32 v0, v0, v86
	v_cvt_f32_u32_e32 v0, v0
	v_cndmask_b32_e32 v86, v96, v97, vcc
	v_cmp_lt_i32_e32 vcc, v99, v123
	v_cvt_pk_bf16_f32 v65, v60, v61
	v_mul_f32_e32 v0, v86, v0
	v_mul_f32_e32 v0, 0xbfb8aa3b, v0
	v_exp_f32_e32 v86, v0
	v_sub_u32_e32 v0, v99, v123
	v_sub_u32_e32 v87, 0, v0
	v_max_i32_e32 v0, v0, v87
	v_cvt_f32_u32_e32 v0, v0
	v_cndmask_b32_e32 v87, v96, v97, vcc
	v_cmp_lt_i32_e32 vcc, v99, v124
	ds_read_b128 v[58:61], v130 offset:36992
	v_mul_f32_e32 v0, v87, v0
	v_mul_f32_e32 v0, 0xbfb8aa3b, v0
	v_exp_f32_e32 v87, v0
	v_sub_u32_e32 v0, v99, v124
	s_waitcnt lgkmcnt(2)
	v_mfma_f32_16x16x32_bf16 v[38:41], v[74:77], v[78:81], v[38:41]
	ds_read_b128 v[74:77], v130 offset:45568
	v_pk_mul_f32 v[54:55], v[86:87], v[54:55]
	v_sub_u32_e32 v86, 0, v0
	v_max_i32_e32 v0, v0, v86
	v_cvt_f32_u32_e32 v0, v0
	v_cndmask_b32_e32 v86, v96, v97, vcc
	v_cmp_lt_i32_e32 vcc, v99, v125
	s_waitcnt lgkmcnt(1)
	v_mfma_f32_16x16x32_bf16 v[34:37], v[58:61], v[62:65], v[34:37]
	v_mul_f32_e32 v0, v86, v0
	v_mul_f32_e32 v0, 0xbfb8aa3b, v0
	v_exp_f32_e32 v86, v0
	v_sub_u32_e32 v0, v99, v125
	v_sub_u32_e32 v87, 0, v0
	v_max_i32_e32 v0, v0, v87
	v_cvt_f32_u32_e32 v0, v0
	v_cndmask_b32_e32 v87, v96, v97, vcc
	v_cmp_lt_i32_e32 vcc, v99, v126
	ds_read_b128 v[58:61], v130 offset:41344
	v_mul_f32_e32 v0, v87, v0
	v_mul_f32_e32 v0, 0xbfb8aa3b, v0
	v_exp_f32_e32 v87, v0
	v_sub_u32_e32 v0, v99, v126
	v_mfma_f32_16x16x32_bf16 v[38:41], v[66:69], v[70:73], v[38:41]
	ds_read_b128 v[66:69], v130 offset:45632
	v_pk_mul_f32 v[56:57], v[86:87], v[56:57]
	v_sub_u32_e32 v86, 0, v0
	v_max_i32_e32 v0, v0, v86
	v_cvt_f32_u32_e32 v0, v0
	v_cndmask_b32_e32 v86, v96, v97, vcc
	v_cmp_lt_i32_e32 vcc, v99, v127
	s_waitcnt lgkmcnt(2)
	v_mfma_f32_16x16x32_bf16 v[42:45], v[74:77], v[78:81], v[42:45]
	v_mul_f32_e32 v0, v86, v0
	v_mul_f32_e32 v0, 0xbfb8aa3b, v0
	v_exp_f32_e32 v86, v0
	v_sub_u32_e32 v0, v99, v127
	v_sub_u32_e32 v87, 0, v0
	v_max_i32_e32 v0, v0, v87
	v_cvt_f32_u32_e32 v0, v0
	v_cndmask_b32_e32 v87, v96, v97, vcc
	ds_read_b128 v[74:77], v130 offset:49920
	s_waitcnt lgkmcnt(2)
	v_mfma_f32_16x16x32_bf16 v[38:41], v[58:61], v[62:65], v[38:41]
	v_mul_f32_e32 v0, v87, v0
	v_mul_f32_e32 v0, 0xbfb8aa3b, v0
	v_exp_f32_e32 v87, v0
	ds_read_b128 v[58:61], v130 offset:45696
	v_sub_u32_e32 v0, v99, v128
	s_waitcnt lgkmcnt(2)
	v_mfma_f32_16x16x32_bf16 v[42:45], v[66:69], v[70:73], v[42:45]
	v_mul_f32_e64 v50, v86, v50
	v_mul_f32_e64 v51, v87, v51
	v_sub_u32_e32 v86, 0, v0
	v_max_i32_e32 v0, v0, v86
	ds_read_b128 v[66:69], v130 offset:49984
	v_cvt_f32_u32_e32 v0, v0
	v_cmp_lt_i32_e32 vcc, v99, v128
	s_waitcnt lgkmcnt(1)
	v_mfma_f32_16x16x32_bf16 v[58:61], v[58:61], v[62:65], v[42:45]
	v_cndmask_b32_e32 v86, v96, v97, vcc
	v_mul_f32_e32 v0, v86, v0
	s_nop 0
	ds_read_b128 v[42:45], v130 offset:50048
	v_mfma_f32_16x16x32_bf16 v[46:49], v[74:77], v[78:81], v[46:49]
	v_mul_f32_e32 v0, 0xbfb8aa3b, v0
	v_exp_f32_e32 v86, v0
	v_sub_u32_e32 v0, v99, v129
	v_sub_u32_e32 v87, 0, v0
	v_max_i32_e32 v0, v0, v87
	s_waitcnt lgkmcnt(1)
	v_mfma_f32_16x16x32_bf16 v[46:49], v[66:69], v[70:73], v[46:49]
	v_cvt_f32_u32_e32 v0, v0
	v_cmp_lt_i32_e32 vcc, v99, v129
	s_waitcnt lgkmcnt(0)
	v_mfma_f32_16x16x32_bf16 v[62:65], v[42:45], v[62:65], v[46:49]
	v_cndmask_b32_e32 v87, v96, v97, vcc
	ds_read_b128 v[42:45], v130 offset:37056
	v_mul_f32_e32 v0, v87, v0
	v_mul_f32_e32 v0, 0xbfb8aa3b, v0
	v_exp_f32_e32 v87, v0
	s_nop 0
	v_pk_mul_f32 v[86:87], v[86:87], v[52:53]
	v_cvt_pk_bf16_f32 v52, v54, v55
	v_cvt_pk_bf16_f32 v53, v56, v57
	v_cvt_pk_bf16_f32 v54, v50, v51
	v_cvt_pk_bf16_f32 v55, v86, v87
	s_waitcnt lgkmcnt(0)
	s_nop 0
	v_mfma_f32_16x16x32_bf16 v[46:49], v[42:45], v[52:55], v[34:37]
	s_nop 2
	ds_read_b128 v[34:37], v130 offset:41408
	s_waitcnt lgkmcnt(0)
	v_mfma_f32_16x16x32_bf16 v[42:45], v[34:37], v[52:55], v[38:41]
	ds_read_b128 v[34:37], v130 offset:45760
	s_nop 0
	v_mul_f32_e32 v0, v47, v47
	v_fmac_f32_e32 v0, v46, v46
	s_waitcnt lgkmcnt(0)
	v_mfma_f32_16x16x32_bf16 v[38:41], v[34:37], v[52:55], v[58:61]
	ds_read_b128 v[34:37], v130 offset:50112
	v_fmac_f32_e32 v0, v48, v48
	v_fmac_f32_e32 v0, v49, v49
	v_fmac_f32_e32 v0, v42, v42
	v_fmac_f32_e32 v0, v43, v43
	v_fmac_f32_e32 v0, v44, v44
	s_waitcnt lgkmcnt(0)
	v_mfma_f32_16x16x32_bf16 v[34:37], v[34:37], v[52:55], v[62:65]
	v_fmac_f32_e32 v0, v45, v45
	v_pk_mul_f32 v[52:53], v[38:39], v[38:39]
	v_pk_mul_f32 v[50:51], v[40:41], v[40:41]
	v_add_f32_e32 v0, v52, v0
	v_add_f32_e32 v0, v53, v0
	v_add_f32_e32 v0, v50, v0
	v_add_f32_e32 v0, v51, v0
	s_nop 0
	v_pk_mul_f32 v[52:53], v[34:35], v[34:35]
	v_pk_mul_f32 v[50:51], v[36:37], v[36:37]
	v_add_f32_e32 v0, v52, v0
	v_add_f32_e32 v0, v53, v0
	v_add_f32_e32 v0, v50, v0
	v_add_f32_e32 v0, v51, v0
	v_and_b32_e32 v51, 64, v170
	v_xor_b32_e32 v50, 16, v170
	v_add_u32_e32 v51, 64, v51
	v_cmp_lt_i32_e32 vcc, v50, v51
	v_mad_i64_i32 v[52:53], s[4:5], v99, s33, v[82:83]
	s_nop 0
	v_cndmask_b32_e32 v50, v170, v50, vcc
	v_lshlrev_b32_e32 v131, 2, v50
	ds_bpermute_b32 v50, v131, v0
	v_lshl_add_u64 v[52:53], v[52:53], 0, v[84:85]
	s_waitcnt lgkmcnt(0)
	v_add_f32_e32 v0, v0, v50
	v_xor_b32_e32 v50, 32, v170
	v_cmp_lt_i32_e32 vcc, v50, v51
	s_nop 1
	v_cndmask_b32_e32 v50, v170, v50, vcc
	v_lshlrev_b32_e32 v132, 2, v50
	ds_bpermute_b32 v50, v132, v0
	s_waitcnt lgkmcnt(0)
	v_add_f32_e32 v0, v0, v50
	v_fmamk_f32 v0, v0, 0x3c800000, v158
	v_cmp_gt_f32_e32 vcc, s8, v0
	v_mul_f32_e32 v50, 0x4b800000, v0
	s_nop 0
	v_cndmask_b32_e32 v0, v0, v50, vcc
	v_rsq_f32_e32 v0, v0
	s_nop 0
	v_mul_f32_e32 v50, 0x45800000, v0
	v_cndmask_b32_e32 v50, v0, v50, vcc
	v_lshlrev_b32_e32 v0, 1, v91
	v_lshl_add_u64 v[52:53], v[52:53], 0, v[0:1]
	global_load_dwordx2 v[54:55], v[52:53], off offset:1536
	global_load_dwordx2 v[214:215], v[52:53], off offset:1568
	global_load_dwordx2 v[216:217], v[52:53], off offset:1600
	global_load_dwordx2 v[218:219], v[52:53], off offset:1632
	v_cmp_lt_i32_e32 vcc, v98, v91
	s_waitcnt vmcnt(0) lgkmcnt(0)
	v_lshlrev_b32_e32 v56, 16, v54
	v_mul_f32_e32 v51, 0xbfb8aa3b, v56
	v_exp_f32_e32 v51, v51
	v_and_b32_e32 v57, 0xffff0000, v54
	v_lshlrev_b32_e32 v54, 16, v55
	v_and_b32_e32 v55, 0xffff0000, v55
	v_add_f32_e32 v51, 1.0, v51
	v_rcp_f32_e32 v58, v51
	v_mul_f32_e32 v51, 0xbfb8aa3b, v57
	v_exp_f32_e32 v51, v51
	s_nop 0
	v_add_f32_e32 v51, 1.0, v51
	v_rcp_f32_e32 v59, v51
	s_nop 0
	v_pk_mul_f32 v[56:57], v[58:59], v[56:57]
	s_nop 0
	v_pk_mul_f32 v[56:57], v[56:57], v[50:51] op_sel_hi:[1,0]
	v_mul_f32_e32 v51, 0xbfb8aa3b, v54
	v_exp_f32_e32 v51, v51
	v_pk_mul_f32 v[46:47], v[46:47], v[56:57]
	v_add_f32_e32 v51, 1.0, v51
	v_rcp_f32_e32 v56, v51
	v_mul_f32_e32 v51, 0xbfb8aa3b, v55
	v_exp_f32_e32 v51, v51
	v_cvt_pk_bf16_f32 v46, v46, v47
	v_add_f32_e32 v51, 1.0, v51
	v_rcp_f32_e32 v57, v51
	s_nop 0
	v_pk_mul_f32 v[54:55], v[56:57], v[54:55]
	s_nop 0
	v_pk_mul_f32 v[54:55], v[54:55], v[50:51] op_sel_hi:[1,0]
	s_nop 0
	v_pk_mul_f32 v[48:49], v[48:49], v[54:55]
	s_nop 0
	v_cvt_pk_bf16_f32 v47, v48, v49
	global_store_dwordx2 v[52:53], v[46:47], off offset:1536
	s_nop 0
	s_nop 0
	v_lshlrev_b32_e32 v48, 16, v214
	v_mul_f32_e32 v51, 0xbfb8aa3b, v48
	v_exp_f32_e32 v51, v51
	v_and_b32_e32 v49, 0xffff0000, v214
	v_lshlrev_b32_e32 v46, 16, v215
	v_and_b32_e32 v47, 0xffff0000, v215
	v_add_f32_e32 v51, 1.0, v51
	v_rcp_f32_e32 v54, v51
	v_mul_f32_e32 v51, 0xbfb8aa3b, v49
	v_exp_f32_e32 v51, v51
	s_nop 0
	v_add_f32_e32 v51, 1.0, v51
	v_rcp_f32_e32 v55, v51
	s_nop 0
	v_pk_mul_f32 v[48:49], v[54:55], v[48:49]
	s_nop 0
	v_pk_mul_f32 v[48:49], v[48:49], v[50:51] op_sel_hi:[1,0]
	s_nop 0
	v_pk_mul_f32 v[42:43], v[42:43], v[48:49]
	v_mul_f32_e32 v48, 0xbfb8aa3b, v46
	v_mul_f32_e32 v49, 0xbfb8aa3b, v47
	v_exp_f32_e32 v48, v48
	v_exp_f32_e32 v49, v49
	v_cvt_pk_bf16_f32 v42, v42, v43
	v_add_f32_e32 v48, 1.0, v48
	v_add_f32_e32 v49, 1.0, v49
	v_rcp_f32_e32 v48, v48
	v_rcp_f32_e32 v49, v49
	s_nop 0
	v_pk_mul_f32 v[46:47], v[48:49], v[46:47]
	s_nop 0
	v_pk_mul_f32 v[46:47], v[46:47], v[50:51] op_sel_hi:[1,0]
	s_nop 0
	v_pk_mul_f32 v[44:45], v[44:45], v[46:47]
	s_nop 0
	v_cvt_pk_bf16_f32 v43, v44, v45
	global_store_dwordx2 v[52:53], v[42:43], off offset:1568
	s_nop 0
	s_nop 0
	v_lshlrev_b32_e32 v44, 16, v216
	v_and_b32_e32 v45, 0xffff0000, v216
	v_mul_f32_e32 v46, 0xbfb8aa3b, v44
	v_mul_f32_e32 v47, 0xbfb8aa3b, v45
	v_exp_f32_e32 v46, v46
	v_exp_f32_e32 v47, v47
	v_lshlrev_b32_e32 v42, 16, v217
	v_and_b32_e32 v43, 0xffff0000, v217
	v_add_f32_e32 v46, 1.0, v46
	v_add_f32_e32 v47, 1.0, v47
	v_rcp_f32_e32 v46, v46
	v_rcp_f32_e32 v47, v47
	s_nop 0
	v_pk_mul_f32 v[44:45], v[46:47], v[44:45]
	s_nop 0
	v_pk_mul_f32 v[44:45], v[44:45], v[50:51] op_sel_hi:[1,0]
	s_nop 0
	v_pk_mul_f32 v[38:39], v[38:39], v[44:45]
	v_mul_f32_e32 v44, 0xbfb8aa3b, v42
	v_mul_f32_e32 v45, 0xbfb8aa3b, v43
	v_exp_f32_e32 v44, v44
	v_exp_f32_e32 v45, v45
	v_cvt_pk_bf16_f32 v38, v38, v39
	v_add_f32_e32 v44, 1.0, v44
	v_add_f32_e32 v45, 1.0, v45
	v_rcp_f32_e32 v44, v44
	v_rcp_f32_e32 v45, v45
	s_nop 0
	v_pk_mul_f32 v[42:43], v[44:45], v[42:43]
	s_nop 0
	v_pk_mul_f32 v[42:43], v[50:51], v[42:43] op_sel_hi:[0,1]
	v_pk_mul_f32 v[40:41], v[40:41], v[42:43]
	s_nop 0
	v_cvt_pk_bf16_f32 v39, v40, v41
	global_store_dwordx2 v[52:53], v[38:39], off offset:1600
	s_nop 0
	s_nop 0
	v_lshlrev_b32_e32 v40, 16, v218
	v_and_b32_e32 v41, 0xffff0000, v218
	v_mul_f32_e32 v42, 0xbfb8aa3b, v40
	v_mul_f32_e32 v43, 0xbfb8aa3b, v41
	v_exp_f32_e32 v42, v42
	v_exp_f32_e32 v43, v43
	v_lshlrev_b32_e32 v38, 16, v219
	v_and_b32_e32 v39, 0xffff0000, v219
	v_add_f32_e32 v42, 1.0, v42
	v_add_f32_e32 v43, 1.0, v43
	v_rcp_f32_e32 v42, v42
	v_rcp_f32_e32 v43, v43
	s_nop 0
	v_pk_mul_f32 v[40:41], v[42:43], v[40:41]
	s_nop 0
	v_pk_mul_f32 v[40:41], v[50:51], v[40:41] op_sel_hi:[0,1]
	v_pk_mul_f32 v[34:35], v[34:35], v[40:41]
	v_mul_f32_e32 v40, 0xbfb8aa3b, v38
	v_mul_f32_e32 v41, 0xbfb8aa3b, v39
	v_exp_f32_e32 v40, v40
	v_exp_f32_e32 v41, v41
	v_cvt_pk_bf16_f32 v34, v34, v35
	v_add_f32_e32 v40, 1.0, v40
	v_add_f32_e32 v41, 1.0, v41
	v_rcp_f32_e32 v40, v40
	v_rcp_f32_e32 v41, v41
	s_nop 0
	v_pk_mul_f32 v[38:39], v[40:41], v[38:39]
	s_nop 0
	v_pk_mul_f32 v[38:39], v[50:51], v[38:39] op_sel_hi:[0,1]
	v_pk_mul_f32 v[36:37], v[36:37], v[38:39]
	s_nop 0
	v_cvt_pk_bf16_f32 v35, v36, v37
	global_store_dwordx2 v[52:53], v[34:35], off offset:1632
	v_mov_b32_e32 v34, v1
	ds_read_b128 v[38:41], v90 offset:9216
	ds_read_b128 v[42:45], v88 offset:18432
	ds_read_b128 v[46:49], v88 offset:20736
	ds_read_b128 v[50:53], v88 offset:23040
	ds_read_b128 v[54:57], v89 offset:18432
	ds_read_b128 v[58:61], v88 offset:27648
	ds_read_b128 v[62:65], v88 offset:29952
	ds_read_b128 v[66:69], v88 offset:32256
	ds_read_b128 v[70:73], v92 offset:18432
	v_mov_b32_e32 v35, v34
	v_mov_b32_e32 v36, v34
	v_mov_b32_e32 v37, v34
	s_waitcnt lgkmcnt(0)
	s_nop 0
	v_mfma_f32_16x16x32_bf16 v[42:45], v[42:45], v[38:41], v[34:37]
	v_mfma_f32_16x16x32_bf16 v[46:49], v[46:49], v[38:41], v[34:37]
	v_mfma_f32_16x16x32_bf16 v[50:53], v[50:53], v[38:41], v[34:37]
	v_mfma_f32_16x16x32_bf16 v[74:77], v[54:57], v[38:41], v[34:37]
	v_mfma_f32_16x16x32_bf16 v[78:81], v[58:61], v[38:41], v[34:37]
	v_mfma_f32_16x16x32_bf16 v[134:137], v[62:65], v[38:41], v[34:37]
	v_mfma_f32_16x16x32_bf16 v[66:69], v[66:69], v[38:41], v[34:37]
	v_mfma_f32_16x16x32_bf16 v[34:37], v[70:73], v[38:41], v[34:37]
	ds_read_b128 v[70:73], v90 offset:9280
	ds_read_b128 v[38:41], v88 offset:18496
	ds_read_b128 v[54:57], v88 offset:20800
	ds_read_b128 v[138:141], v88 offset:23104
	ds_read_b128 v[142:145], v89 offset:18496
	ds_read_b128 v[146:149], v88 offset:27712
	ds_read_b128 v[150:153], v88 offset:30016
	ds_read_b128 v[86:89], v88 offset:32320
	ds_read_b128 v[166:169], v92 offset:18496
	s_waitcnt lgkmcnt(0)
	v_mfma_f32_16x16x32_bf16 v[62:65], v[38:41], v[70:73], v[42:45]
	v_mfma_f32_16x16x32_bf16 v[38:41], v[86:89], v[70:73], v[66:69]
	s_nop 2
	v_sub_u32_e32 v66, v98, v91
	v_sub_u32_e32 v67, 0, v66
	v_max_i32_e32 v66, v66, v67
	v_cvt_f32_u32_e32 v66, v66
	v_cndmask_b32_e32 v67, v96, v97, vcc
	v_cmp_gt_i32_e32 vcc, v98, v91
	v_sub_u32_e32 v68, v98, v102
	v_mul_f32_e32 v66, v67, v66
	v_sub_u32_e32 v67, v102, v98
	v_cndmask_b32_e32 v67, v67, v68, vcc
	v_cvt_f32_i32_e32 v67, v67
	v_cndmask_b32_e32 v68, v97, v96, vcc
	v_cmp_lt_i32_e32 vcc, v98, v104
	v_mfma_f32_16x16x32_bf16 v[58:61], v[54:57], v[70:73], v[46:49]
	v_mul_f32_e32 v67, v68, v67
	v_sub_u32_e32 v68, v98, v104
	v_sub_u32_e32 v69, 0, v68
	v_max_i32_e32 v68, v68, v69
	v_cvt_f32_u32_e32 v68, v68
	v_cndmask_b32_e32 v69, v96, v97, vcc
	v_mfma_f32_16x16x32_bf16 v[54:57], v[138:141], v[70:73], v[50:53]
	v_cmp_lt_i32_e32 vcc, v98, v103
	v_mul_f32_e32 v68, v69, v68
	v_sub_u32_e32 v69, v98, v103
	v_mfma_f32_16x16x32_bf16 v[50:53], v[142:145], v[70:73], v[74:77]
	v_mul_f32_e32 v66, 0xbfb8aa3b, v66
	v_mul_f32_e32 v67, 0xbfb8aa3b, v67
	v_exp_f32_e32 v66, v66
	v_mfma_f32_16x16x32_bf16 v[46:49], v[146:149], v[70:73], v[78:81]
	v_exp_f32_e32 v67, v67
	v_mul_f32_e32 v68, 0xbfb8aa3b, v68
	v_exp_f32_e32 v68, v68
	v_mfma_f32_16x16x32_bf16 v[42:45], v[150:153], v[70:73], v[134:137]
	v_mul_f32_e64 v62, v66, v62
	v_mul_f32_e64 v63, v67, v63
	v_sub_u32_e32 v67, 64, v99
	v_add_u32_e32 v66, 0x41, v99
	v_mfma_f32_16x16x32_bf16 v[34:37], v[166:169], v[70:73], v[34:37]
	v_sub_u32_e32 v70, 0, v69
	v_max_i32_e32 v69, v69, v70
	v_cvt_f32_u32_e32 v69, v69
	v_cndmask_b32_e32 v70, v96, v97, vcc
	v_cmp_lt_i32_e32 vcc, v98, v94
	v_cvt_f32_i32_e32 v67, v67
	v_mul_f32_e32 v69, v70, v69
	v_sub_u32_e32 v70, v98, v94
	v_sub_u32_e32 v71, 0, v70
	v_max_i32_e32 v70, v70, v71
	v_cvt_f32_u32_e32 v70, v70
	v_cndmask_b32_e32 v71, v96, v97, vcc
	v_cmp_lt_i32_e32 vcc, v98, v95
	v_mul_f32_e32 v69, 0xbfb8aa3b, v69
	v_mul_f32_e32 v70, v71, v70
	v_sub_u32_e32 v71, v98, v95
	v_sub_u32_e32 v72, 0, v71
	v_max_i32_e32 v71, v71, v72
	v_cvt_f32_u32_e32 v71, v71
	v_cndmask_b32_e32 v72, v96, v97, vcc
	v_cmp_lt_i32_e32 vcc, v98, v100
	v_cvt_f32_i32_e32 v66, v66
	v_mul_f32_e32 v71, v72, v71
	v_sub_u32_e32 v72, v98, v100
	v_sub_u32_e32 v73, 0, v72
	v_max_i32_e32 v72, v72, v73
	v_cvt_f32_u32_e32 v72, v72
	v_cndmask_b32_e32 v73, v96, v97, vcc
	v_cmp_lt_i32_e32 vcc, v98, v101
	v_exp_f32_e32 v69, v69
	v_mul_f32_e32 v72, v73, v72
	v_sub_u32_e32 v73, v98, v101
	v_sub_u32_e32 v74, 0, v73
	v_max_i32_e32 v73, v73, v74
	v_cvt_f32_u32_e32 v73, v73
	v_cndmask_b32_e32 v74, v96, v97, vcc
	v_cmp_lt_i32_e32 vcc, v98, v105
	v_mul_f32_e32 v67, v67, v97
	v_mul_f32_e32 v73, v74, v73
	v_sub_u32_e32 v74, v98, v105
	v_sub_u32_e32 v75, 0, v74
	v_max_i32_e32 v74, v74, v75
	v_cvt_f32_u32_e32 v74, v74
	v_cndmask_b32_e32 v75, v96, v97, vcc
	v_cmp_lt_i32_e32 vcc, v98, v106
	v_mul_f32_e32 v66, v66, v96
	v_mul_f32_e32 v74, v75, v74
	v_sub_u32_e32 v75, v98, v106
	v_sub_u32_e32 v76, 0, v75
	v_max_i32_e32 v75, v75, v76
	v_cvt_f32_u32_e32 v75, v75
	v_cndmask_b32_e32 v76, v96, v97, vcc
	v_cmp_lt_i32_e32 vcc, v98, v107
	v_mul_f32_e32 v67, 0xbfb8aa3b, v67
	v_mul_f32_e32 v75, v76, v75
	v_sub_u32_e32 v76, v98, v107
	v_sub_u32_e32 v77, 0, v76
	v_max_i32_e32 v76, v76, v77
	v_cvt_f32_u32_e32 v76, v76
	v_cndmask_b32_e32 v77, v96, v97, vcc
	v_cmp_lt_i32_e32 vcc, v98, v108
	v_pk_mul_f32 v[64:65], v[68:69], v[64:65]
	v_mul_f32_e32 v76, v77, v76
	v_sub_u32_e32 v77, v98, v108
	v_sub_u32_e32 v78, 0, v77
	v_max_i32_e32 v77, v77, v78
	v_cvt_f32_u32_e32 v77, v77
	v_cndmask_b32_e32 v78, v96, v97, vcc
	v_cmp_lt_i32_e32 vcc, v98, v109
	v_mul_f32_e32 v66, 0xbfb8aa3b, v66
	v_mul_f32_e32 v77, v78, v77
	v_sub_u32_e32 v78, v98, v109
	v_sub_u32_e32 v79, 0, v78
	v_max_i32_e32 v78, v78, v79
	v_cvt_f32_u32_e32 v78, v78
	v_cndmask_b32_e32 v79, v96, v97, vcc
	v_cmp_lt_i32_e32 vcc, v98, v110
	v_exp_f32_e32 v68, v67
	v_mul_f32_e32 v78, v79, v78
	v_sub_u32_e32 v79, v98, v110
	v_sub_u32_e32 v80, 0, v79
	v_max_i32_e32 v79, v79, v80
	v_cvt_f32_u32_e32 v79, v79
	v_cndmask_b32_e32 v80, v96, v97, vcc
	v_cmp_lt_i32_e32 vcc, v98, v111
	v_exp_f32_e32 v66, v66
	v_mul_f32_e32 v79, v80, v79
	v_sub_u32_e32 v80, v98, v111
	v_sub_u32_e32 v81, 0, v80
	v_max_i32_e32 v80, v80, v81
	v_cvt_f32_u32_e32 v80, v80
	v_cndmask_b32_e32 v81, v96, v97, vcc
	v_cmp_lt_i32_e32 vcc, v98, v112
	v_pk_mul_f32 v[22:23], v[68:69], v[22:23] op_sel_hi:[0,1]
	v_mul_f32_e32 v80, v81, v80
	v_sub_u32_e32 v81, v98, v112
	v_sub_u32_e32 v86, 0, v81
	v_max_i32_e32 v81, v81, v86
	v_cvt_f32_u32_e32 v81, v81
	v_cndmask_b32_e32 v86, v96, v97, vcc
	v_pk_mul_f32 v[24:25], v[68:69], v[24:25] op_sel_hi:[0,1]
	v_pk_fma_f32 v[20:21], v[66:67], v[20:21], v[24:25] op_sel_hi:[0,1,1]
	v_mul_f32_e32 v81, v86, v81
	v_sub_u32_e32 v86, v98, v113
	v_sub_u32_e32 v87, 0, v86
	v_max_i32_e32 v86, v86, v87
	v_cvt_f32_u32_e32 v86, v86
	v_pk_fma_f32 v[18:19], v[66:67], v[18:19], v[22:23] op_sel_hi:[0,1,1]
	ds_read_b128 v[22:25], v130 offset:36864
	v_mul_f32_e32 v70, 0xbfb8aa3b, v70
	v_mul_f32_e32 v71, 0xbfb8aa3b, v71
	v_mul_f32_e32 v72, 0xbfb8aa3b, v72
	v_mul_f32_e32 v73, 0xbfb8aa3b, v73
	v_cmp_lt_i32_e32 vcc, v98, v113
	v_exp_f32_e32 v70, v70
	v_exp_f32_e32 v71, v71
	v_exp_f32_e32 v72, v72
	v_exp_f32_e32 v73, v73
	v_cndmask_b32_e32 v87, v96, v97, vcc
	v_mul_f32_e32 v86, v87, v86
	v_sub_u32_e32 v87, v98, v114
	v_sub_u32_e32 v88, 0, v87
	v_max_i32_e32 v87, v87, v88
	v_cvt_f32_u32_e32 v87, v87
	v_pk_mul_f32 v[58:59], v[70:71], v[58:59]
	v_pk_mul_f32 v[60:61], v[72:73], v[60:61]
	v_pk_mul_f32 v[14:15], v[68:69], v[14:15] op_sel_hi:[0,1]
	v_pk_mul_f32 v[16:17], v[68:69], v[16:17] op_sel_hi:[0,1]
	v_pk_mul_f32 v[10:11], v[68:69], v[10:11] op_sel_hi:[0,1]
	v_pk_mul_f32 v[12:13], v[68:69], v[12:13] op_sel_hi:[0,1]
	v_pk_fma_f32 v[8:9], v[66:67], v[8:9], v[16:17] op_sel_hi:[0,1,1]
	v_pk_fma_f32 v[6:7], v[66:67], v[6:7], v[14:15] op_sel_hi:[0,1,1]
	v_pk_fma_f32 v[12:13], v[66:67], v[4:5], v[12:13] op_sel_hi:[0,1,1]
	v_pk_fma_f32 v[10:11], v[66:67], v[2:3], v[10:11] op_sel_hi:[0,1,1]
	v_cvt_pk_bf16_f32 v14, v62, v63
	v_cvt_pk_bf16_f32 v15, v64, v65
	v_cvt_pk_bf16_f32 v16, v58, v59
	v_cvt_pk_bf16_f32 v17, v60, v61
	v_cmp_lt_i32_e32 vcc, v98, v114
	v_pk_mul_f32 v[30:31], v[68:69], v[30:31] op_sel_hi:[0,1]
	s_waitcnt lgkmcnt(0)
	v_mfma_f32_16x16x32_bf16 v[10:13], v[22:25], v[14:17], v[10:13]
	ds_read_b128 v[22:25], v130 offset:41216
	v_cndmask_b32_e32 v88, v96, v97, vcc
	v_mul_f32_e32 v87, v88, v87
	v_sub_u32_e32 v88, v98, v115
	v_sub_u32_e32 v89, 0, v88
	v_max_i32_e32 v88, v88, v89
	v_cvt_f32_u32_e32 v88, v88
	v_cmp_lt_i32_e32 vcc, v98, v115
	s_waitcnt lgkmcnt(0)
	v_mfma_f32_16x16x32_bf16 v[4:7], v[22:25], v[14:17], v[6:9]
	v_cndmask_b32_e32 v89, v96, v97, vcc
	v_mul_f32_e32 v88, v89, v88
	v_sub_u32_e32 v89, v98, v116
	ds_read_b128 v[22:25], v130 offset:45568
	v_sub_u32_e32 v90, 0, v89
	v_max_i32_e32 v89, v89, v90
	v_cvt_f32_u32_e32 v89, v89
	v_cmp_lt_i32_e32 vcc, v98, v116
	s_waitcnt lgkmcnt(0)
	v_mfma_f32_16x16x32_bf16 v[18:21], v[22:25], v[14:17], v[18:21]
	v_cndmask_b32_e32 v90, v96, v97, vcc
	v_mul_f32_e32 v89, v90, v89
	v_sub_u32_e32 v90, v98, v117
	v_sub_u32_e32 v91, 0, v90
	v_max_i32_e32 v90, v90, v91
	ds_read_b128 v[22:25], v130 offset:49920
	v_cvt_f32_u32_e32 v90, v90
	v_cmp_lt_i32_e32 vcc, v98, v117
	v_pk_mul_f32 v[32:33], v[68:69], v[32:33] op_sel_hi:[0,1]
	v_pk_fma_f32 v[28:29], v[66:67], v[28:29], v[32:33] op_sel_hi:[0,1,1]
	v_cndmask_b32_e32 v91, v96, v97, vcc
	v_mul_f32_e32 v90, v91, v90
	v_sub_u32_e32 v91, v98, v118
	v_sub_u32_e32 v92, 0, v91
	v_max_i32_e32 v91, v91, v92
	v_cvt_f32_u32_e32 v91, v91
	v_pk_fma_f32 v[26:27], v[66:67], v[26:27], v[30:31] op_sel_hi:[0,1,1]
	v_cmp_lt_i32_e32 vcc, v98, v118
	v_mul_f32_e32 v74, 0xbfb8aa3b, v74
	s_waitcnt lgkmcnt(0)
	v_mfma_f32_16x16x32_bf16 v[14:17], v[22:25], v[14:17], v[26:29]
	v_mul_f32_e32 v75, 0xbfb8aa3b, v75
	v_mul_f32_e32 v76, 0xbfb8aa3b, v76
	v_mul_f32_e32 v77, 0xbfb8aa3b, v77
	ds_read_b128 v[26:29], v130 offset:36928
	v_mul_f32_e32 v78, 0xbfb8aa3b, v78
	v_mul_f32_e32 v79, 0xbfb8aa3b, v79
	v_mul_f32_e32 v80, 0xbfb8aa3b, v80
	v_mul_f32_e32 v81, 0xbfb8aa3b, v81
	v_cndmask_b32_e32 v92, v96, v97, vcc
	v_exp_f32_e32 v74, v74
	v_exp_f32_e32 v75, v75
	v_exp_f32_e32 v76, v76
	v_exp_f32_e32 v77, v77
	v_exp_f32_e32 v78, v78
	v_exp_f32_e32 v79, v79
	v_exp_f32_e32 v80, v80
	v_exp_f32_e32 v81, v81
	v_mul_f32_e32 v91, v92, v91
	v_sub_u32_e32 v92, v98, v119
	v_sub_u32_e32 v93, 0, v92
	v_max_i32_e32 v92, v92, v93
	v_cvt_f32_u32_e32 v92, v92
	v_pk_mul_f32 v[54:55], v[74:75], v[54:55]
	v_pk_mul_f32 v[56:57], v[76:77], v[56:57]
	v_pk_mul_f32 v[50:51], v[78:79], v[50:51]
	v_pk_mul_f32 v[52:53], v[80:81], v[52:53]
	v_cmp_lt_i32_e32 vcc, v98, v119
	v_cvt_pk_bf16_f32 v22, v54, v55
	v_cvt_pk_bf16_f32 v23, v56, v57
	v_cvt_pk_bf16_f32 v24, v50, v51
	v_cvt_pk_bf16_f32 v25, v52, v53
	v_cndmask_b32_e32 v93, v96, v97, vcc
	v_mul_f32_e32 v92, v93, v92
	s_waitcnt lgkmcnt(0)
	v_mfma_f32_16x16x32_bf16 v[8:11], v[26:29], v[22:25], v[10:13]
	ds_read_b128 v[26:29], v130 offset:41280
	v_sub_u32_e32 v93, v98, v120
	v_sub_u32_e32 v94, 0, v93
	v_max_i32_e32 v93, v93, v94
	v_cvt_f32_u32_e32 v93, v93
	v_cmp_lt_i32_e32 vcc, v98, v120
	s_waitcnt lgkmcnt(0)
	v_mfma_f32_16x16x32_bf16 v[4:7], v[26:29], v[22:25], v[4:7]
	v_cndmask_b32_e32 v94, v96, v97, vcc
	v_mul_f32_e32 v93, v94, v93
	v_sub_u32_e32 v94, v98, v121
	v_sub_u32_e32 v95, 0, v94
	ds_read_b128 v[26:29], v130 offset:45632
	v_max_i32_e32 v94, v94, v95
	v_cvt_f32_u32_e32 v94, v94
	v_cmp_lt_i32_e32 vcc, v98, v121
	s_waitcnt lgkmcnt(0)
	v_mfma_f32_16x16x32_bf16 v[18:21], v[26:29], v[22:25], v[18:21]
	v_cndmask_b32_e32 v95, v96, v97, vcc
	v_mul_f32_e32 v94, v95, v94
	v_sub_u32_e32 v95, v98, v123
	v_sub_u32_e32 v100, 0, v95
	v_max_i32_e32 v95, v95, v100
	v_cvt_f32_u32_e32 v95, v95
	ds_read_b128 v[26:29], v130 offset:49984
	v_cmp_lt_i32_e32 vcc, v98, v123
	s_waitcnt lgkmcnt(0)
	v_mfma_f32_16x16x32_bf16 v[12:15], v[26:29], v[22:25], v[14:17]
	v_cndmask_b32_e32 v100, v96, v97, vcc
	v_mul_f32_e32 v95, v100, v95
	v_sub_u32_e32 v100, v98, v124
	v_sub_u32_e32 v101, 0, v100
	v_max_i32_e32 v100, v100, v101
	v_cvt_f32_u32_e32 v100, v100
	v_cmp_lt_i32_e32 vcc, v98, v124
	ds_read_b128 v[26:29], v130 offset:36992
	v_mul_f32_e32 v86, 0xbfb8aa3b, v86
	v_cndmask_b32_e32 v101, v96, v97, vcc
	v_mul_f32_e32 v87, 0xbfb8aa3b, v87
	v_mul_f32_e32 v88, 0xbfb8aa3b, v88
	v_mul_f32_e32 v89, 0xbfb8aa3b, v89
	v_mul_f32_e32 v90, 0xbfb8aa3b, v90
	v_mul_f32_e32 v91, 0xbfb8aa3b, v91
	v_mul_f32_e32 v92, 0xbfb8aa3b, v92
	v_mul_f32_e32 v93, 0xbfb8aa3b, v93
	v_mul_f32_e32 v100, v101, v100
	v_sub_u32_e32 v101, v98, v125
	v_exp_f32_e32 v86, v86
	v_exp_f32_e32 v87, v87
	v_exp_f32_e32 v88, v88
	v_exp_f32_e32 v89, v89
	v_exp_f32_e32 v90, v90
	v_exp_f32_e32 v91, v91
	v_exp_f32_e32 v92, v92
	v_exp_f32_e32 v93, v93
	v_sub_u32_e32 v102, 0, v101
	v_max_i32_e32 v101, v101, v102
	v_cvt_f32_u32_e32 v101, v101
	v_cmp_lt_i32_e32 vcc, v98, v125
	v_pk_mul_f32 v[46:47], v[86:87], v[46:47]
	v_pk_mul_f32 v[48:49], v[88:89], v[48:49]
	v_pk_mul_f32 v[42:43], v[90:91], v[42:43]
	v_pk_mul_f32 v[44:45], v[92:93], v[44:45]
	v_cndmask_b32_e32 v102, v96, v97, vcc
	v_cvt_pk_bf16_f32 v22, v46, v47
	v_cvt_pk_bf16_f32 v23, v48, v49
	v_cvt_pk_bf16_f32 v24, v42, v43
	v_cvt_pk_bf16_f32 v25, v44, v45
	v_mul_f32_e32 v101, v102, v101
	v_sub_u32_e32 v102, v98, v126
	s_waitcnt lgkmcnt(0)
	v_mfma_f32_16x16x32_bf16 v[8:11], v[26:29], v[22:25], v[8:11]
	ds_read_b128 v[26:29], v130 offset:41344
	v_sub_u32_e32 v103, 0, v102
	v_max_i32_e32 v102, v102, v103
	v_cvt_f32_u32_e32 v102, v102
	v_cmp_lt_i32_e32 vcc, v98, v126
	s_waitcnt lgkmcnt(0)
	v_mfma_f32_16x16x32_bf16 v[4:7], v[26:29], v[22:25], v[4:7]
	v_cndmask_b32_e32 v103, v96, v97, vcc
	v_mul_f32_e32 v102, v103, v102
	v_sub_u32_e32 v103, v98, v127
	v_sub_u32_e32 v104, 0, v103
	v_max_i32_e32 v103, v103, v104
	ds_read_b128 v[26:29], v130 offset:45696
	v_cvt_f32_u32_e32 v103, v103
	v_cmp_lt_i32_e32 vcc, v98, v127
	s_waitcnt lgkmcnt(0)
	v_mfma_f32_16x16x32_bf16 v[18:21], v[26:29], v[22:25], v[18:21]
	v_cndmask_b32_e32 v104, v96, v97, vcc
	v_mul_f32_e32 v103, v104, v103
	v_sub_u32_e32 v104, v98, v128
	v_sub_u32_e32 v105, 0, v104
	v_max_i32_e32 v104, v104, v105
	v_cvt_f32_u32_e32 v104, v104
	ds_read_b128 v[26:29], v130 offset:50048
	v_cmp_lt_i32_e32 vcc, v98, v128
	s_waitcnt lgkmcnt(0)
	v_mfma_f32_16x16x32_bf16 v[22:25], v[26:29], v[22:25], v[12:15]
	v_cndmask_b32_e32 v105, v96, v97, vcc
	v_mul_f32_e32 v104, v105, v104
	v_sub_u32_e32 v105, v98, v129
	v_sub_u32_e32 v106, 0, v105
	v_max_i32_e32 v105, v105, v106
	v_cvt_f32_u32_e32 v105, v105
	v_cmp_lt_i32_e32 vcc, v98, v129
	ds_read_b128 v[12:15], v130 offset:37056
	v_mul_f32_e32 v94, 0xbfb8aa3b, v94
	v_cndmask_b32_e32 v106, v96, v97, vcc
	v_mul_f32_e32 v105, v106, v105
	v_mul_f32_e32 v95, 0xbfb8aa3b, v95
	v_mul_f32_e32 v100, 0xbfb8aa3b, v100
	v_mul_f32_e32 v101, 0xbfb8aa3b, v101
	v_mul_f32_e32 v102, 0xbfb8aa3b, v102
	v_mul_f32_e32 v103, 0xbfb8aa3b, v103
	v_mul_f32_e32 v104, 0xbfb8aa3b, v104
	v_mul_f32_e32 v105, 0xbfb8aa3b, v105
	v_exp_f32_e32 v94, v94
	v_exp_f32_e32 v95, v95
	v_exp_f32_e32 v100, v100
	v_exp_f32_e32 v101, v101
	v_exp_f32_e32 v102, v102
	v_exp_f32_e32 v103, v103
	v_exp_f32_e32 v104, v104
	v_exp_f32_e32 v105, v105
	v_pk_mul_f32 v[38:39], v[94:95], v[38:39]
	v_pk_mul_f32 v[34:35], v[102:103], v[34:35]
	v_pk_mul_f32 v[40:41], v[100:101], v[40:41]
	v_pk_mul_f32 v[2:3], v[104:105], v[36:37]
	v_cvt_pk_bf16_f32 v26, v38, v39
	v_cvt_pk_bf16_f32 v27, v40, v41
	v_cvt_pk_bf16_f32 v28, v34, v35
	v_cvt_pk_bf16_f32 v29, v2, v3
	s_waitcnt lgkmcnt(0)
	s_nop 0
	v_mfma_f32_16x16x32_bf16 v[14:17], v[12:15], v[26:29], v[8:11]
	s_nop 2
	ds_read_b128 v[8:11], v130 offset:41408
	s_waitcnt lgkmcnt(0)
	v_mfma_f32_16x16x32_bf16 v[10:13], v[8:11], v[26:29], v[4:7]
	s_nop 2
	ds_read_b128 v[2:5], v130 offset:45760
	s_waitcnt lgkmcnt(0)
	v_mfma_f32_16x16x32_bf16 v[6:9], v[2:5], v[26:29], v[18:21]
	ds_read_b128 v[2:5], v130 offset:50112
	s_nop 6
	v_pk_mul_f32 v[20:21], v[6:7], v[6:7]
	s_waitcnt lgkmcnt(0)
	v_mfma_f32_16x16x32_bf16 v[2:5], v[2:5], v[26:29], v[22:25]
	s_nop 2
	v_mul_f32_e32 v22, v15, v15
	v_fmac_f32_e32 v22, v14, v14
	v_fmac_f32_e32 v22, v16, v16
	v_fmac_f32_e32 v22, v17, v17
	v_fmac_f32_e32 v22, v10, v10
	v_fmac_f32_e32 v22, v11, v11
	v_fmac_f32_e32 v22, v12, v12
	v_fmac_f32_e32 v22, v13, v13
	v_add_f32_e32 v20, v20, v22
	v_pk_mul_f32 v[18:19], v[8:9], v[8:9]
	v_add_f32_e32 v20, v21, v20
	v_add_f32_e32 v18, v18, v20
	v_add_f32_e32 v22, v19, v18
	v_pk_mul_f32 v[20:21], v[2:3], v[2:3]
	v_pk_mul_f32 v[18:19], v[4:5], v[4:5]
	v_add_f32_e32 v20, v20, v22
	v_add_f32_e32 v20, v21, v20
	v_add_f32_e32 v18, v18, v20
	v_mad_i64_i32 v[20:21], s[4:5], v98, s33, v[82:83]
	v_lshl_add_u64 v[20:21], v[20:21], 0, v[84:85]
	v_lshl_add_u64 v[20:21], v[20:21], 0, v[0:1]
	global_load_dwordx2 v[22:23], v[20:21], off offset:1536
	global_load_dwordx2 v[214:215], v[20:21], off offset:1568
	global_load_dwordx2 v[216:217], v[20:21], off offset:1600
	global_load_dwordx2 v[218:219], v[20:21], off offset:1632
	v_add_f32_e32 v18, v19, v18
	ds_bpermute_b32 v19, v131, v18
	s_waitcnt lgkmcnt(0)
	v_add_f32_e32 v18, v18, v19
	ds_bpermute_b32 v19, v132, v18
	s_waitcnt lgkmcnt(0)
	v_add_f32_e32 v18, v18, v19
	v_fmamk_f32 v18, v18, 0x3c800000, v158
	v_cmp_gt_f32_e32 vcc, s8, v18
	v_mul_f32_e32 v19, 0x4b800000, v18
	s_waitcnt vmcnt(0)
	v_lshlrev_b32_e32 v24, 16, v22
	v_mul_f32_e32 v0, 0xbfb8aa3b, v24
	v_exp_f32_e32 v0, v0
	v_and_b32_e32 v25, 0xffff0000, v22
	v_cndmask_b32_e32 v18, v18, v19, vcc
	v_rsq_f32_e32 v18, v18
	v_add_f32_e32 v0, 1.0, v0
	v_rcp_f32_e32 v26, v0
	v_mul_f32_e32 v0, 0xbfb8aa3b, v25
	v_exp_f32_e32 v0, v0
	v_lshlrev_b32_e32 v22, 16, v23
	v_mul_f32_e32 v19, 0x45800000, v18
	v_cndmask_b32_e32 v18, v18, v19, vcc
	v_add_f32_e32 v0, 1.0, v0
	v_rcp_f32_e32 v27, v0
	v_mul_f32_e32 v0, 0xbfb8aa3b, v22
	v_exp_f32_e32 v0, v0
	v_and_b32_e32 v23, 0xffff0000, v23
	v_pk_mul_f32 v[24:25], v[26:27], v[24:25]
	v_add_f32_e32 v0, 1.0, v0
	v_pk_mul_f32 v[24:25], v[24:25], v[18:19] op_sel_hi:[1,0]
	s_nop 0
	v_pk_mul_f32 v[14:15], v[14:15], v[24:25]
	v_rcp_f32_e32 v24, v0
	v_mul_f32_e32 v0, 0xbfb8aa3b, v23
	v_exp_f32_e32 v0, v0
	v_cvt_pk_bf16_f32 v14, v14, v15
	v_add_f32_e32 v0, 1.0, v0
	v_rcp_f32_e32 v25, v0
	s_nop 0
	v_pk_mul_f32 v[22:23], v[24:25], v[22:23]
	s_nop 0
	v_pk_mul_f32 v[22:23], v[22:23], v[18:19] op_sel_hi:[1,0]
	s_nop 0
	v_pk_mul_f32 v[16:17], v[16:17], v[22:23]
	s_nop 0
	v_cvt_pk_bf16_f32 v15, v16, v17
	global_store_dwordx2 v[20:21], v[14:15], off offset:1536
	s_nop 0
	s_nop 0
	v_lshlrev_b32_e32 v16, 16, v214
	v_mul_f32_e32 v0, 0xbfb8aa3b, v16
	v_exp_f32_e32 v0, v0
	v_and_b32_e32 v17, 0xffff0000, v214
	v_lshlrev_b32_e32 v14, 16, v215
	v_and_b32_e32 v15, 0xffff0000, v215
	v_add_f32_e32 v0, 1.0, v0
	v_rcp_f32_e32 v22, v0
	v_mul_f32_e32 v0, 0xbfb8aa3b, v17
	v_exp_f32_e32 v0, v0
	s_nop 0
	v_add_f32_e32 v0, 1.0, v0
	v_rcp_f32_e32 v23, v0
	v_mul_f32_e32 v0, 0xbfb8aa3b, v14
	v_exp_f32_e32 v0, v0
	v_pk_mul_f32 v[16:17], v[22:23], v[16:17]
	s_nop 0
	v_pk_mul_f32 v[16:17], v[16:17], v[18:19] op_sel_hi:[1,0]
	v_add_f32_e32 v0, 1.0, v0
	v_pk_mul_f32 v[10:11], v[10:11], v[16:17]
	v_rcp_f32_e32 v16, v0
	v_mul_f32_e32 v0, 0xbfb8aa3b, v15
	v_exp_f32_e32 v0, v0
	v_cvt_pk_bf16_f32 v10, v10, v11
	v_add_f32_e32 v0, 1.0, v0
	v_rcp_f32_e32 v17, v0
	s_nop 0
	v_pk_mul_f32 v[14:15], v[16:17], v[14:15]
	s_nop 0
	v_pk_mul_f32 v[14:15], v[14:15], v[18:19] op_sel_hi:[1,0]
	s_nop 0
	v_pk_mul_f32 v[12:13], v[12:13], v[14:15]
	s_nop 0
	v_cvt_pk_bf16_f32 v11, v12, v13
	global_store_dwordx2 v[20:21], v[10:11], off offset:1568
	s_nop 0
	s_nop 0
	v_lshlrev_b32_e32 v12, 16, v216
	v_mul_f32_e32 v0, 0xbfb8aa3b, v12
	v_exp_f32_e32 v0, v0
	v_and_b32_e32 v13, 0xffff0000, v216
	v_lshlrev_b32_e32 v10, 16, v217
	v_and_b32_e32 v11, 0xffff0000, v217
	v_add_f32_e32 v0, 1.0, v0
	v_rcp_f32_e32 v14, v0
	v_mul_f32_e32 v0, 0xbfb8aa3b, v13
	v_exp_f32_e32 v0, v0
	s_nop 0
	v_add_f32_e32 v0, 1.0, v0
	v_rcp_f32_e32 v15, v0
	v_mul_f32_e32 v0, 0xbfb8aa3b, v10
	v_exp_f32_e32 v0, v0
	v_pk_mul_f32 v[12:13], v[14:15], v[12:13]
	s_nop 0
	v_pk_mul_f32 v[12:13], v[12:13], v[18:19] op_sel_hi:[1,0]
	v_add_f32_e32 v0, 1.0, v0
	v_pk_mul_f32 v[6:7], v[6:7], v[12:13]
	v_rcp_f32_e32 v12, v0
	v_mul_f32_e32 v0, 0xbfb8aa3b, v11
	v_exp_f32_e32 v0, v0
	v_cvt_pk_bf16_f32 v6, v6, v7
	v_add_f32_e32 v0, 1.0, v0
	v_rcp_f32_e32 v13, v0
	s_nop 0
	v_pk_mul_f32 v[10:11], v[12:13], v[10:11]
	s_nop 0
	v_pk_mul_f32 v[10:11], v[10:11], v[18:19] op_sel_hi:[1,0]
	s_nop 0
	v_pk_mul_f32 v[8:9], v[8:9], v[10:11]
	s_nop 0
	v_cvt_pk_bf16_f32 v7, v8, v9
	global_store_dwordx2 v[20:21], v[6:7], off offset:1600
	s_nop 0
	s_nop 0
	v_lshlrev_b32_e32 v8, 16, v218
	v_mul_f32_e32 v0, 0xbfb8aa3b, v8
	v_exp_f32_e32 v0, v0
	v_and_b32_e32 v9, 0xffff0000, v218
	v_lshlrev_b32_e32 v6, 16, v219
	v_and_b32_e32 v7, 0xffff0000, v219
	v_add_f32_e32 v0, 1.0, v0
	v_rcp_f32_e32 v10, v0
	v_mul_f32_e32 v0, 0xbfb8aa3b, v9
	v_exp_f32_e32 v0, v0
	s_nop 0
	v_add_f32_e32 v0, 1.0, v0
	v_rcp_f32_e32 v11, v0
	v_mul_f32_e32 v0, 0xbfb8aa3b, v6
	v_exp_f32_e32 v0, v0
	v_pk_mul_f32 v[8:9], v[10:11], v[8:9]
	s_nop 0
	v_pk_mul_f32 v[8:9], v[18:19], v[8:9] op_sel_hi:[0,1]
	v_add_f32_e32 v0, 1.0, v0
	v_pk_mul_f32 v[2:3], v[2:3], v[8:9]
	v_rcp_f32_e32 v8, v0
	v_mul_f32_e32 v0, 0xbfb8aa3b, v7
	v_exp_f32_e32 v0, v0
	v_cvt_pk_bf16_f32 v2, v2, v3
	v_add_f32_e32 v0, 1.0, v0
	v_rcp_f32_e32 v9, v0
	s_nop 0
	v_pk_mul_f32 v[6:7], v[8:9], v[6:7]
	s_nop 0
	v_pk_mul_f32 v[6:7], v[18:19], v[6:7] op_sel_hi:[0,1]
	v_pk_mul_f32 v[4:5], v[4:5], v[6:7]
	s_nop 0
	v_cvt_pk_bf16_f32 v3, v4, v5
	global_store_dwordx2 v[20:21], v[2:3], off offset:1632
